# weight-copy phases read the f32 weights with non-temporal loads (streamed once, should not displace the residual stream from the caches)
# baseline (speedup 1.0000x reference)
.LBB0_916:
	s_lshl_b32 s69, s64, 1
	s_lshl_b32 s70, s65, 1
	v_or_b32_e32 v56, s69, v1
	v_or_b32_e32 v57, s70, v0
	v_add_lshl_u32 v4, v56, v3, 10
	v_add_lshl_u32 v53, v57, v48, 10
	v_or_b32_e32 v52, v49, v4
	v_or_b32_e32 v4, v50, v53
	v_lshl_add_u64 v[54:55], v[4:5], 2, s[88:89]
	v_mov_b32_e32 v53, v5
	v_lshl_add_u64 v[52:53], v[52:53], 2, s[88:89]
	global_load_dword v126, v[54:55], off nt
	global_load_dword v127, v[52:53], off nt
	v_mad_u64_u32 v[52:53], s[72:73], v57, s40, v[2:3]
	v_mad_u64_u32 v[54:55], s[72:73], v56, s40, v[2:3]
	s_add_i32 s71, s69, 4
	s_add_i32 s72, s70, 4
	v_or_b32_e32 v56, s71, v1
	v_or_b32_e32 v57, s72, v0
	v_add_lshl_u32 v53, v57, v48, 10
	s_add_i32 s71, s69, 8
	s_add_i32 s65, s65, 16
	s_add_i32 s64, s64, 16
	s_add_i32 s68, s68, -16
	v_mov_b32_e32 v142, v52
	v_mov_b32_e32 v143, v54
	v_add_lshl_u32 v4, v56, v3, 10
	v_or_b32_e32 v52, v49, v4
	v_or_b32_e32 v4, v50, v53
	v_lshl_add_u64 v[54:55], v[4:5], 2, s[88:89]
	v_mov_b32_e32 v53, v5
	v_lshl_add_u64 v[52:53], v[52:53], 2, s[88:89]
	global_load_dword v128, v[54:55], off nt
	global_load_dword v129, v[52:53], off nt
	v_mad_u64_u32 v[52:53], s[72:73], v57, s40, v[2:3]
	v_mad_u64_u32 v[54:55], s[72:73], v56, s40, v[2:3]
	s_add_i32 s72, s70, 8
	v_or_b32_e32 v56, s71, v1
	v_or_b32_e32 v57, s72, v0
	v_add_lshl_u32 v53, v57, v48, 10
	s_add_i32 s71, s69, 12
	v_mov_b32_e32 v144, v52
	v_mov_b32_e32 v145, v54
	v_add_lshl_u32 v4, v56, v3, 10
	v_or_b32_e32 v52, v49, v4
	v_or_b32_e32 v4, v50, v53
	v_lshl_add_u64 v[54:55], v[4:5], 2, s[88:89]
	v_mov_b32_e32 v53, v5
	v_lshl_add_u64 v[52:53], v[52:53], 2, s[88:89]
	global_load_dword v130, v[54:55], off nt
	global_load_dword v131, v[52:53], off nt
	v_mad_u64_u32 v[52:53], s[72:73], v57, s40, v[2:3]
	v_mad_u64_u32 v[54:55], s[72:73], v56, s40, v[2:3]
	s_add_i32 s72, s70, 12
	v_or_b32_e32 v56, s71, v1
	v_or_b32_e32 v57, s72, v0
	v_add_lshl_u32 v53, v57, v48, 10
	s_add_i32 s71, s69, 16
	v_mov_b32_e32 v146, v52
	v_mov_b32_e32 v147, v54
	v_add_lshl_u32 v4, v56, v3, 10
	v_or_b32_e32 v52, v49, v4
	v_or_b32_e32 v4, v50, v53
	v_lshl_add_u64 v[54:55], v[4:5], 2, s[88:89]
	v_mov_b32_e32 v53, v5
	v_lshl_add_u64 v[52:53], v[52:53], 2, s[88:89]
	global_load_dword v132, v[54:55], off nt
	global_load_dword v133, v[52:53], off nt
	v_mad_u64_u32 v[52:53], s[72:73], v57, s40, v[2:3]
	v_mad_u64_u32 v[54:55], s[72:73], v56, s40, v[2:3]
	s_add_i32 s72, s70, 16
	v_or_b32_e32 v56, s71, v1
	v_or_b32_e32 v57, s72, v0
	v_add_lshl_u32 v53, v57, v48, 10
	s_add_i32 s71, s69, 20
	v_mov_b32_e32 v148, v52
	v_mov_b32_e32 v149, v54
	v_add_lshl_u32 v4, v56, v3, 10
	v_or_b32_e32 v52, v49, v4
	v_or_b32_e32 v4, v50, v53
	v_lshl_add_u64 v[54:55], v[4:5], 2, s[88:89]
	v_mov_b32_e32 v53, v5
	v_lshl_add_u64 v[52:53], v[52:53], 2, s[88:89]
	global_load_dword v134, v[54:55], off nt
	global_load_dword v135, v[52:53], off nt
	v_mad_u64_u32 v[52:53], s[72:73], v57, s40, v[2:3]
	v_mad_u64_u32 v[54:55], s[72:73], v56, s40, v[2:3]
	s_add_i32 s72, s70, 20
	v_or_b32_e32 v56, s71, v1
	v_or_b32_e32 v57, s72, v0
	v_add_lshl_u32 v53, v57, v48, 10
	s_add_i32 s71, s69, 24
	s_add_i32 s69, s69, 28
	v_mov_b32_e32 v150, v52
	v_mov_b32_e32 v151, v54
	v_add_lshl_u32 v4, v56, v3, 10
	v_or_b32_e32 v52, v49, v4
	v_or_b32_e32 v4, v50, v53
	v_lshl_add_u64 v[54:55], v[4:5], 2, s[88:89]
	v_mov_b32_e32 v53, v5
	v_lshl_add_u64 v[52:53], v[52:53], 2, s[88:89]
	global_load_dword v136, v[54:55], off nt
	global_load_dword v137, v[52:53], off nt
	v_mad_u64_u32 v[52:53], s[72:73], v57, s40, v[2:3]
	v_mad_u64_u32 v[54:55], s[72:73], v56, s40, v[2:3]
	s_add_i32 s72, s70, 24
	v_or_b32_e32 v56, s71, v1
	v_or_b32_e32 v57, s72, v0
	v_add_lshl_u32 v53, v57, v48, 10
	s_add_i32 s70, s70, 28
	s_cmp_lg_u32 s68, 0
	v_mov_b32_e32 v152, v52
	v_mov_b32_e32 v153, v54
	v_add_lshl_u32 v4, v56, v3, 10
	v_or_b32_e32 v52, v49, v4
	v_or_b32_e32 v4, v50, v53
	v_lshl_add_u64 v[54:55], v[4:5], 2, s[88:89]
	v_mov_b32_e32 v53, v5
	v_lshl_add_u64 v[52:53], v[52:53], 2, s[88:89]
	global_load_dword v138, v[54:55], off nt
	global_load_dword v139, v[52:53], off nt
	v_mad_u64_u32 v[52:53], s[72:73], v57, s40, v[2:3]
	v_mad_u64_u32 v[54:55], s[72:73], v56, s40, v[2:3]
	v_or_b32_e32 v56, s69, v1
	v_or_b32_e32 v57, s70, v0
	v_mov_b32_e32 v55, v5
	v_mov_b32_e32 v154, v52
	v_mov_b32_e32 v155, v54
	v_add_lshl_u32 v4, v56, v3, 10
	v_add_lshl_u32 v52, v57, v48, 10
	v_or_b32_e32 v54, v49, v4
	v_or_b32_e32 v4, v50, v52
	v_lshl_add_u64 v[52:53], v[4:5], 2, s[88:89]
	v_lshl_add_u64 v[54:55], v[54:55], 2, s[88:89]
	global_load_dword v140, v[52:53], off nt
	global_load_dword v141, v[54:55], off nt
	v_mad_u64_u32 v[52:53], s[70:71], v57, s40, v[2:3]
	v_mad_u64_u32 v[54:55], s[70:71], v56, s40, v[2:3]
	v_mov_b32_e32 v156, v52
	v_mov_b32_e32 v157, v54
	s_waitcnt vmcnt(15)
	ds_write_b32 v142, v126
	s_waitcnt vmcnt(14)
	ds_write_b32 v143, v127
	s_waitcnt vmcnt(13)
	ds_write_b32 v144, v128
	s_waitcnt vmcnt(12)
	ds_write_b32 v145, v129
	s_waitcnt vmcnt(11)
	ds_write_b32 v146, v130
	s_waitcnt vmcnt(10)
	ds_write_b32 v147, v131
	s_waitcnt vmcnt(9)
	ds_write_b32 v148, v132
	s_waitcnt vmcnt(8)
	ds_write_b32 v149, v133
	s_waitcnt vmcnt(7)
	ds_write_b32 v150, v134
	s_waitcnt vmcnt(6)
	ds_write_b32 v151, v135
	s_waitcnt vmcnt(5)
	ds_write_b32 v152, v136
	s_waitcnt vmcnt(4)
	ds_write_b32 v153, v137
	s_waitcnt vmcnt(3)
	ds_write_b32 v154, v138
	s_waitcnt vmcnt(2)
	ds_write_b32 v155, v139
	s_waitcnt vmcnt(1)
	ds_write_b32 v156, v140
	s_waitcnt vmcnt(0)
	ds_write_b32 v157, v141
	s_cbranch_scc1 .LBB0_916
	v_or_b32_e32 v3, v51, v96
	v_lshlrev_b32_e32 v4, 2, v3
	v_or_b32_e32 v49, 0x5000, v4
	global_load_dword v90, v49, s[12:13]
	global_load_dword v80, v49, s[92:93]
	v_or_b32_e32 v49, 0x5020, v4
	global_load_dword v62, v49, s[12:13]
	global_load_dword v60, v49, s[92:93]
	v_or_b32_e32 v49, 0x5040, v4
	global_load_dword v58, v49, s[12:13]
	global_load_dword v56, v49, s[92:93]
	v_or_b32_e32 v4, 0x5060, v4
	global_load_dword v52, v4, s[12:13]
	global_load_dword v50, v4, s[92:93]
	s_waitcnt lgkmcnt(0)
	ds_read2_b32 v[74:75], v97 offset0:33 offset1:41
	ds_read2_b32 v[66:67], v97 offset0:66 offset1:74
	ds_read2_b32 v[64:65], v97 offset0:99 offset1:107
	ds_read2_b32 v[76:77], v97 offset0:132 offset1:140
	ds_read2_b32 v[72:73], v97 offset0:165 offset1:173
	ds_read2_b32 v[70:71], v97 offset0:198 offset1:206
	ds_read2_b32 v[68:69], v97 offset0:231 offset1:239
	ds_read2_b32 v[78:79], v97 offset1:8
	s_waitcnt lgkmcnt(4)
	v_mov_b32_e32 v86, v76
	v_mov_b32_e32 v83, v66
	s_waitcnt lgkmcnt(2)
	v_mov_b32_e32 v87, v70
	v_mov_b32_e32 v84, v74
	s_waitcnt lgkmcnt(0)
	v_mov_b32_e32 v82, v78
	v_mov_b32_e32 v85, v64
	v_mov_b32_e32 v88, v72
	v_mov_b32_e32 v89, v68
	v_lshlrev_b32_e32 v4, 1, v48
	v_lshl_add_u64 v[54:55], v[6:7], 0, v[4:5]
	v_lshl_add_u64 v[48:49], v[22:23], 0, v[4:5]
	v_mul_u32_u24_e32 v3, 0xb00, v3
	v_mov_b32_e32 v70, v77
	v_mov_b32_e32 v68, v73
	s_waitcnt vmcnt(7)
	v_pk_mul_f32 v[112:113], v[90:91], v[86:87] op_sel_hi:[0,1]
	v_pk_mul_f32 v[92:93], v[90:91], v[82:83] op_sel_hi:[0,1]
	v_pk_mul_f32 v[110:111], v[90:91], v[84:85] op_sel_hi:[0,1]
	v_pk_mul_f32 v[90:91], v[90:91], v[88:89] op_sel_hi:[0,1]
	v_bfe_u32 v64, v112, 16, 1
	v_bfe_u32 v66, v113, 16, 1
	v_bfe_u32 v4, v91, 16, 1
	v_bfe_u32 v53, v90, 16, 1
	v_bfe_u32 v63, v93, 16, 1
	v_add3_u32 v66, v113, v66, s46
	v_add3_u32 v64, v112, v64, s46
	v_bfe_u32 v57, v111, 16, 1
	v_add3_u32 v53, v90, v53, s46
	v_add3_u32 v4, v91, v4, s46
	v_bfe_u32 v61, v92, 16, 1
	v_add3_u32 v63, v93, v63, s46
	v_lshrrev_b32_e32 v64, 16, v64
	v_lshrrev_b32_e32 v66, 16, v66
	s_waitcnt vmcnt(6)
	v_pk_mul_f32 v[86:87], v[80:81], v[86:87] op_sel_hi:[0,1]
	v_bfe_u32 v59, v110, 16, 1
	v_add3_u32 v57, v111, v57, s46
	v_add3_u32 v61, v92, v61, s46
	v_lshrrev_b32_e32 v63, 16, v63
	v_and_or_b32 v93, v4, s47, v66
	v_and_or_b32 v92, v53, s47, v64
	v_pk_mul_f32 v[82:83], v[80:81], v[82:83] op_sel_hi:[0,1]
	v_pk_mul_f32 v[84:85], v[80:81], v[84:85] op_sel_hi:[0,1]
	v_pk_mul_f32 v[80:81], v[80:81], v[88:89] op_sel_hi:[0,1]
	v_bfe_u32 v64, v86, 16, 1
	v_bfe_u32 v66, v87, 16, 1
	v_add3_u32 v59, v110, v59, s46
	v_lshrrev_b32_e32 v61, 16, v61
	v_and_or_b32 v91, v57, s47, v63
	v_lshlrev_b32_e32 v4, 1, v3
	v_bfe_u32 v3, v81, 16, 1
	v_bfe_u32 v53, v80, 16, 1
	v_bfe_u32 v63, v83, 16, 1
	v_add3_u32 v66, v87, v66, s46
	v_add3_u32 v64, v86, v64, s46
	v_and_or_b32 v90, v59, s47, v61
	v_bfe_u32 v57, v85, 16, 1
	v_add3_u32 v53, v80, v53, s46
	v_add3_u32 v3, v81, v3, s46
	v_bfe_u32 v61, v82, 16, 1
	v_add3_u32 v63, v83, v63, s46
	v_lshrrev_b32_e32 v64, 16, v64
	v_lshrrev_b32_e32 v66, 16, v66
	v_add3_u32 v57, v85, v57, s46
	v_add3_u32 v61, v82, v61, s46
	v_lshrrev_b32_e32 v63, 16, v63
	v_and_or_b32 v83, v3, s47, v66
	v_and_or_b32 v82, v53, s47, v64
	v_mov_b32_e32 v66, v79
	v_mov_b32_e32 v64, v75
	v_and_or_b32 v81, v57, s47, v63
	s_waitcnt vmcnt(5)
	v_pk_mul_f32 v[78:79], v[62:63], v[66:67] op_sel_hi:[0,1]
	v_pk_mul_f32 v[74:75], v[62:63], v[64:65] op_sel_hi:[0,1]
	v_pk_mul_f32 v[76:77], v[62:63], v[70:71] op_sel_hi:[0,1]
	v_pk_mul_f32 v[62:63], v[62:63], v[68:69] op_sel_hi:[0,1]
	v_bfe_u32 v3, v63, 16, 1
	v_bfe_u32 v59, v84, 16, 1
	v_add3_u32 v3, v63, v3, s46
	v_bfe_u32 v63, v77, 16, 1
	v_lshl_add_u64 v[110:111], v[54:55], 0, v[4:5]
	v_add3_u32 v59, v84, v59, s46
	v_lshl_add_u64 v[84:85], v[48:49], 0, v[4:5]
	v_bfe_u32 v4, v62, 16, 1
	v_add3_u32 v63, v77, v63, s46
	v_lshrrev_b32_e32 v61, 16, v61
	v_bfe_u32 v53, v75, 16, 1
	v_add3_u32 v4, v62, v4, s46
	v_bfe_u32 v62, v76, 16, 1
	v_lshrrev_b32_e32 v63, 16, v63
	v_and_or_b32 v80, v59, s47, v61
	v_add3_u32 v53, v75, v53, s46
	v_bfe_u32 v59, v78, 16, 1
	v_bfe_u32 v61, v79, 16, 1
	v_add3_u32 v62, v76, v62, s46
	v_and_or_b32 v75, v3, s47, v63
	v_or_b32_e32 v3, v51, v98
	v_bfe_u32 v57, v74, 16, 1
	v_add3_u32 v61, v79, v61, s46
	v_add3_u32 v59, v78, v59, s46
	v_lshrrev_b32_e32 v62, 16, v62
	v_mul_u32_u24_e32 v3, 0xb00, v3
	v_add3_u32 v57, v74, v57, s46
	v_lshrrev_b32_e32 v59, 16, v59
	v_lshrrev_b32_e32 v61, 16, v61
	v_and_or_b32 v74, v4, s47, v62
	v_lshlrev_b32_e32 v4, 1, v3
	v_and_or_b32 v73, v53, s47, v61
	v_and_or_b32 v72, v57, s47, v59
	v_lshl_add_u64 v[62:63], v[54:55], 0, v[4:5]
	global_store_dwordx4 v[110:111], v[90:93], off
	global_store_dwordx4 v[84:85], v[80:83], off
	global_store_dwordx4 v[62:63], v[72:75], off
	s_waitcnt vmcnt(7)
	v_pk_mul_f32 v[62:63], v[60:61], v[66:67] op_sel_hi:[0,1]
	v_pk_mul_f32 v[64:65], v[60:61], v[64:65] op_sel_hi:[0,1]
	v_pk_mul_f32 v[66:67], v[60:61], v[70:71] op_sel_hi:[0,1]
	v_pk_mul_f32 v[60:61], v[60:61], v[68:69] op_sel_hi:[0,1]
	v_bfe_u32 v3, v61, 16, 1
	v_bfe_u32 v53, v60, 16, 1
	v_bfe_u32 v57, v65, 16, 1
	v_bfe_u32 v59, v64, 16, 1
	v_add3_u32 v59, v64, v59, s46
	v_add3_u32 v57, v65, v57, s46
	v_add3_u32 v53, v60, v53, s46
	v_add3_u32 v3, v61, v3, s46
	v_bfe_u32 v60, v62, 16, 1
	v_bfe_u32 v61, v63, 16, 1
	v_bfe_u32 v64, v66, 16, 1
	v_bfe_u32 v65, v67, 16, 1
	v_add3_u32 v65, v67, v65, s46
	v_add3_u32 v64, v66, v64, s46
	v_add3_u32 v61, v63, v61, s46
	v_add3_u32 v60, v62, v60, s46
	v_lshrrev_b32_e32 v60, 16, v60
	v_lshrrev_b32_e32 v61, 16, v61
	v_lshrrev_b32_e32 v62, 16, v64
	v_lshrrev_b32_e32 v63, 16, v65
	v_and_or_b32 v63, v3, s47, v63
	v_and_or_b32 v62, v53, s47, v62
	v_and_or_b32 v61, v57, s47, v61
	v_and_or_b32 v60, v59, s47, v60
	v_lshl_add_u64 v[64:65], v[48:49], 0, v[4:5]
	global_store_dwordx4 v[64:65], v[60:63], off
	ds_read2_b32 v[62:63], v97 offset0:16 offset1:24
	ds_read2_b32 v[64:65], v97 offset0:49 offset1:57
	ds_read2_b32 v[66:67], v97 offset0:82 offset1:90
	ds_read2_b32 v[68:69], v97 offset0:115 offset1:123
	ds_read2_b32 v[70:71], v97 offset0:148 offset1:156
	ds_read2_b32 v[72:73], v97 offset0:181 offset1:189
	ds_read2_b32 v[74:75], v97 offset0:214 offset1:222
	ds_read2_b32 v[76:77], v97 offset0:247 offset1:255
	s_waitcnt lgkmcnt(7)
	v_mov_b32_e32 v78, v62
	s_waitcnt lgkmcnt(5)
	v_mov_b32_e32 v79, v66
	v_mov_b32_e32 v80, v64
	s_waitcnt lgkmcnt(4)
	v_mov_b32_e32 v81, v68
	s_waitcnt lgkmcnt(3)
	v_mov_b32_e32 v84, v70
	s_waitcnt lgkmcnt(1)
	v_mov_b32_e32 v85, v74
	v_mov_b32_e32 v88, v72
	s_waitcnt lgkmcnt(0)
	v_mov_b32_e32 v89, v76
	s_waitcnt vmcnt(7)
	v_pk_mul_f32 v[60:61], v[58:59], v[78:79] op_sel_hi:[0,1]
	v_pk_mul_f32 v[82:83], v[58:59], v[80:81] op_sel_hi:[0,1]
	v_pk_mul_f32 v[86:87], v[58:59], v[84:85] op_sel_hi:[0,1]
	v_pk_mul_f32 v[58:59], v[58:59], v[88:89] op_sel_hi:[0,1]
	v_bfe_u32 v3, v59, 16, 1
	v_bfe_u32 v64, v87, 16, 1
	v_add3_u32 v3, v59, v3, s46
	v_bfe_u32 v59, v61, 16, 1
	v_add3_u32 v64, v87, v64, s46
	v_bfe_u32 v4, v58, 16, 1
	v_bfe_u32 v62, v86, 16, 1
	v_add3_u32 v59, v61, v59, s46
	v_lshrrev_b32_e32 v61, 16, v64
	v_add3_u32 v4, v58, v4, s46
	v_bfe_u32 v58, v60, 16, 1
	v_add3_u32 v62, v86, v62, s46
	v_and_or_b32 v61, v3, s47, v61
	v_or_b32_e32 v3, v51, v99
	v_bfe_u32 v53, v83, 16, 1
	v_bfe_u32 v57, v82, 16, 1
	v_add3_u32 v58, v60, v58, s46
	v_lshrrev_b32_e32 v60, 16, v62
	v_mul_u32_u24_e32 v3, 0xb00, v3
	v_add3_u32 v57, v82, v57, s46
	v_add3_u32 v53, v83, v53, s46
	v_lshrrev_b32_e32 v58, 16, v58
	v_lshrrev_b32_e32 v59, 16, v59
	v_and_or_b32 v60, v4, s47, v60
	v_lshlrev_b32_e32 v4, 1, v3
	v_and_or_b32 v59, v53, s47, v59
	v_and_or_b32 v58, v57, s47, v58
	v_lshl_add_u64 v[82:83], v[54:55], 0, v[4:5]
	global_store_dwordx4 v[82:83], v[58:61], off
	v_mov_b32_e32 v68, v65
	v_mov_b32_e32 v66, v63
	s_waitcnt vmcnt(7)
	v_pk_mul_f32 v[58:59], v[56:57], v[78:79] op_sel_hi:[0,1]
	v_pk_mul_f32 v[60:61], v[56:57], v[80:81] op_sel_hi:[0,1]
	v_pk_mul_f32 v[78:79], v[56:57], v[84:85] op_sel_hi:[0,1]
	v_pk_mul_f32 v[56:57], v[56:57], v[88:89] op_sel_hi:[0,1]
	v_bfe_u32 v3, v57, 16, 1
	v_bfe_u32 v53, v56, 16, 1
	v_bfe_u32 v62, v61, 16, 1
	v_bfe_u32 v64, v60, 16, 1
	v_add3_u32 v60, v60, v64, s46
	v_add3_u32 v61, v61, v62, s46
	v_add3_u32 v53, v56, v53, s46
	v_add3_u32 v3, v57, v3, s46
	v_bfe_u32 v56, v58, 16, 1
	v_bfe_u32 v57, v59, 16, 1
	v_bfe_u32 v62, v78, 16, 1
	v_bfe_u32 v64, v79, 16, 1
	v_add3_u32 v64, v79, v64, s46
	v_add3_u32 v62, v78, v62, s46
	v_add3_u32 v57, v59, v57, s46
	v_add3_u32 v56, v58, v56, s46
	v_lshrrev_b32_e32 v56, 16, v56
	v_lshrrev_b32_e32 v57, 16, v57
	v_lshrrev_b32_e32 v58, 16, v62
	v_lshrrev_b32_e32 v59, 16, v64
	v_and_or_b32 v59, v3, s47, v59
	v_and_or_b32 v58, v53, s47, v58
	v_and_or_b32 v57, v61, s47, v57
	v_and_or_b32 v56, v60, s47, v56
	v_lshl_add_u64 v[60:61], v[48:49], 0, v[4:5]
	global_store_dwordx4 v[60:61], v[56:59], off
	v_mov_b32_e32 v74, v71
	v_mov_b32_e32 v76, v73
	s_waitcnt vmcnt(7)
	v_pk_mul_f32 v[58:59], v[52:53], v[68:69] op_sel_hi:[0,1]
	v_pk_mul_f32 v[56:57], v[52:53], v[66:67] op_sel_hi:[0,1]
	v_pk_mul_f32 v[60:61], v[52:53], v[74:75] op_sel_hi:[0,1]
	v_pk_mul_f32 v[52:53], v[52:53], v[76:77] op_sel_hi:[0,1]
	v_bfe_u32 v62, v59, 16, 1
	v_bfe_u32 v3, v53, 16, 1
	v_add3_u32 v62, v59, v62, s46
	v_bfe_u32 v59, v61, 16, 1
	v_bfe_u32 v63, v58, 16, 1
	v_add3_u32 v3, v53, v3, s46
	v_bfe_u32 v53, v57, 16, 1
	v_add3_u32 v59, v61, v59, s46
	v_bfe_u32 v4, v52, 16, 1
	v_add3_u32 v63, v58, v63, s46
	v_bfe_u32 v58, v60, 16, 1
	v_add3_u32 v53, v57, v53, s46
	v_lshrrev_b32_e32 v57, 16, v59
	v_add3_u32 v4, v52, v4, s46
	v_bfe_u32 v52, v56, 16, 1
	v_add3_u32 v58, v60, v58, s46
	v_and_or_b32 v59, v3, s47, v57
	v_or_b32_e32 v3, v51, v100
	v_add3_u32 v52, v56, v52, s46
	v_lshrrev_b32_e32 v56, 16, v58
	v_mul_u32_u24_e32 v3, 0xb00, v3
	v_lshrrev_b32_e32 v52, 16, v52
	v_lshrrev_b32_e32 v53, 16, v53
	v_and_or_b32 v58, v4, s47, v56
	v_lshlrev_b32_e32 v4, 1, v3
	v_and_or_b32 v57, v62, s47, v53
	v_and_or_b32 v56, v63, s47, v52
	v_lshl_add_u64 v[52:53], v[54:55], 0, v[4:5]
	global_store_dwordx4 v[52:53], v[56:59], off
	s_waitcnt vmcnt(7)
	v_pk_mul_f32 v[52:53], v[50:51], v[66:67] op_sel_hi:[0,1]
	v_pk_mul_f32 v[54:55], v[50:51], v[68:69] op_sel_hi:[0,1]
	v_pk_mul_f32 v[56:57], v[50:51], v[74:75] op_sel_hi:[0,1]
	v_pk_mul_f32 v[50:51], v[50:51], v[76:77] op_sel_hi:[0,1]
	v_bfe_u32 v3, v51, 16, 1
	v_bfe_u32 v58, v50, 16, 1
	v_bfe_u32 v59, v55, 16, 1
	v_bfe_u32 v60, v54, 16, 1
	v_add3_u32 v54, v54, v60, s46
	v_add3_u32 v55, v55, v59, s46
	v_add3_u32 v50, v50, v58, s46
	v_add3_u32 v3, v51, v3, s46
	v_bfe_u32 v51, v52, 16, 1
	v_bfe_u32 v58, v53, 16, 1
	v_bfe_u32 v59, v56, 16, 1
	v_bfe_u32 v60, v57, 16, 1
	v_add3_u32 v57, v57, v60, s46
	v_add3_u32 v56, v56, v59, s46
	v_add3_u32 v53, v53, v58, s46
	v_add3_u32 v51, v52, v51, s46
	v_lshrrev_b32_e32 v58, 16, v51
	v_lshrrev_b32_e32 v51, 16, v53
	v_lshrrev_b32_e32 v52, 16, v56
	v_lshrrev_b32_e32 v53, 16, v57
	v_and_or_b32 v53, v3, s47, v53
	v_and_or_b32 v52, v50, s47, v52
	v_and_or_b32 v51, v55, s47, v51
	v_and_or_b32 v50, v54, s47, v58
	v_lshl_add_u64 v[48:49], v[48:49], 0, v[4:5]
	global_store_dwordx4 v[48:49], v[50:53], off
	s_waitcnt lgkmcnt(0)

.LBB0_920:
	s_lshl_b32 s69, s64, 1
	s_lshl_b32 s70, s65, 1
	v_or_b32_e32 v56, s69, v1
	v_or_b32_e32 v57, s70, v0
	v_add_lshl_u32 v4, v56, v3, 10
	v_add_lshl_u32 v53, v57, v48, 10
	v_or_b32_e32 v52, v49, v4
	v_or_b32_e32 v4, v50, v53
	v_lshl_add_u64 v[54:55], v[4:5], 2, s[60:61]
	v_mov_b32_e32 v53, v5
	v_lshl_add_u64 v[52:53], v[52:53], 2, s[60:61]
	global_load_dword v126, v[54:55], off nt
	global_load_dword v127, v[52:53], off nt
	v_mad_u64_u32 v[52:53], s[72:73], v57, s40, v[2:3]
	v_mad_u64_u32 v[54:55], s[72:73], v56, s40, v[2:3]
	s_add_i32 s71, s69, 4
	s_add_i32 s72, s70, 4
	v_or_b32_e32 v56, s71, v1
	v_or_b32_e32 v57, s72, v0
	v_add_lshl_u32 v53, v57, v48, 10
	s_add_i32 s71, s69, 8
	s_add_i32 s65, s65, 16
	s_add_i32 s64, s64, 16
	s_add_i32 s68, s68, -16
	v_mov_b32_e32 v142, v52
	v_mov_b32_e32 v143, v54
	v_add_lshl_u32 v4, v56, v3, 10
	v_or_b32_e32 v52, v49, v4
	v_or_b32_e32 v4, v50, v53
	v_lshl_add_u64 v[54:55], v[4:5], 2, s[60:61]
	v_mov_b32_e32 v53, v5
	v_lshl_add_u64 v[52:53], v[52:53], 2, s[60:61]
	global_load_dword v128, v[54:55], off nt
	global_load_dword v129, v[52:53], off nt
	v_mad_u64_u32 v[52:53], s[72:73], v57, s40, v[2:3]
	v_mad_u64_u32 v[54:55], s[72:73], v56, s40, v[2:3]
	s_add_i32 s72, s70, 8
	v_or_b32_e32 v56, s71, v1
	v_or_b32_e32 v57, s72, v0
	v_add_lshl_u32 v53, v57, v48, 10
	s_add_i32 s71, s69, 12
	v_mov_b32_e32 v144, v52
	v_mov_b32_e32 v145, v54
	v_add_lshl_u32 v4, v56, v3, 10
	v_or_b32_e32 v52, v49, v4
	v_or_b32_e32 v4, v50, v53
	v_lshl_add_u64 v[54:55], v[4:5], 2, s[60:61]
	v_mov_b32_e32 v53, v5
	v_lshl_add_u64 v[52:53], v[52:53], 2, s[60:61]
	global_load_dword v130, v[54:55], off nt
	global_load_dword v131, v[52:53], off nt
	v_mad_u64_u32 v[52:53], s[72:73], v57, s40, v[2:3]
	v_mad_u64_u32 v[54:55], s[72:73], v56, s40, v[2:3]
	s_add_i32 s72, s70, 12
	v_or_b32_e32 v56, s71, v1
	v_or_b32_e32 v57, s72, v0
	v_add_lshl_u32 v53, v57, v48, 10
	s_add_i32 s71, s69, 16
	v_mov_b32_e32 v146, v52
	v_mov_b32_e32 v147, v54
	v_add_lshl_u32 v4, v56, v3, 10
	v_or_b32_e32 v52, v49, v4
	v_or_b32_e32 v4, v50, v53
	v_lshl_add_u64 v[54:55], v[4:5], 2, s[60:61]
	v_mov_b32_e32 v53, v5
	v_lshl_add_u64 v[52:53], v[52:53], 2, s[60:61]
	global_load_dword v132, v[54:55], off nt
	global_load_dword v133, v[52:53], off nt
	v_mad_u64_u32 v[52:53], s[72:73], v57, s40, v[2:3]
	v_mad_u64_u32 v[54:55], s[72:73], v56, s40, v[2:3]
	s_add_i32 s72, s70, 16
	v_or_b32_e32 v56, s71, v1
	v_or_b32_e32 v57, s72, v0
	v_add_lshl_u32 v53, v57, v48, 10
	s_add_i32 s71, s69, 20
	v_mov_b32_e32 v148, v52
	v_mov_b32_e32 v149, v54
	v_add_lshl_u32 v4, v56, v3, 10
	v_or_b32_e32 v52, v49, v4
	v_or_b32_e32 v4, v50, v53
	v_lshl_add_u64 v[54:55], v[4:5], 2, s[60:61]
	v_mov_b32_e32 v53, v5
	v_lshl_add_u64 v[52:53], v[52:53], 2, s[60:61]
	global_load_dword v134, v[54:55], off nt
	global_load_dword v135, v[52:53], off nt
	v_mad_u64_u32 v[52:53], s[72:73], v57, s40, v[2:3]
	v_mad_u64_u32 v[54:55], s[72:73], v56, s40, v[2:3]
	s_add_i32 s72, s70, 20
	v_or_b32_e32 v56, s71, v1
	v_or_b32_e32 v57, s72, v0
	v_add_lshl_u32 v53, v57, v48, 10
	s_add_i32 s71, s69, 24
	s_add_i32 s69, s69, 28
	v_mov_b32_e32 v150, v52
	v_mov_b32_e32 v151, v54
	v_add_lshl_u32 v4, v56, v3, 10
	v_or_b32_e32 v52, v49, v4
	v_or_b32_e32 v4, v50, v53
	v_lshl_add_u64 v[54:55], v[4:5], 2, s[60:61]
	v_mov_b32_e32 v53, v5
	v_lshl_add_u64 v[52:53], v[52:53], 2, s[60:61]
	global_load_dword v136, v[54:55], off nt
	global_load_dword v137, v[52:53], off nt
	v_mad_u64_u32 v[52:53], s[72:73], v57, s40, v[2:3]
	v_mad_u64_u32 v[54:55], s[72:73], v56, s40, v[2:3]
	s_add_i32 s72, s70, 24
	v_or_b32_e32 v56, s71, v1
	v_or_b32_e32 v57, s72, v0
	v_add_lshl_u32 v53, v57, v48, 10
	s_add_i32 s70, s70, 28
	s_cmp_lg_u32 s68, 0
	v_mov_b32_e32 v152, v52
	v_mov_b32_e32 v153, v54
	v_add_lshl_u32 v4, v56, v3, 10
	v_or_b32_e32 v52, v49, v4
	v_or_b32_e32 v4, v50, v53
	v_lshl_add_u64 v[54:55], v[4:5], 2, s[60:61]
	v_mov_b32_e32 v53, v5
	v_lshl_add_u64 v[52:53], v[52:53], 2, s[60:61]
	global_load_dword v138, v[54:55], off nt
	global_load_dword v139, v[52:53], off nt
	v_mad_u64_u32 v[52:53], s[72:73], v57, s40, v[2:3]
	v_mad_u64_u32 v[54:55], s[72:73], v56, s40, v[2:3]
	v_or_b32_e32 v56, s69, v1
	v_or_b32_e32 v57, s70, v0
	v_mov_b32_e32 v55, v5
	v_mov_b32_e32 v154, v52
	v_mov_b32_e32 v155, v54
	v_add_lshl_u32 v4, v56, v3, 10
	v_add_lshl_u32 v52, v57, v48, 10
	v_or_b32_e32 v54, v49, v4
	v_or_b32_e32 v4, v50, v52
	v_lshl_add_u64 v[52:53], v[4:5], 2, s[60:61]
	v_lshl_add_u64 v[54:55], v[54:55], 2, s[60:61]
	global_load_dword v140, v[52:53], off nt
	global_load_dword v141, v[54:55], off nt
	v_mad_u64_u32 v[52:53], s[70:71], v57, s40, v[2:3]
	v_mad_u64_u32 v[54:55], s[70:71], v56, s40, v[2:3]
	v_mov_b32_e32 v156, v52
	v_mov_b32_e32 v157, v54
	s_waitcnt vmcnt(15)
	ds_write_b32 v142, v126
	s_waitcnt vmcnt(14)
	ds_write_b32 v143, v127
	s_waitcnt vmcnt(13)
	ds_write_b32 v144, v128
	s_waitcnt vmcnt(12)
	ds_write_b32 v145, v129
	s_waitcnt vmcnt(11)
	ds_write_b32 v146, v130
	s_waitcnt vmcnt(10)
	ds_write_b32 v147, v131
	s_waitcnt vmcnt(9)
	ds_write_b32 v148, v132
	s_waitcnt vmcnt(8)
	ds_write_b32 v149, v133
	s_waitcnt vmcnt(7)
	ds_write_b32 v150, v134
	s_waitcnt vmcnt(6)
	ds_write_b32 v151, v135
	s_waitcnt vmcnt(5)
	ds_write_b32 v152, v136
	s_waitcnt vmcnt(4)
	ds_write_b32 v153, v137
	s_waitcnt vmcnt(3)
	ds_write_b32 v154, v138
	s_waitcnt vmcnt(2)
	ds_write_b32 v155, v139
	s_waitcnt vmcnt(1)
	ds_write_b32 v156, v140
	s_waitcnt vmcnt(0)
	ds_write_b32 v157, v141
	s_cbranch_scc1 .LBB0_920
	v_or_b32_e32 v3, v51, v96
	v_lshlrev_b32_e32 v4, 2, v3
	v_or_b32_e32 v49, 0x2000, v4
	global_load_dword v90, v49, s[12:13]
	global_load_dword v80, v49, s[92:93]
	v_or_b32_e32 v49, 0x2020, v4
	global_load_dword v62, v49, s[12:13]
	global_load_dword v60, v49, s[92:93]
	v_or_b32_e32 v49, 0x2040, v4
	global_load_dword v58, v49, s[12:13]
	global_load_dword v56, v49, s[92:93]
	v_or_b32_e32 v4, 0x2060, v4
	global_load_dword v52, v4, s[12:13]
	global_load_dword v50, v4, s[92:93]
	s_waitcnt lgkmcnt(0)
	ds_read2_b32 v[74:75], v97 offset0:33 offset1:41
	ds_read2_b32 v[66:67], v97 offset0:66 offset1:74
	ds_read2_b32 v[64:65], v97 offset0:99 offset1:107
	ds_read2_b32 v[76:77], v97 offset0:132 offset1:140
	ds_read2_b32 v[72:73], v97 offset0:165 offset1:173
	ds_read2_b32 v[70:71], v97 offset0:198 offset1:206
	ds_read2_b32 v[68:69], v97 offset0:231 offset1:239
	ds_read2_b32 v[78:79], v97 offset1:8
	s_waitcnt lgkmcnt(4)
	v_mov_b32_e32 v86, v76
	v_mov_b32_e32 v83, v66
	s_waitcnt lgkmcnt(2)
	v_mov_b32_e32 v87, v70
	v_mov_b32_e32 v84, v74
	s_waitcnt lgkmcnt(0)
	v_mov_b32_e32 v82, v78
	v_mov_b32_e32 v85, v64
	v_mov_b32_e32 v88, v72
	v_mov_b32_e32 v89, v68
	v_lshlrev_b32_e32 v4, 1, v48
	v_lshl_add_u64 v[54:55], v[8:9], 0, v[4:5]
	v_lshl_add_u64 v[48:49], v[24:25], 0, v[4:5]
	v_mov_b32_e32 v70, v77
	v_mov_b32_e32 v68, v73
	s_waitcnt vmcnt(7)
	v_pk_mul_f32 v[112:113], v[90:91], v[86:87] op_sel_hi:[0,1]
	v_pk_mul_f32 v[92:93], v[90:91], v[82:83] op_sel_hi:[0,1]
	v_pk_mul_f32 v[110:111], v[90:91], v[84:85] op_sel_hi:[0,1]
	v_pk_mul_f32 v[90:91], v[90:91], v[88:89] op_sel_hi:[0,1]
	v_bfe_u32 v64, v112, 16, 1
	v_bfe_u32 v66, v113, 16, 1
	v_bfe_u32 v4, v91, 16, 1
	v_bfe_u32 v53, v90, 16, 1
	v_bfe_u32 v63, v93, 16, 1
	v_add3_u32 v66, v113, v66, s46
	v_add3_u32 v64, v112, v64, s46
	v_bfe_u32 v57, v111, 16, 1
	v_add3_u32 v53, v90, v53, s46
	v_add3_u32 v4, v91, v4, s46
	v_bfe_u32 v61, v92, 16, 1
	v_add3_u32 v63, v93, v63, s46
	v_lshrrev_b32_e32 v64, 16, v64
	v_lshrrev_b32_e32 v66, 16, v66
	s_waitcnt vmcnt(6)
	v_pk_mul_f32 v[86:87], v[80:81], v[86:87] op_sel_hi:[0,1]
	v_bfe_u32 v59, v110, 16, 1
	v_add3_u32 v57, v111, v57, s46
	v_add3_u32 v61, v92, v61, s46
	v_lshrrev_b32_e32 v63, 16, v63
	v_and_or_b32 v93, v4, s47, v66
	v_and_or_b32 v92, v53, s47, v64
	v_pk_mul_f32 v[82:83], v[80:81], v[82:83] op_sel_hi:[0,1]
	v_pk_mul_f32 v[84:85], v[80:81], v[84:85] op_sel_hi:[0,1]
	v_pk_mul_f32 v[80:81], v[80:81], v[88:89] op_sel_hi:[0,1]
	v_bfe_u32 v64, v86, 16, 1
	v_bfe_u32 v66, v87, 16, 1
	v_add3_u32 v59, v110, v59, s46
	v_lshrrev_b32_e32 v61, 16, v61
	v_and_or_b32 v91, v57, s47, v63
	v_lshlrev_b32_e32 v4, 11, v3
	v_bfe_u32 v3, v81, 16, 1
	v_bfe_u32 v53, v80, 16, 1
	v_bfe_u32 v63, v83, 16, 1
	v_add3_u32 v66, v87, v66, s46
	v_add3_u32 v64, v86, v64, s46
	v_and_or_b32 v90, v59, s47, v61
	v_bfe_u32 v57, v85, 16, 1
	v_add3_u32 v53, v80, v53, s46
	v_add3_u32 v3, v81, v3, s46
	v_bfe_u32 v61, v82, 16, 1
	v_add3_u32 v63, v83, v63, s46
	v_lshrrev_b32_e32 v64, 16, v64
	v_lshrrev_b32_e32 v66, 16, v66
	v_add3_u32 v57, v85, v57, s46
	v_add3_u32 v61, v82, v61, s46
	v_lshrrev_b32_e32 v63, 16, v63
	v_and_or_b32 v83, v3, s47, v66
	v_and_or_b32 v82, v53, s47, v64
	v_mov_b32_e32 v66, v79
	v_mov_b32_e32 v64, v75
	v_and_or_b32 v81, v57, s47, v63
	s_waitcnt vmcnt(5)
	v_pk_mul_f32 v[78:79], v[62:63], v[66:67] op_sel_hi:[0,1]
	v_pk_mul_f32 v[74:75], v[62:63], v[64:65] op_sel_hi:[0,1]
	v_pk_mul_f32 v[76:77], v[62:63], v[70:71] op_sel_hi:[0,1]
	v_pk_mul_f32 v[62:63], v[62:63], v[68:69] op_sel_hi:[0,1]
	v_bfe_u32 v59, v84, 16, 1
	v_bfe_u32 v3, v63, 16, 1
	v_lshl_add_u64 v[110:111], v[54:55], 0, v[4:5]
	v_add3_u32 v59, v84, v59, s46
	v_lshl_add_u64 v[84:85], v[48:49], 0, v[4:5]
	v_bfe_u32 v4, v62, 16, 1
	v_add3_u32 v3, v63, v3, s46
	v_bfe_u32 v63, v77, 16, 1
	v_lshrrev_b32_e32 v61, 16, v61
	v_add3_u32 v4, v62, v4, s46
	v_bfe_u32 v62, v76, 16, 1
	v_add3_u32 v63, v77, v63, s46
	v_and_or_b32 v80, v59, s47, v61
	v_bfe_u32 v53, v75, 16, 1
	v_bfe_u32 v59, v78, 16, 1
	v_bfe_u32 v61, v79, 16, 1
	v_add3_u32 v62, v76, v62, s46
	v_lshrrev_b32_e32 v63, 16, v63
	v_bfe_u32 v57, v74, 16, 1
	v_add3_u32 v53, v75, v53, s46
	v_add3_u32 v61, v79, v61, s46
	v_add3_u32 v59, v78, v59, s46
	v_lshrrev_b32_e32 v62, 16, v62
	v_and_or_b32 v75, v3, s47, v63
	v_or_b32_e32 v3, v51, v98
	v_add3_u32 v57, v74, v57, s46
	v_lshrrev_b32_e32 v59, 16, v59
	v_lshrrev_b32_e32 v61, 16, v61
	v_and_or_b32 v74, v4, s47, v62
	v_lshlrev_b32_e32 v4, 11, v3
	v_and_or_b32 v73, v53, s47, v61
	v_and_or_b32 v72, v57, s47, v59
	v_lshl_add_u64 v[62:63], v[54:55], 0, v[4:5]
	global_store_dwordx4 v[62:63], v[72:75], off
	s_waitcnt vmcnt(5)
	v_pk_mul_f32 v[62:63], v[60:61], v[66:67] op_sel_hi:[0,1]
	v_pk_mul_f32 v[64:65], v[60:61], v[64:65] op_sel_hi:[0,1]
	v_pk_mul_f32 v[66:67], v[60:61], v[70:71] op_sel_hi:[0,1]
	v_pk_mul_f32 v[60:61], v[60:61], v[68:69] op_sel_hi:[0,1]
	v_bfe_u32 v3, v61, 16, 1
	v_bfe_u32 v53, v60, 16, 1
	v_bfe_u32 v57, v65, 16, 1
	v_bfe_u32 v59, v64, 16, 1
	v_add3_u32 v59, v64, v59, s46
	v_add3_u32 v57, v65, v57, s46
	v_add3_u32 v53, v60, v53, s46
	v_add3_u32 v3, v61, v3, s46
	v_bfe_u32 v60, v62, 16, 1
	v_bfe_u32 v61, v63, 16, 1
	v_bfe_u32 v64, v66, 16, 1
	v_bfe_u32 v65, v67, 16, 1
	v_add3_u32 v65, v67, v65, s46
	v_add3_u32 v64, v66, v64, s46
	v_add3_u32 v61, v63, v61, s46
	v_add3_u32 v60, v62, v60, s46
	v_lshrrev_b32_e32 v60, 16, v60
	v_lshrrev_b32_e32 v61, 16, v61
	v_lshrrev_b32_e32 v62, 16, v64
	v_lshrrev_b32_e32 v63, 16, v65
	v_and_or_b32 v63, v3, s47, v63
	v_and_or_b32 v62, v53, s47, v62
	v_and_or_b32 v61, v57, s47, v61
	v_and_or_b32 v60, v59, s47, v60
	v_lshl_add_u64 v[64:65], v[48:49], 0, v[4:5]
	global_store_dwordx4 v[110:111], v[90:93], off
	global_store_dwordx4 v[84:85], v[80:83], off
	global_store_dwordx4 v[64:65], v[60:63], off
	ds_read2_b32 v[62:63], v97 offset0:49 offset1:57
	ds_read2_b32 v[64:65], v97 offset0:82 offset1:90
	ds_read2_b32 v[66:67], v97 offset0:115 offset1:123
	ds_read2_b32 v[68:69], v97 offset0:148 offset1:156
	ds_read2_b32 v[70:71], v97 offset0:181 offset1:189
	ds_read2_b32 v[72:73], v97 offset0:214 offset1:222
	ds_read2_b32 v[74:75], v97 offset0:247 offset1:255
	ds_read2_b32 v[76:77], v97 offset0:16 offset1:24
	s_waitcnt lgkmcnt(6)
	v_mov_b32_e32 v79, v64
	v_mov_b32_e32 v80, v62
	s_waitcnt lgkmcnt(5)
	v_mov_b32_e32 v81, v66
	s_waitcnt lgkmcnt(4)
	v_mov_b32_e32 v84, v68
	s_waitcnt lgkmcnt(0)
	v_mov_b32_e32 v78, v76
	v_mov_b32_e32 v85, v72
	v_mov_b32_e32 v88, v70
	v_mov_b32_e32 v89, v74
	s_waitcnt vmcnt(7)
	v_pk_mul_f32 v[60:61], v[58:59], v[78:79] op_sel_hi:[0,1]
	v_pk_mul_f32 v[82:83], v[58:59], v[80:81] op_sel_hi:[0,1]
	v_pk_mul_f32 v[86:87], v[58:59], v[84:85] op_sel_hi:[0,1]
	v_pk_mul_f32 v[58:59], v[58:59], v[88:89] op_sel_hi:[0,1]
	v_bfe_u32 v3, v59, 16, 1
	v_bfe_u32 v64, v87, 16, 1
	v_bfe_u32 v4, v58, 16, 1
	v_add3_u32 v3, v59, v3, s46
	v_bfe_u32 v59, v61, 16, 1
	v_bfe_u32 v62, v86, 16, 1
	v_add3_u32 v64, v87, v64, s46
	v_add3_u32 v4, v58, v4, s46
	v_bfe_u32 v58, v60, 16, 1
	v_add3_u32 v62, v86, v62, s46
	v_add3_u32 v59, v61, v59, s46
	v_lshrrev_b32_e32 v61, 16, v64
	v_bfe_u32 v53, v83, 16, 1
	v_bfe_u32 v57, v82, 16, 1
	v_add3_u32 v58, v60, v58, s46
	v_lshrrev_b32_e32 v60, 16, v62
	v_and_or_b32 v61, v3, s47, v61
	v_or_b32_e32 v3, v51, v99
	v_add3_u32 v57, v82, v57, s46
	v_add3_u32 v53, v83, v53, s46
	v_lshrrev_b32_e32 v58, 16, v58
	v_lshrrev_b32_e32 v59, 16, v59
	v_and_or_b32 v60, v4, s47, v60
	v_lshlrev_b32_e32 v4, 11, v3
	v_and_or_b32 v59, v53, s47, v59
	v_and_or_b32 v58, v57, s47, v58
	v_lshl_add_u64 v[82:83], v[54:55], 0, v[4:5]
	global_store_dwordx4 v[82:83], v[58:61], off
	v_mov_b32_e32 v66, v63
	v_mov_b32_e32 v72, v69
	s_waitcnt vmcnt(7)
	v_pk_mul_f32 v[58:59], v[56:57], v[78:79] op_sel_hi:[0,1]
	v_pk_mul_f32 v[60:61], v[56:57], v[80:81] op_sel_hi:[0,1]
	v_pk_mul_f32 v[78:79], v[56:57], v[84:85] op_sel_hi:[0,1]
	v_pk_mul_f32 v[56:57], v[56:57], v[88:89] op_sel_hi:[0,1]
	v_bfe_u32 v3, v57, 16, 1
	v_bfe_u32 v53, v56, 16, 1
	v_bfe_u32 v62, v61, 16, 1
	v_bfe_u32 v64, v60, 16, 1
	v_add3_u32 v60, v60, v64, s46
	v_add3_u32 v61, v61, v62, s46
	v_add3_u32 v53, v56, v53, s46
	v_add3_u32 v3, v57, v3, s46
	v_bfe_u32 v56, v58, 16, 1
	v_bfe_u32 v57, v59, 16, 1
	v_bfe_u32 v62, v78, 16, 1
	v_bfe_u32 v64, v79, 16, 1
	v_add3_u32 v64, v79, v64, s46
	v_add3_u32 v62, v78, v62, s46
	v_add3_u32 v57, v59, v57, s46
	v_add3_u32 v56, v58, v56, s46
	v_lshrrev_b32_e32 v56, 16, v56
	v_lshrrev_b32_e32 v57, 16, v57
	v_lshrrev_b32_e32 v58, 16, v62
	v_lshrrev_b32_e32 v59, 16, v64
	v_and_or_b32 v59, v3, s47, v59
	v_and_or_b32 v58, v53, s47, v58
	v_and_or_b32 v57, v61, s47, v57
	v_and_or_b32 v56, v60, s47, v56
	v_lshl_add_u64 v[60:61], v[48:49], 0, v[4:5]
	global_store_dwordx4 v[60:61], v[56:59], off
	v_mov_b32_e32 v64, v77
	v_mov_b32_e32 v74, v71
	s_waitcnt vmcnt(7)
	v_pk_mul_f32 v[58:59], v[52:53], v[66:67] op_sel_hi:[0,1]
	v_pk_mul_f32 v[56:57], v[52:53], v[64:65] op_sel_hi:[0,1]
	v_pk_mul_f32 v[60:61], v[52:53], v[72:73] op_sel_hi:[0,1]
	v_pk_mul_f32 v[52:53], v[52:53], v[74:75] op_sel_hi:[0,1]
	v_bfe_u32 v62, v59, 16, 1
	v_bfe_u32 v3, v53, 16, 1
	v_bfe_u32 v63, v58, 16, 1
	v_add3_u32 v62, v59, v62, s46
	v_bfe_u32 v59, v61, 16, 1
	v_bfe_u32 v4, v52, 16, 1
	v_add3_u32 v63, v58, v63, s46
	v_add3_u32 v3, v53, v3, s46
	v_bfe_u32 v53, v57, 16, 1
	v_bfe_u32 v58, v60, 16, 1
	v_add3_u32 v59, v61, v59, s46
	v_add3_u32 v4, v52, v4, s46
	v_bfe_u32 v52, v56, 16, 1
	v_add3_u32 v58, v60, v58, s46
	v_add3_u32 v53, v57, v53, s46
	v_lshrrev_b32_e32 v57, 16, v59
	v_add3_u32 v52, v56, v52, s46
	v_lshrrev_b32_e32 v56, 16, v58
	v_and_or_b32 v59, v3, s47, v57
	v_or_b32_e32 v3, v51, v100
	v_lshrrev_b32_e32 v52, 16, v52
	v_lshrrev_b32_e32 v53, 16, v53
	v_and_or_b32 v58, v4, s47, v56
	v_lshlrev_b32_e32 v4, 11, v3
	v_and_or_b32 v57, v62, s47, v53
	v_and_or_b32 v56, v63, s47, v52
	v_lshl_add_u64 v[52:53], v[54:55], 0, v[4:5]
	global_store_dwordx4 v[52:53], v[56:59], off
	s_waitcnt vmcnt(7)
	v_pk_mul_f32 v[52:53], v[50:51], v[64:65] op_sel_hi:[0,1]
	v_pk_mul_f32 v[54:55], v[50:51], v[66:67] op_sel_hi:[0,1]
	v_pk_mul_f32 v[56:57], v[50:51], v[72:73] op_sel_hi:[0,1]
	v_pk_mul_f32 v[50:51], v[50:51], v[74:75] op_sel_hi:[0,1]
	v_bfe_u32 v3, v51, 16, 1
	v_bfe_u32 v58, v50, 16, 1
	v_bfe_u32 v59, v55, 16, 1
	v_bfe_u32 v60, v54, 16, 1
	v_add3_u32 v54, v54, v60, s46
	v_add3_u32 v55, v55, v59, s46
	v_add3_u32 v50, v50, v58, s46
	v_add3_u32 v3, v51, v3, s46
	v_bfe_u32 v51, v52, 16, 1
	v_bfe_u32 v58, v53, 16, 1
	v_bfe_u32 v59, v56, 16, 1
	v_bfe_u32 v60, v57, 16, 1
	v_add3_u32 v57, v57, v60, s46
	v_add3_u32 v56, v56, v59, s46
	v_add3_u32 v53, v53, v58, s46
	v_add3_u32 v51, v52, v51, s46
	v_lshrrev_b32_e32 v58, 16, v51
	v_lshrrev_b32_e32 v51, 16, v53
	v_lshrrev_b32_e32 v52, 16, v56
	v_lshrrev_b32_e32 v53, 16, v57
	v_and_or_b32 v53, v3, s47, v53
	v_and_or_b32 v52, v50, s47, v52
	v_and_or_b32 v51, v55, s47, v51
	v_and_or_b32 v50, v54, s47, v58
	v_lshl_add_u64 v[48:49], v[48:49], 0, v[4:5]
	global_store_dwordx4 v[48:49], v[50:53], off
	s_waitcnt lgkmcnt(0)

.LBB0_925:
	s_lshl_b32 s69, s64, 1
	s_lshl_b32 s70, s65, 1
	v_or_b32_e32 v56, s69, v1
	v_or_b32_e32 v57, s70, v0
	v_add_lshl_u32 v4, v56, v3, 10
	v_add_lshl_u32 v53, v57, v48, 10
	v_or_b32_e32 v52, v49, v4
	v_or_b32_e32 v4, v50, v53
	v_lshl_add_u64 v[54:55], v[4:5], 2, s[6:7]
	v_mov_b32_e32 v53, v5
	v_lshl_add_u64 v[52:53], v[52:53], 2, s[6:7]
	global_load_dword v126, v[54:55], off nt
	global_load_dword v127, v[52:53], off nt
	v_mad_u64_u32 v[52:53], s[72:73], v57, s40, v[2:3]
	v_mad_u64_u32 v[54:55], s[72:73], v56, s40, v[2:3]
	s_add_i32 s71, s69, 4
	s_add_i32 s72, s70, 4
	v_or_b32_e32 v56, s71, v1
	v_or_b32_e32 v57, s72, v0
	v_add_lshl_u32 v53, v57, v48, 10
	s_add_i32 s71, s69, 8
	s_add_i32 s65, s65, 16
	s_add_i32 s64, s64, 16
	s_add_i32 s68, s68, -16
	v_mov_b32_e32 v142, v52
	v_mov_b32_e32 v143, v54
	v_add_lshl_u32 v4, v56, v3, 10
	v_or_b32_e32 v52, v49, v4
	v_or_b32_e32 v4, v50, v53
	v_lshl_add_u64 v[54:55], v[4:5], 2, s[6:7]
	v_mov_b32_e32 v53, v5
	v_lshl_add_u64 v[52:53], v[52:53], 2, s[6:7]
	global_load_dword v128, v[54:55], off nt
	global_load_dword v129, v[52:53], off nt
	v_mad_u64_u32 v[52:53], s[72:73], v57, s40, v[2:3]
	v_mad_u64_u32 v[54:55], s[72:73], v56, s40, v[2:3]
	s_add_i32 s72, s70, 8
	v_or_b32_e32 v56, s71, v1
	v_or_b32_e32 v57, s72, v0
	v_add_lshl_u32 v53, v57, v48, 10
	s_add_i32 s71, s69, 12
	v_mov_b32_e32 v144, v52
	v_mov_b32_e32 v145, v54
	v_add_lshl_u32 v4, v56, v3, 10
	v_or_b32_e32 v52, v49, v4
	v_or_b32_e32 v4, v50, v53
	v_lshl_add_u64 v[54:55], v[4:5], 2, s[6:7]
	v_mov_b32_e32 v53, v5
	v_lshl_add_u64 v[52:53], v[52:53], 2, s[6:7]
	global_load_dword v130, v[54:55], off nt
	global_load_dword v131, v[52:53], off nt
	v_mad_u64_u32 v[52:53], s[72:73], v57, s40, v[2:3]
	v_mad_u64_u32 v[54:55], s[72:73], v56, s40, v[2:3]
	s_add_i32 s72, s70, 12
	v_or_b32_e32 v56, s71, v1
	v_or_b32_e32 v57, s72, v0
	v_add_lshl_u32 v53, v57, v48, 10
	s_add_i32 s71, s69, 16
	v_mov_b32_e32 v146, v52
	v_mov_b32_e32 v147, v54
	v_add_lshl_u32 v4, v56, v3, 10
	v_or_b32_e32 v52, v49, v4
	v_or_b32_e32 v4, v50, v53
	v_lshl_add_u64 v[54:55], v[4:5], 2, s[6:7]
	v_mov_b32_e32 v53, v5
	v_lshl_add_u64 v[52:53], v[52:53], 2, s[6:7]
	global_load_dword v132, v[54:55], off nt
	global_load_dword v133, v[52:53], off nt
	v_mad_u64_u32 v[52:53], s[72:73], v57, s40, v[2:3]
	v_mad_u64_u32 v[54:55], s[72:73], v56, s40, v[2:3]
	s_add_i32 s72, s70, 16
	v_or_b32_e32 v56, s71, v1
	v_or_b32_e32 v57, s72, v0
	v_add_lshl_u32 v53, v57, v48, 10
	s_add_i32 s71, s69, 20
	v_mov_b32_e32 v148, v52
	v_mov_b32_e32 v149, v54
	v_add_lshl_u32 v4, v56, v3, 10
	v_or_b32_e32 v52, v49, v4
	v_or_b32_e32 v4, v50, v53
	v_lshl_add_u64 v[54:55], v[4:5], 2, s[6:7]
	v_mov_b32_e32 v53, v5
	v_lshl_add_u64 v[52:53], v[52:53], 2, s[6:7]
	global_load_dword v134, v[54:55], off nt
	global_load_dword v135, v[52:53], off nt
	v_mad_u64_u32 v[52:53], s[72:73], v57, s40, v[2:3]
	v_mad_u64_u32 v[54:55], s[72:73], v56, s40, v[2:3]
	s_add_i32 s72, s70, 20
	v_or_b32_e32 v56, s71, v1
	v_or_b32_e32 v57, s72, v0
	v_add_lshl_u32 v53, v57, v48, 10
	s_add_i32 s71, s69, 24
	s_add_i32 s69, s69, 28
	v_mov_b32_e32 v150, v52
	v_mov_b32_e32 v151, v54
	v_add_lshl_u32 v4, v56, v3, 10
	v_or_b32_e32 v52, v49, v4
	v_or_b32_e32 v4, v50, v53
	v_lshl_add_u64 v[54:55], v[4:5], 2, s[6:7]
	v_mov_b32_e32 v53, v5
	v_lshl_add_u64 v[52:53], v[52:53], 2, s[6:7]
	global_load_dword v136, v[54:55], off nt
	global_load_dword v137, v[52:53], off nt
	v_mad_u64_u32 v[52:53], s[72:73], v57, s40, v[2:3]
	v_mad_u64_u32 v[54:55], s[72:73], v56, s40, v[2:3]
	s_add_i32 s72, s70, 24
	v_or_b32_e32 v56, s71, v1
	v_or_b32_e32 v57, s72, v0
	v_add_lshl_u32 v53, v57, v48, 10
	s_add_i32 s70, s70, 28
	s_cmp_lg_u32 s68, 0
	v_mov_b32_e32 v152, v52
	v_mov_b32_e32 v153, v54
	v_add_lshl_u32 v4, v56, v3, 10
	v_or_b32_e32 v52, v49, v4
	v_or_b32_e32 v4, v50, v53
	v_lshl_add_u64 v[54:55], v[4:5], 2, s[6:7]
	v_mov_b32_e32 v53, v5
	v_lshl_add_u64 v[52:53], v[52:53], 2, s[6:7]
	global_load_dword v138, v[54:55], off nt
	global_load_dword v139, v[52:53], off nt
	v_mad_u64_u32 v[52:53], s[72:73], v57, s40, v[2:3]
	v_mad_u64_u32 v[54:55], s[72:73], v56, s40, v[2:3]
	v_or_b32_e32 v56, s69, v1
	v_or_b32_e32 v57, s70, v0
	v_mov_b32_e32 v55, v5
	v_mov_b32_e32 v154, v52
	v_mov_b32_e32 v155, v54
	v_add_lshl_u32 v4, v56, v3, 10
	v_add_lshl_u32 v52, v57, v48, 10
	v_or_b32_e32 v54, v49, v4
	v_or_b32_e32 v4, v50, v52
	v_lshl_add_u64 v[52:53], v[4:5], 2, s[6:7]
	v_lshl_add_u64 v[54:55], v[54:55], 2, s[6:7]
	global_load_dword v140, v[52:53], off nt
	global_load_dword v141, v[54:55], off nt
	v_mad_u64_u32 v[52:53], s[70:71], v57, s40, v[2:3]
	v_mad_u64_u32 v[54:55], s[70:71], v56, s40, v[2:3]
	v_mov_b32_e32 v156, v52
	v_mov_b32_e32 v157, v54
	s_waitcnt vmcnt(15)
	ds_write_b32 v142, v126
	s_waitcnt vmcnt(14)
	ds_write_b32 v143, v127
	s_waitcnt vmcnt(13)
	ds_write_b32 v144, v128
	s_waitcnt vmcnt(12)
	ds_write_b32 v145, v129
	s_waitcnt vmcnt(11)
	ds_write_b32 v146, v130
	s_waitcnt vmcnt(10)
	ds_write_b32 v147, v131
	s_waitcnt vmcnt(9)
	ds_write_b32 v148, v132
	s_waitcnt vmcnt(8)
	ds_write_b32 v149, v133
	s_waitcnt vmcnt(7)
	ds_write_b32 v150, v134
	s_waitcnt vmcnt(6)
	ds_write_b32 v151, v135
	s_waitcnt vmcnt(5)
	ds_write_b32 v152, v136
	s_waitcnt vmcnt(4)
	ds_write_b32 v153, v137
	s_waitcnt vmcnt(3)
	ds_write_b32 v154, v138
	s_waitcnt vmcnt(2)
	ds_write_b32 v155, v139
	s_waitcnt vmcnt(1)
	ds_write_b32 v156, v140
	s_waitcnt vmcnt(0)
	ds_write_b32 v157, v141
	s_cbranch_scc1 .LBB0_925
	s_waitcnt lgkmcnt(0)
	ds_read2_b32 v[56:57], v97 offset0:33 offset1:41
	ds_read2_b32 v[58:59], v97 offset0:66 offset1:74
	ds_read2_b32 v[60:61], v97 offset0:99 offset1:107
	ds_read2_b32 v[62:63], v97 offset1:8
	ds_read2_b32 v[64:65], v97 offset0:132 offset1:140
	ds_read2_b32 v[66:67], v97 offset0:165 offset1:173
	ds_read2_b32 v[68:69], v97 offset0:198 offset1:206
	ds_read2_b32 v[70:71], v97 offset0:231 offset1:239
	v_lshlrev_b32_e32 v4, 1, v48
	s_waitcnt lgkmcnt(4)
	v_bfe_u32 v3, v62, 16, 1
	v_lshl_add_u64 v[48:49], v[10:11], 0, v[4:5]
	v_add3_u32 v3, v62, v3, s46
	v_bfe_u32 v4, v56, 16, 1
	v_lshrrev_b32_e32 v3, 16, v3
	v_add3_u32 v4, v56, v4, s46
	v_and_or_b32 v52, v4, s47, v3
	v_bfe_u32 v3, v58, 16, 1
	v_add3_u32 v3, v58, v3, s46
	v_bfe_u32 v4, v60, 16, 1
	v_lshrrev_b32_e32 v3, 16, v3
	v_add3_u32 v4, v60, v4, s46
	v_and_or_b32 v53, v4, s47, v3
	s_waitcnt lgkmcnt(3)
	v_bfe_u32 v3, v64, 16, 1
	v_add3_u32 v3, v64, v3, s46
	s_waitcnt lgkmcnt(2)
	v_bfe_u32 v4, v66, 16, 1
	v_lshrrev_b32_e32 v3, 16, v3
	v_add3_u32 v4, v66, v4, s46
	v_and_or_b32 v54, v4, s47, v3
	s_waitcnt lgkmcnt(1)
	v_bfe_u32 v3, v68, 16, 1
	v_add3_u32 v3, v68, v3, s46
	s_waitcnt lgkmcnt(0)
	v_bfe_u32 v4, v70, 16, 1
	v_lshrrev_b32_e32 v3, 16, v3
	v_add3_u32 v4, v70, v4, s46
	v_and_or_b32 v55, v4, s47, v3
	v_or_b32_e32 v3, v51, v96
	v_lshlrev_b32_e32 v4, 9, v3
	v_bfe_u32 v3, v63, 16, 1
	v_lshl_add_u64 v[72:73], v[48:49], 0, v[4:5]
	v_add3_u32 v3, v63, v3, s46
	v_bfe_u32 v4, v57, 16, 1
	v_lshrrev_b32_e32 v3, 16, v3
	v_add3_u32 v4, v57, v4, s46
	global_store_dwordx4 v[72:73], v[52:55], off
	s_nop 1
	v_and_or_b32 v52, v4, s47, v3
	v_bfe_u32 v3, v59, 16, 1
	v_add3_u32 v3, v59, v3, s46
	v_bfe_u32 v4, v61, 16, 1
	v_lshrrev_b32_e32 v3, 16, v3
	v_add3_u32 v4, v61, v4, s46
	v_and_or_b32 v53, v4, s47, v3
	v_bfe_u32 v3, v65, 16, 1
	v_add3_u32 v3, v65, v3, s46
	v_bfe_u32 v4, v67, 16, 1
	v_lshrrev_b32_e32 v3, 16, v3
	v_add3_u32 v4, v67, v4, s46
	v_and_or_b32 v54, v4, s47, v3
	v_bfe_u32 v3, v69, 16, 1
	v_add3_u32 v3, v69, v3, s46
	v_bfe_u32 v4, v71, 16, 1
	v_lshrrev_b32_e32 v3, 16, v3
	v_add3_u32 v4, v71, v4, s46
	v_and_or_b32 v55, v4, s47, v3
	v_or_b32_e32 v3, v51, v98
	v_lshlrev_b32_e32 v4, 9, v3
	v_lshl_add_u64 v[56:57], v[48:49], 0, v[4:5]
	global_store_dwordx4 v[56:57], v[52:55], off
	ds_read2_b32 v[56:57], v97 offset0:49 offset1:57
	ds_read2_b32 v[58:59], v97 offset0:82 offset1:90
	ds_read2_b32 v[60:61], v97 offset0:115 offset1:123
	ds_read2_b32 v[62:63], v97 offset0:16 offset1:24
	ds_read2_b32 v[64:65], v97 offset0:148 offset1:156
	ds_read2_b32 v[66:67], v97 offset0:181 offset1:189
	ds_read2_b32 v[68:69], v97 offset0:214 offset1:222
	ds_read2_b32 v[70:71], v97 offset0:247 offset1:255
	s_waitcnt lgkmcnt(4)
	v_bfe_u32 v3, v62, 16, 1
	v_add3_u32 v3, v62, v3, s46
	v_bfe_u32 v4, v56, 16, 1
	v_lshrrev_b32_e32 v3, 16, v3
	v_add3_u32 v4, v56, v4, s46
	v_and_or_b32 v52, v4, s47, v3
	v_bfe_u32 v3, v58, 16, 1
	v_add3_u32 v3, v58, v3, s46
	v_bfe_u32 v4, v60, 16, 1
	v_lshrrev_b32_e32 v3, 16, v3
	v_add3_u32 v4, v60, v4, s46
	v_and_or_b32 v53, v4, s47, v3
	s_waitcnt lgkmcnt(3)
	v_bfe_u32 v3, v64, 16, 1
	v_add3_u32 v3, v64, v3, s46
	s_waitcnt lgkmcnt(2)
	v_bfe_u32 v4, v66, 16, 1
	v_lshrrev_b32_e32 v3, 16, v3
	v_add3_u32 v4, v66, v4, s46
	v_and_or_b32 v54, v4, s47, v3
	s_waitcnt lgkmcnt(1)
	v_bfe_u32 v3, v68, 16, 1
	v_add3_u32 v3, v68, v3, s46
	s_waitcnt lgkmcnt(0)
	v_bfe_u32 v4, v70, 16, 1
	v_lshrrev_b32_e32 v3, 16, v3
	v_add3_u32 v4, v70, v4, s46
	v_and_or_b32 v55, v4, s47, v3
	v_or_b32_e32 v3, v51, v99
	v_lshlrev_b32_e32 v4, 9, v3
	v_bfe_u32 v3, v63, 16, 1
	v_lshl_add_u64 v[72:73], v[48:49], 0, v[4:5]
	v_add3_u32 v3, v63, v3, s46
	v_bfe_u32 v4, v57, 16, 1
	v_lshrrev_b32_e32 v3, 16, v3
	v_add3_u32 v4, v57, v4, s46
	global_store_dwordx4 v[72:73], v[52:55], off
	s_nop 1
	v_and_or_b32 v52, v4, s47, v3
	v_bfe_u32 v3, v59, 16, 1
	v_add3_u32 v3, v59, v3, s46
	v_bfe_u32 v4, v61, 16, 1
	v_lshrrev_b32_e32 v3, 16, v3
	v_add3_u32 v4, v61, v4, s46
	v_and_or_b32 v53, v4, s47, v3
	v_bfe_u32 v3, v65, 16, 1
	v_add3_u32 v3, v65, v3, s46
	v_bfe_u32 v4, v67, 16, 1
	v_lshrrev_b32_e32 v3, 16, v3
	v_add3_u32 v4, v67, v4, s46
	v_and_or_b32 v54, v4, s47, v3
	v_bfe_u32 v3, v69, 16, 1
	v_add3_u32 v3, v69, v3, s46
	v_bfe_u32 v4, v71, 16, 1
	v_lshrrev_b32_e32 v3, 16, v3
	v_add3_u32 v4, v71, v4, s46
	v_and_or_b32 v55, v4, s47, v3
	v_or_b32_e32 v3, v51, v100
	v_lshlrev_b32_e32 v4, 9, v3
	v_lshl_add_u64 v[48:49], v[48:49], 0, v[4:5]
	global_store_dwordx4 v[48:49], v[52:55], off
	s_waitcnt lgkmcnt(0)

.LBB0_930:
	s_lshl_b32 s65, s36, 1
	s_lshl_b32 s68, s37, 1
	v_or_b32_e32 v56, s65, v1
	v_or_b32_e32 v57, s68, v0
	v_add_lshl_u32 v4, v56, v3, 10
	v_add_lshl_u32 v53, v57, v48, 10
	v_or_b32_e32 v52, v49, v4
	v_or_b32_e32 v4, v50, v53
	v_lshl_add_u64 v[54:55], v[4:5], 2, s[4:5]
	v_mov_b32_e32 v53, v5
	v_lshl_add_u64 v[52:53], v[52:53], 2, s[4:5]
	global_load_dword v126, v[54:55], off nt
	global_load_dword v127, v[52:53], off nt
	v_mad_u64_u32 v[52:53], s[70:71], v57, s40, v[2:3]
	v_mad_u64_u32 v[54:55], s[70:71], v56, s40, v[2:3]
	s_add_i32 s69, s65, 4
	s_add_i32 s70, s68, 4
	v_or_b32_e32 v56, s69, v1
	v_or_b32_e32 v57, s70, v0
	v_add_lshl_u32 v53, v57, v48, 10
	s_add_i32 s69, s65, 8
	s_add_i32 s37, s37, 16
	s_add_i32 s36, s36, 16
	s_add_i32 s64, s64, -16
	v_mov_b32_e32 v142, v52
	v_mov_b32_e32 v143, v54
	v_add_lshl_u32 v4, v56, v3, 10
	v_or_b32_e32 v52, v49, v4
	v_or_b32_e32 v4, v50, v53
	v_lshl_add_u64 v[54:55], v[4:5], 2, s[4:5]
	v_mov_b32_e32 v53, v5
	v_lshl_add_u64 v[52:53], v[52:53], 2, s[4:5]
	global_load_dword v128, v[54:55], off nt
	global_load_dword v129, v[52:53], off nt
	v_mad_u64_u32 v[52:53], s[70:71], v57, s40, v[2:3]
	v_mad_u64_u32 v[54:55], s[70:71], v56, s40, v[2:3]
	s_add_i32 s70, s68, 8
	v_or_b32_e32 v56, s69, v1
	v_or_b32_e32 v57, s70, v0
	v_add_lshl_u32 v53, v57, v48, 10
	s_add_i32 s69, s65, 12
	v_mov_b32_e32 v144, v52
	v_mov_b32_e32 v145, v54
	v_add_lshl_u32 v4, v56, v3, 10
	v_or_b32_e32 v52, v49, v4
	v_or_b32_e32 v4, v50, v53
	v_lshl_add_u64 v[54:55], v[4:5], 2, s[4:5]
	v_mov_b32_e32 v53, v5
	v_lshl_add_u64 v[52:53], v[52:53], 2, s[4:5]
	global_load_dword v130, v[54:55], off nt
	global_load_dword v131, v[52:53], off nt
	v_mad_u64_u32 v[52:53], s[70:71], v57, s40, v[2:3]
	v_mad_u64_u32 v[54:55], s[70:71], v56, s40, v[2:3]
	s_add_i32 s70, s68, 12
	v_or_b32_e32 v56, s69, v1
	v_or_b32_e32 v57, s70, v0
	v_add_lshl_u32 v53, v57, v48, 10
	s_add_i32 s69, s65, 16
	v_mov_b32_e32 v146, v52
	v_mov_b32_e32 v147, v54
	v_add_lshl_u32 v4, v56, v3, 10
	v_or_b32_e32 v52, v49, v4
	v_or_b32_e32 v4, v50, v53
	v_lshl_add_u64 v[54:55], v[4:5], 2, s[4:5]
	v_mov_b32_e32 v53, v5
	v_lshl_add_u64 v[52:53], v[52:53], 2, s[4:5]
	global_load_dword v132, v[54:55], off nt
	global_load_dword v133, v[52:53], off nt
	v_mad_u64_u32 v[52:53], s[70:71], v57, s40, v[2:3]
	v_mad_u64_u32 v[54:55], s[70:71], v56, s40, v[2:3]
	s_add_i32 s70, s68, 16
	v_or_b32_e32 v56, s69, v1
	v_or_b32_e32 v57, s70, v0
	v_add_lshl_u32 v53, v57, v48, 10
	s_add_i32 s69, s65, 20
	v_mov_b32_e32 v148, v52
	v_mov_b32_e32 v149, v54
	v_add_lshl_u32 v4, v56, v3, 10
	v_or_b32_e32 v52, v49, v4
	v_or_b32_e32 v4, v50, v53
	v_lshl_add_u64 v[54:55], v[4:5], 2, s[4:5]
	v_mov_b32_e32 v53, v5
	v_lshl_add_u64 v[52:53], v[52:53], 2, s[4:5]
	global_load_dword v134, v[54:55], off nt
	global_load_dword v135, v[52:53], off nt
	v_mad_u64_u32 v[52:53], s[70:71], v57, s40, v[2:3]
	v_mad_u64_u32 v[54:55], s[70:71], v56, s40, v[2:3]
	s_add_i32 s70, s68, 20
	v_or_b32_e32 v56, s69, v1
	v_or_b32_e32 v57, s70, v0
	v_add_lshl_u32 v53, v57, v48, 10
	s_add_i32 s69, s65, 24
	s_add_i32 s65, s65, 28
	v_mov_b32_e32 v150, v52
	v_mov_b32_e32 v151, v54
	v_add_lshl_u32 v4, v56, v3, 10
	v_or_b32_e32 v52, v49, v4
	v_or_b32_e32 v4, v50, v53
	v_lshl_add_u64 v[54:55], v[4:5], 2, s[4:5]
	v_mov_b32_e32 v53, v5
	v_lshl_add_u64 v[52:53], v[52:53], 2, s[4:5]
	global_load_dword v136, v[54:55], off nt
	global_load_dword v137, v[52:53], off nt
	v_mad_u64_u32 v[52:53], s[70:71], v57, s40, v[2:3]
	v_mad_u64_u32 v[54:55], s[70:71], v56, s40, v[2:3]
	s_add_i32 s70, s68, 24
	v_or_b32_e32 v56, s69, v1
	v_or_b32_e32 v57, s70, v0
	v_add_lshl_u32 v53, v57, v48, 10
	s_add_i32 s68, s68, 28
	s_cmp_lg_u32 s64, 0
	v_mov_b32_e32 v152, v52
	v_mov_b32_e32 v153, v54
	v_add_lshl_u32 v4, v56, v3, 10
	v_or_b32_e32 v52, v49, v4
	v_or_b32_e32 v4, v50, v53
	v_lshl_add_u64 v[54:55], v[4:5], 2, s[4:5]
	v_mov_b32_e32 v53, v5
	v_lshl_add_u64 v[52:53], v[52:53], 2, s[4:5]
	global_load_dword v138, v[54:55], off nt
	global_load_dword v139, v[52:53], off nt
	v_mad_u64_u32 v[52:53], s[70:71], v57, s40, v[2:3]
	v_mad_u64_u32 v[54:55], s[70:71], v56, s40, v[2:3]
	v_or_b32_e32 v56, s65, v1
	v_or_b32_e32 v57, s68, v0
	v_mov_b32_e32 v55, v5
	v_mov_b32_e32 v154, v52
	v_mov_b32_e32 v155, v54
	v_add_lshl_u32 v4, v56, v3, 10
	v_add_lshl_u32 v52, v57, v48, 10
	v_or_b32_e32 v54, v49, v4
	v_or_b32_e32 v4, v50, v52
	v_lshl_add_u64 v[52:53], v[4:5], 2, s[4:5]
	v_lshl_add_u64 v[54:55], v[54:55], 2, s[4:5]
	global_load_dword v140, v[52:53], off nt
	global_load_dword v141, v[54:55], off nt
	v_mad_u64_u32 v[52:53], s[68:69], v57, s40, v[2:3]
	v_mad_u64_u32 v[54:55], s[68:69], v56, s40, v[2:3]
	v_mov_b32_e32 v156, v52
	v_mov_b32_e32 v157, v54
	s_waitcnt vmcnt(15)
	ds_write_b32 v142, v126
	s_waitcnt vmcnt(14)
	ds_write_b32 v143, v127
	s_waitcnt vmcnt(13)
	ds_write_b32 v144, v128
	s_waitcnt vmcnt(12)
	ds_write_b32 v145, v129
	s_waitcnt vmcnt(11)
	ds_write_b32 v146, v130
	s_waitcnt vmcnt(10)
	ds_write_b32 v147, v131
	s_waitcnt vmcnt(9)
	ds_write_b32 v148, v132
	s_waitcnt vmcnt(8)
	ds_write_b32 v149, v133
	s_waitcnt vmcnt(7)
	ds_write_b32 v150, v134
	s_waitcnt vmcnt(6)
	ds_write_b32 v151, v135
	s_waitcnt vmcnt(5)
	ds_write_b32 v152, v136
	s_waitcnt vmcnt(4)
	ds_write_b32 v153, v137
	s_waitcnt vmcnt(3)
	ds_write_b32 v154, v138
	s_waitcnt vmcnt(2)
	ds_write_b32 v155, v139
	s_waitcnt vmcnt(1)
	ds_write_b32 v156, v140
	s_waitcnt vmcnt(0)
	ds_write_b32 v157, v141
	s_cbranch_scc1 .LBB0_930
	s_waitcnt lgkmcnt(0)
	ds_read2_b32 v[56:57], v97 offset0:33 offset1:41
	ds_read2_b32 v[58:59], v97 offset0:66 offset1:74
	ds_read2_b32 v[60:61], v97 offset0:99 offset1:107
	ds_read2_b32 v[62:63], v97 offset1:8
	ds_read2_b32 v[64:65], v97 offset0:132 offset1:140
	ds_read2_b32 v[66:67], v97 offset0:165 offset1:173
	ds_read2_b32 v[68:69], v97 offset0:198 offset1:206
	ds_read2_b32 v[70:71], v97 offset0:231 offset1:239
	v_lshlrev_b32_e32 v4, 1, v48
	s_waitcnt lgkmcnt(4)
	v_bfe_u32 v3, v62, 16, 1
	v_lshl_add_u64 v[48:49], v[12:13], 0, v[4:5]
	v_add3_u32 v3, v62, v3, s46
	v_bfe_u32 v4, v56, 16, 1
	v_lshrrev_b32_e32 v3, 16, v3
	v_add3_u32 v4, v56, v4, s46
	v_and_or_b32 v52, v4, s47, v3
	v_bfe_u32 v3, v58, 16, 1
	v_add3_u32 v3, v58, v3, s46
	v_bfe_u32 v4, v60, 16, 1
	v_lshrrev_b32_e32 v3, 16, v3
	v_add3_u32 v4, v60, v4, s46
	v_and_or_b32 v53, v4, s47, v3
	s_waitcnt lgkmcnt(3)
	v_bfe_u32 v3, v64, 16, 1
	v_add3_u32 v3, v64, v3, s46
	s_waitcnt lgkmcnt(2)
	v_bfe_u32 v4, v66, 16, 1
	v_lshrrev_b32_e32 v3, 16, v3
	v_add3_u32 v4, v66, v4, s46
	v_and_or_b32 v54, v4, s47, v3
	s_waitcnt lgkmcnt(1)
	v_bfe_u32 v3, v68, 16, 1
	v_add3_u32 v3, v68, v3, s46
	s_waitcnt lgkmcnt(0)
	v_bfe_u32 v4, v70, 16, 1
	v_lshrrev_b32_e32 v3, 16, v3
	v_add3_u32 v4, v70, v4, s46
	v_and_or_b32 v55, v4, s47, v3
	v_or_b32_e32 v3, v51, v96
	v_lshlrev_b32_e32 v4, 10, v3
	v_bfe_u32 v3, v63, 16, 1
	v_lshl_add_u64 v[72:73], v[48:49], 0, v[4:5]
	v_add3_u32 v3, v63, v3, s46
	v_bfe_u32 v4, v57, 16, 1
	v_lshrrev_b32_e32 v3, 16, v3
	v_add3_u32 v4, v57, v4, s46
	global_store_dwordx4 v[72:73], v[52:55], off
	s_nop 1
	v_and_or_b32 v52, v4, s47, v3
	v_bfe_u32 v3, v59, 16, 1
	v_add3_u32 v3, v59, v3, s46
	v_bfe_u32 v4, v61, 16, 1
	v_lshrrev_b32_e32 v3, 16, v3
	v_add3_u32 v4, v61, v4, s46
	v_and_or_b32 v53, v4, s47, v3
	v_bfe_u32 v3, v65, 16, 1
	v_add3_u32 v3, v65, v3, s46
	v_bfe_u32 v4, v67, 16, 1
	v_lshrrev_b32_e32 v3, 16, v3
	v_add3_u32 v4, v67, v4, s46
	v_and_or_b32 v54, v4, s47, v3
	v_bfe_u32 v3, v69, 16, 1
	v_add3_u32 v3, v69, v3, s46
	v_bfe_u32 v4, v71, 16, 1
	v_lshrrev_b32_e32 v3, 16, v3
	v_add3_u32 v4, v71, v4, s46
	v_and_or_b32 v55, v4, s47, v3
	v_or_b32_e32 v3, v51, v98
	v_lshlrev_b32_e32 v4, 10, v3
	v_lshl_add_u64 v[56:57], v[48:49], 0, v[4:5]
	global_store_dwordx4 v[56:57], v[52:55], off
	ds_read2_b32 v[56:57], v97 offset0:49 offset1:57
	ds_read2_b32 v[58:59], v97 offset0:82 offset1:90
	ds_read2_b32 v[60:61], v97 offset0:115 offset1:123
	ds_read2_b32 v[62:63], v97 offset0:16 offset1:24
	ds_read2_b32 v[64:65], v97 offset0:148 offset1:156
	ds_read2_b32 v[66:67], v97 offset0:181 offset1:189
	ds_read2_b32 v[68:69], v97 offset0:214 offset1:222
	ds_read2_b32 v[70:71], v97 offset0:247 offset1:255
	s_waitcnt lgkmcnt(4)
	v_bfe_u32 v3, v62, 16, 1
	v_add3_u32 v3, v62, v3, s46
	v_bfe_u32 v4, v56, 16, 1
	v_lshrrev_b32_e32 v3, 16, v3
	v_add3_u32 v4, v56, v4, s46
	v_and_or_b32 v52, v4, s47, v3
	v_bfe_u32 v3, v58, 16, 1
	v_add3_u32 v3, v58, v3, s46
	v_bfe_u32 v4, v60, 16, 1
	v_lshrrev_b32_e32 v3, 16, v3
	v_add3_u32 v4, v60, v4, s46
	v_and_or_b32 v53, v4, s47, v3
	s_waitcnt lgkmcnt(3)
	v_bfe_u32 v3, v64, 16, 1
	v_add3_u32 v3, v64, v3, s46
	s_waitcnt lgkmcnt(2)
	v_bfe_u32 v4, v66, 16, 1
	v_lshrrev_b32_e32 v3, 16, v3
	v_add3_u32 v4, v66, v4, s46
	v_and_or_b32 v54, v4, s47, v3
	s_waitcnt lgkmcnt(1)
	v_bfe_u32 v3, v68, 16, 1
	v_add3_u32 v3, v68, v3, s46
	s_waitcnt lgkmcnt(0)
	v_bfe_u32 v4, v70, 16, 1
	v_lshrrev_b32_e32 v3, 16, v3
	v_add3_u32 v4, v70, v4, s46
	v_and_or_b32 v55, v4, s47, v3
	v_or_b32_e32 v3, v51, v99
	v_lshlrev_b32_e32 v4, 10, v3
	v_bfe_u32 v3, v63, 16, 1
	v_lshl_add_u64 v[72:73], v[48:49], 0, v[4:5]
	v_add3_u32 v3, v63, v3, s46
	v_bfe_u32 v4, v57, 16, 1
	v_lshrrev_b32_e32 v3, 16, v3
	v_add3_u32 v4, v57, v4, s46
	global_store_dwordx4 v[72:73], v[52:55], off
	s_nop 1
	v_and_or_b32 v52, v4, s47, v3
	v_bfe_u32 v3, v59, 16, 1
	v_add3_u32 v3, v59, v3, s46
	v_bfe_u32 v4, v61, 16, 1
	v_lshrrev_b32_e32 v3, 16, v3
	v_add3_u32 v4, v61, v4, s46
	v_and_or_b32 v53, v4, s47, v3
	v_bfe_u32 v3, v65, 16, 1
	v_add3_u32 v3, v65, v3, s46
	v_bfe_u32 v4, v67, 16, 1
	v_lshrrev_b32_e32 v3, 16, v3
	v_add3_u32 v4, v67, v4, s46
	v_and_or_b32 v54, v4, s47, v3
	v_bfe_u32 v3, v69, 16, 1
	v_add3_u32 v3, v69, v3, s46
	v_bfe_u32 v4, v71, 16, 1
	v_lshrrev_b32_e32 v3, 16, v3
	v_add3_u32 v4, v71, v4, s46
	v_and_or_b32 v55, v4, s47, v3
	v_or_b32_e32 v3, v51, v100
	v_lshlrev_b32_e32 v4, 10, v3
	v_lshl_add_u64 v[48:49], v[48:49], 0, v[4:5]
	global_store_dwordx4 v[48:49], v[52:55], off
	s_waitcnt lgkmcnt(0)

.LBB0_935:
	s_lshl_b32 s64, s9, 1
	s_lshl_b32 s37, s8, 1
	v_or_b32_e32 v50, s64, v4
	v_or_b32_e32 v52, s37, v3
	v_mad_u64_u32 v[50:51], s[68:69], v50, s67, v[48:49]
	v_mad_u64_u32 v[52:53], s[68:69], v52, s67, v[48:49]
	global_load_dword v126, v[50:51], off nt
	global_load_dword v127, v[52:53], off nt
	v_or_b32_e32 v54, s37, v1
	v_or_b32_e32 v55, s64, v0
	v_mad_u64_u32 v[50:51], s[68:69], v55, s40, v[2:3]
	v_mad_u64_u32 v[52:53], s[68:69], v54, s40, v[2:3]
	s_add_i32 s68, s64, 4
	s_add_i32 s65, s37, 4
	v_or_b32_e32 v55, s68, v0
	v_or_b32_e32 v54, s65, v1
	s_add_i32 s9, s9, 16
	s_add_i32 s8, s8, 16
	s_add_i32 s36, s36, -16
	v_mov_b32_e32 v142, v50
	v_mov_b32_e32 v143, v52
	v_or_b32_e32 v50, s68, v4
	v_or_b32_e32 v52, s65, v3
	v_mad_u64_u32 v[50:51], s[68:69], v50, s67, v[48:49]
	v_mad_u64_u32 v[52:53], s[68:69], v52, s67, v[48:49]
	global_load_dword v128, v[50:51], off nt
	global_load_dword v129, v[52:53], off nt
	v_mad_u64_u32 v[50:51], s[68:69], v55, s40, v[2:3]
	v_mad_u64_u32 v[52:53], s[68:69], v54, s40, v[2:3]
	s_add_i32 s68, s64, 8
	s_add_i32 s65, s37, 8
	v_or_b32_e32 v55, s68, v0
	v_or_b32_e32 v54, s65, v1
	v_mov_b32_e32 v144, v50
	v_mov_b32_e32 v145, v52
	v_or_b32_e32 v50, s68, v4
	v_or_b32_e32 v52, s65, v3
	v_mad_u64_u32 v[50:51], s[68:69], v50, s67, v[48:49]
	v_mad_u64_u32 v[52:53], s[68:69], v52, s67, v[48:49]
	global_load_dword v130, v[50:51], off nt
	global_load_dword v131, v[52:53], off nt
	v_mad_u64_u32 v[50:51], s[68:69], v55, s40, v[2:3]
	v_mad_u64_u32 v[52:53], s[68:69], v54, s40, v[2:3]
	s_add_i32 s68, s64, 12
	s_add_i32 s65, s37, 12
	v_or_b32_e32 v55, s68, v0
	v_or_b32_e32 v54, s65, v1
	v_mov_b32_e32 v146, v50
	v_mov_b32_e32 v147, v52
	v_or_b32_e32 v50, s68, v4
	v_or_b32_e32 v52, s65, v3
	v_mad_u64_u32 v[50:51], s[68:69], v50, s67, v[48:49]
	v_mad_u64_u32 v[52:53], s[68:69], v52, s67, v[48:49]
	global_load_dword v132, v[50:51], off nt
	global_load_dword v133, v[52:53], off nt
	v_mad_u64_u32 v[50:51], s[68:69], v55, s40, v[2:3]
	v_mad_u64_u32 v[52:53], s[68:69], v54, s40, v[2:3]
	s_add_i32 s68, s64, 16
	s_add_i32 s65, s37, 16
	v_or_b32_e32 v55, s68, v0
	v_or_b32_e32 v54, s65, v1
	v_mov_b32_e32 v148, v50
	v_mov_b32_e32 v149, v52
	v_or_b32_e32 v50, s68, v4
	v_or_b32_e32 v52, s65, v3
	v_mad_u64_u32 v[50:51], s[68:69], v50, s67, v[48:49]
	v_mad_u64_u32 v[52:53], s[68:69], v52, s67, v[48:49]
	global_load_dword v134, v[50:51], off nt
	global_load_dword v135, v[52:53], off nt
	v_mad_u64_u32 v[50:51], s[68:69], v55, s40, v[2:3]
	v_mad_u64_u32 v[52:53], s[68:69], v54, s40, v[2:3]
	s_add_i32 s68, s64, 20
	s_add_i32 s65, s37, 20
	v_or_b32_e32 v55, s68, v0
	v_or_b32_e32 v54, s65, v1
	v_mov_b32_e32 v150, v50
	v_mov_b32_e32 v151, v52
	v_or_b32_e32 v50, s68, v4
	v_or_b32_e32 v52, s65, v3
	v_mad_u64_u32 v[50:51], s[68:69], v50, s67, v[48:49]
	v_mad_u64_u32 v[52:53], s[68:69], v52, s67, v[48:49]
	global_load_dword v136, v[50:51], off nt
	global_load_dword v137, v[52:53], off nt
	v_mad_u64_u32 v[50:51], s[68:69], v55, s40, v[2:3]
	v_mad_u64_u32 v[52:53], s[68:69], v54, s40, v[2:3]
	s_add_i32 s68, s64, 24
	s_add_i32 s65, s37, 24
	v_or_b32_e32 v55, s68, v0
	v_or_b32_e32 v54, s65, v1
	s_add_i32 s64, s64, 28
	s_add_i32 s37, s37, 28
	s_cmp_lg_u32 s36, 0
	v_mov_b32_e32 v152, v50
	v_mov_b32_e32 v153, v52
	v_or_b32_e32 v50, s68, v4
	v_or_b32_e32 v52, s65, v3
	v_mad_u64_u32 v[50:51], s[68:69], v50, s67, v[48:49]
	v_mad_u64_u32 v[52:53], s[68:69], v52, s67, v[48:49]
	global_load_dword v138, v[50:51], off nt
	global_load_dword v139, v[52:53], off nt
	v_mad_u64_u32 v[50:51], s[68:69], v55, s40, v[2:3]
	v_mad_u64_u32 v[52:53], s[68:69], v54, s40, v[2:3]
	v_or_b32_e32 v55, s64, v0
	v_or_b32_e32 v54, s37, v1
	v_mov_b32_e32 v154, v50
	v_mov_b32_e32 v155, v52
	v_or_b32_e32 v50, s64, v4
	v_or_b32_e32 v52, s37, v3
	v_mad_u64_u32 v[50:51], s[64:65], v50, s67, v[48:49]
	v_mad_u64_u32 v[52:53], s[64:65], v52, s67, v[48:49]
	global_load_dword v140, v[50:51], off nt
	global_load_dword v141, v[52:53], off nt
	v_mad_u64_u32 v[50:51], s[64:65], v55, s40, v[2:3]
	v_mad_u64_u32 v[52:53], s[64:65], v54, s40, v[2:3]
	v_mov_b32_e32 v156, v50
	v_mov_b32_e32 v157, v52
	s_waitcnt vmcnt(15)
	ds_write_b32 v142, v126
	s_waitcnt vmcnt(14)
	ds_write_b32 v143, v127
	s_waitcnt vmcnt(13)
	ds_write_b32 v144, v128
	s_waitcnt vmcnt(12)
	ds_write_b32 v145, v129
	s_waitcnt vmcnt(11)
	ds_write_b32 v146, v130
	s_waitcnt vmcnt(10)
	ds_write_b32 v147, v131
	s_waitcnt vmcnt(9)
	ds_write_b32 v148, v132
	s_waitcnt vmcnt(8)
	ds_write_b32 v149, v133
	s_waitcnt vmcnt(7)
	ds_write_b32 v150, v134
	s_waitcnt vmcnt(6)
	ds_write_b32 v151, v135
	s_waitcnt vmcnt(5)
	ds_write_b32 v152, v136
	s_waitcnt vmcnt(4)
	ds_write_b32 v153, v137
	s_waitcnt vmcnt(3)
	ds_write_b32 v154, v138
	s_waitcnt vmcnt(2)
	ds_write_b32 v155, v139
	s_waitcnt vmcnt(1)
	ds_write_b32 v156, v140
	s_waitcnt vmcnt(0)
	ds_write_b32 v157, v141
	s_cbranch_scc1 .LBB0_935
	v_or_b32_e32 v4, v101, v60
	v_cndmask_b32_e64 v3, 0, 1, s[94:95]
	v_mov_b32_e32 v71, 1.0
	v_cmp_ne_u32_e64 s[8:9], 1, v3
	s_andn2_b64 vcc, exec, s[94:95]
	v_lshlrev_b32_e32 v3, 2, v4
	v_mov_b32_e32 v70, 1.0
	s_cbranch_vccnz .LBB0_938
	global_load_dword v70, v3, s[78:79]

.LBB0_956:
	s_lshl_b32 s36, s9, 1
	s_lshl_b32 s35, s8, 1
	v_or_b32_e32 v50, s36, v4
	v_or_b32_e32 v52, s35, v3
	v_mad_u64_u32 v[50:51], s[64:65], v50, s67, v[48:49]
	v_mad_u64_u32 v[52:53], s[64:65], v52, s67, v[48:49]
	global_load_dword v126, v[50:51], off nt
	global_load_dword v127, v[52:53], off nt
	v_or_b32_e32 v54, s35, v1
	v_or_b32_e32 v55, s36, v0
	v_mad_u64_u32 v[50:51], s[64:65], v55, s40, v[2:3]
	v_mad_u64_u32 v[52:53], s[64:65], v54, s40, v[2:3]
	s_add_i32 s64, s36, 4
	s_add_i32 s37, s35, 4
	v_or_b32_e32 v55, s64, v0
	v_or_b32_e32 v54, s37, v1
	s_add_i32 s9, s9, 16
	s_add_i32 s8, s8, 16
	s_add_i32 s34, s34, -16
	v_mov_b32_e32 v142, v50
	v_mov_b32_e32 v143, v52
	v_or_b32_e32 v50, s64, v4
	v_or_b32_e32 v52, s37, v3
	v_mad_u64_u32 v[50:51], s[64:65], v50, s67, v[48:49]
	v_mad_u64_u32 v[52:53], s[64:65], v52, s67, v[48:49]
	global_load_dword v128, v[50:51], off nt
	global_load_dword v129, v[52:53], off nt
	v_mad_u64_u32 v[50:51], s[64:65], v55, s40, v[2:3]
	v_mad_u64_u32 v[52:53], s[64:65], v54, s40, v[2:3]
	s_add_i32 s64, s36, 8
	s_add_i32 s37, s35, 8
	v_or_b32_e32 v55, s64, v0
	v_or_b32_e32 v54, s37, v1
	v_mov_b32_e32 v144, v50
	v_mov_b32_e32 v145, v52
	v_or_b32_e32 v50, s64, v4
	v_or_b32_e32 v52, s37, v3
	v_mad_u64_u32 v[50:51], s[64:65], v50, s67, v[48:49]
	v_mad_u64_u32 v[52:53], s[64:65], v52, s67, v[48:49]
	global_load_dword v130, v[50:51], off nt
	global_load_dword v131, v[52:53], off nt
	v_mad_u64_u32 v[50:51], s[64:65], v55, s40, v[2:3]
	v_mad_u64_u32 v[52:53], s[64:65], v54, s40, v[2:3]
	s_add_i32 s64, s36, 12
	s_add_i32 s37, s35, 12
	v_or_b32_e32 v55, s64, v0
	v_or_b32_e32 v54, s37, v1
	v_mov_b32_e32 v146, v50
	v_mov_b32_e32 v147, v52
	v_or_b32_e32 v50, s64, v4
	v_or_b32_e32 v52, s37, v3
	v_mad_u64_u32 v[50:51], s[64:65], v50, s67, v[48:49]
	v_mad_u64_u32 v[52:53], s[64:65], v52, s67, v[48:49]
	global_load_dword v132, v[50:51], off nt
	global_load_dword v133, v[52:53], off nt
	v_mad_u64_u32 v[50:51], s[64:65], v55, s40, v[2:3]
	v_mad_u64_u32 v[52:53], s[64:65], v54, s40, v[2:3]
	s_add_i32 s64, s36, 16
	s_add_i32 s37, s35, 16
	v_or_b32_e32 v55, s64, v0
	v_or_b32_e32 v54, s37, v1
	v_mov_b32_e32 v148, v50
	v_mov_b32_e32 v149, v52
	v_or_b32_e32 v50, s64, v4
	v_or_b32_e32 v52, s37, v3
	v_mad_u64_u32 v[50:51], s[64:65], v50, s67, v[48:49]
	v_mad_u64_u32 v[52:53], s[64:65], v52, s67, v[48:49]
	global_load_dword v134, v[50:51], off nt
	global_load_dword v135, v[52:53], off nt
	v_mad_u64_u32 v[50:51], s[64:65], v55, s40, v[2:3]
	v_mad_u64_u32 v[52:53], s[64:65], v54, s40, v[2:3]
	s_add_i32 s64, s36, 20
	s_add_i32 s37, s35, 20
	v_or_b32_e32 v55, s64, v0
	v_or_b32_e32 v54, s37, v1
	v_mov_b32_e32 v150, v50
	v_mov_b32_e32 v151, v52
	v_or_b32_e32 v50, s64, v4
	v_or_b32_e32 v52, s37, v3
	v_mad_u64_u32 v[50:51], s[64:65], v50, s67, v[48:49]
	v_mad_u64_u32 v[52:53], s[64:65], v52, s67, v[48:49]
	global_load_dword v136, v[50:51], off nt
	global_load_dword v137, v[52:53], off nt
	v_mad_u64_u32 v[50:51], s[64:65], v55, s40, v[2:3]
	v_mad_u64_u32 v[52:53], s[64:65], v54, s40, v[2:3]
	s_add_i32 s64, s36, 24
	s_add_i32 s37, s35, 24
	v_or_b32_e32 v55, s64, v0
	v_or_b32_e32 v54, s37, v1
	s_add_i32 s36, s36, 28
	s_add_i32 s35, s35, 28
	s_cmp_lg_u32 s34, 0
	v_mov_b32_e32 v152, v50
	v_mov_b32_e32 v153, v52
	v_or_b32_e32 v50, s64, v4
	v_or_b32_e32 v52, s37, v3
	v_mad_u64_u32 v[50:51], s[64:65], v50, s67, v[48:49]
	v_mad_u64_u32 v[52:53], s[64:65], v52, s67, v[48:49]
	global_load_dword v138, v[50:51], off nt
	global_load_dword v139, v[52:53], off nt
	v_mad_u64_u32 v[50:51], s[64:65], v55, s40, v[2:3]
	v_mad_u64_u32 v[52:53], s[64:65], v54, s40, v[2:3]
	v_or_b32_e32 v55, s36, v0
	v_or_b32_e32 v54, s35, v1
	v_mov_b32_e32 v154, v50
	v_mov_b32_e32 v155, v52
	v_or_b32_e32 v50, s36, v4
	v_or_b32_e32 v52, s35, v3
	v_mad_u64_u32 v[50:51], s[36:37], v50, s67, v[48:49]
	v_mad_u64_u32 v[52:53], s[36:37], v52, s67, v[48:49]
	global_load_dword v140, v[50:51], off nt
	global_load_dword v141, v[52:53], off nt
	v_mad_u64_u32 v[50:51], s[36:37], v55, s40, v[2:3]
	v_mad_u64_u32 v[52:53], s[36:37], v54, s40, v[2:3]
	v_mov_b32_e32 v156, v50
	v_mov_b32_e32 v157, v52
	s_waitcnt vmcnt(15)
	ds_write_b32 v142, v126
	s_waitcnt vmcnt(14)
	ds_write_b32 v143, v127
	s_waitcnt vmcnt(13)
	ds_write_b32 v144, v128
	s_waitcnt vmcnt(12)
	ds_write_b32 v145, v129
	s_waitcnt vmcnt(11)
	ds_write_b32 v146, v130
	s_waitcnt vmcnt(10)
	ds_write_b32 v147, v131
	s_waitcnt vmcnt(9)
	ds_write_b32 v148, v132
	s_waitcnt vmcnt(8)
	ds_write_b32 v149, v133
	s_waitcnt vmcnt(7)
	ds_write_b32 v150, v134
	s_waitcnt vmcnt(6)
	ds_write_b32 v151, v135
	s_waitcnt vmcnt(5)
	ds_write_b32 v152, v136
	s_waitcnt vmcnt(4)
	ds_write_b32 v153, v137
	s_waitcnt vmcnt(3)
	ds_write_b32 v154, v138
	s_waitcnt vmcnt(2)
	ds_write_b32 v155, v139
	s_waitcnt vmcnt(1)
	ds_write_b32 v156, v140
	s_waitcnt vmcnt(0)
	ds_write_b32 v157, v141
	s_cbranch_scc1 .LBB0_956
	v_or_b32_e32 v4, v101, v60
	v_cndmask_b32_e64 v3, 0, 1, s[94:95]
	v_mov_b32_e32 v69, 1.0
	v_cmp_ne_u32_e64 s[8:9], 1, v3
	s_andn2_b64 vcc, exec, s[94:95]
	v_lshlrev_b32_e32 v3, 2, v4
	v_mov_b32_e32 v68, 1.0
	s_cbranch_vccnz .LBB0_959
	global_load_dword v68, v3, s[78:79]

.LBB0_977:
	s_lshl_b32 s34, s9, 1
	s_lshl_b32 s11, s8, 1
	v_or_b32_e32 v54, s34, v4
	v_or_b32_e32 v56, s11, v3
	v_mad_i64_i32 v[54:55], s[36:37], v54, s41, v[52:53]
	v_mad_i64_i32 v[56:57], s[36:37], v56, s41, v[52:53]
	global_load_dword v126, v[54:55], off nt
	global_load_dword v127, v[56:57], off nt
	v_or_b32_e32 v49, s11, v1
	v_or_b32_e32 v51, s34, v0
	v_mad_u64_u32 v[54:55], s[36:37], v51, s40, v[2:3]
	v_mad_u64_u32 v[56:57], s[36:37], v49, s40, v[2:3]
	s_add_i32 s36, s34, 4
	s_add_i32 s35, s11, 4
	v_or_b32_e32 v51, s36, v0
	v_or_b32_e32 v49, s35, v1
	s_add_i32 s9, s9, 16
	s_add_i32 s8, s8, 16
	s_add_i32 s10, s10, -16
	v_mov_b32_e32 v142, v54
	v_mov_b32_e32 v143, v56
	v_or_b32_e32 v54, s36, v4
	v_or_b32_e32 v56, s35, v3
	v_mad_i64_i32 v[54:55], s[36:37], v54, s41, v[52:53]
	v_mad_i64_i32 v[56:57], s[36:37], v56, s41, v[52:53]
	global_load_dword v128, v[54:55], off nt
	global_load_dword v129, v[56:57], off nt
	v_mad_u64_u32 v[54:55], s[36:37], v51, s40, v[2:3]
	v_mad_u64_u32 v[56:57], s[36:37], v49, s40, v[2:3]
	s_add_i32 s36, s34, 8
	s_add_i32 s35, s11, 8
	v_or_b32_e32 v51, s36, v0
	v_or_b32_e32 v49, s35, v1
	v_mov_b32_e32 v144, v54
	v_mov_b32_e32 v145, v56
	v_or_b32_e32 v54, s36, v4
	v_or_b32_e32 v56, s35, v3
	v_mad_i64_i32 v[54:55], s[36:37], v54, s41, v[52:53]
	v_mad_i64_i32 v[56:57], s[36:37], v56, s41, v[52:53]
	global_load_dword v130, v[54:55], off nt
	global_load_dword v131, v[56:57], off nt
	v_mad_u64_u32 v[54:55], s[36:37], v51, s40, v[2:3]
	v_mad_u64_u32 v[56:57], s[36:37], v49, s40, v[2:3]
	s_add_i32 s36, s34, 12
	s_add_i32 s35, s11, 12
	v_or_b32_e32 v51, s36, v0
	v_or_b32_e32 v49, s35, v1
	v_mov_b32_e32 v146, v54
	v_mov_b32_e32 v147, v56
	v_or_b32_e32 v54, s36, v4
	v_or_b32_e32 v56, s35, v3
	v_mad_i64_i32 v[54:55], s[36:37], v54, s41, v[52:53]
	v_mad_i64_i32 v[56:57], s[36:37], v56, s41, v[52:53]
	global_load_dword v132, v[54:55], off nt
	global_load_dword v133, v[56:57], off nt
	v_mad_u64_u32 v[54:55], s[36:37], v51, s40, v[2:3]
	v_mad_u64_u32 v[56:57], s[36:37], v49, s40, v[2:3]
	s_add_i32 s36, s34, 16
	s_add_i32 s35, s11, 16
	v_or_b32_e32 v51, s36, v0
	v_or_b32_e32 v49, s35, v1
	v_mov_b32_e32 v148, v54
	v_mov_b32_e32 v149, v56
	v_or_b32_e32 v54, s36, v4
	v_or_b32_e32 v56, s35, v3
	v_mad_i64_i32 v[54:55], s[36:37], v54, s41, v[52:53]
	v_mad_i64_i32 v[56:57], s[36:37], v56, s41, v[52:53]
	global_load_dword v134, v[54:55], off nt
	global_load_dword v135, v[56:57], off nt
	v_mad_u64_u32 v[54:55], s[36:37], v51, s40, v[2:3]
	v_mad_u64_u32 v[56:57], s[36:37], v49, s40, v[2:3]
	s_add_i32 s36, s34, 20
	s_add_i32 s35, s11, 20
	v_or_b32_e32 v51, s36, v0
	v_or_b32_e32 v49, s35, v1
	v_mov_b32_e32 v150, v54
	v_mov_b32_e32 v151, v56
	v_or_b32_e32 v54, s36, v4
	v_or_b32_e32 v56, s35, v3
	v_mad_i64_i32 v[54:55], s[36:37], v54, s41, v[52:53]
	v_mad_i64_i32 v[56:57], s[36:37], v56, s41, v[52:53]
	global_load_dword v136, v[54:55], off nt
	global_load_dword v137, v[56:57], off nt
	v_mad_u64_u32 v[54:55], s[36:37], v51, s40, v[2:3]
	v_mad_u64_u32 v[56:57], s[36:37], v49, s40, v[2:3]
	s_add_i32 s36, s34, 24
	s_add_i32 s35, s11, 24
	v_or_b32_e32 v51, s36, v0
	v_or_b32_e32 v49, s35, v1
	s_add_i32 s34, s34, 28
	s_add_i32 s11, s11, 28
	s_cmp_lg_u32 s10, 0
	v_mov_b32_e32 v152, v54
	v_mov_b32_e32 v153, v56
	v_or_b32_e32 v54, s36, v4
	v_or_b32_e32 v56, s35, v3
	v_mad_i64_i32 v[54:55], s[36:37], v54, s41, v[52:53]
	v_mad_i64_i32 v[56:57], s[36:37], v56, s41, v[52:53]
	global_load_dword v138, v[54:55], off nt
	global_load_dword v139, v[56:57], off nt
	v_mad_u64_u32 v[54:55], s[36:37], v51, s40, v[2:3]
	v_mad_u64_u32 v[56:57], s[36:37], v49, s40, v[2:3]
	v_or_b32_e32 v51, s34, v0
	v_or_b32_e32 v49, s11, v1
	v_mov_b32_e32 v154, v54
	v_mov_b32_e32 v155, v56
	v_or_b32_e32 v54, s34, v4
	v_or_b32_e32 v56, s11, v3
	v_mad_i64_i32 v[54:55], s[34:35], v54, s41, v[52:53]
	v_mad_i64_i32 v[56:57], s[34:35], v56, s41, v[52:53]
	global_load_dword v140, v[54:55], off nt
	global_load_dword v141, v[56:57], off nt
	v_mad_u64_u32 v[54:55], s[34:35], v51, s40, v[2:3]
	v_mad_u64_u32 v[56:57], s[34:35], v49, s40, v[2:3]
	v_mov_b32_e32 v156, v54
	v_mov_b32_e32 v157, v56
	s_waitcnt vmcnt(15)
	ds_write_b32 v142, v126
	s_waitcnt vmcnt(14)
	ds_write_b32 v143, v127
	s_waitcnt vmcnt(13)
	ds_write_b32 v144, v128
	s_waitcnt vmcnt(12)
	ds_write_b32 v145, v129
	s_waitcnt vmcnt(11)
	ds_write_b32 v146, v130
	s_waitcnt vmcnt(10)
	ds_write_b32 v147, v131
	s_waitcnt vmcnt(9)
	ds_write_b32 v148, v132
	s_waitcnt vmcnt(8)
	ds_write_b32 v149, v133
	s_waitcnt vmcnt(7)
	ds_write_b32 v150, v134
	s_waitcnt vmcnt(6)
	ds_write_b32 v151, v135
	s_waitcnt vmcnt(5)
	ds_write_b32 v152, v136
	s_waitcnt vmcnt(4)
	ds_write_b32 v153, v137
	s_waitcnt vmcnt(3)
	ds_write_b32 v154, v138
	s_waitcnt vmcnt(2)
	ds_write_b32 v155, v139
	s_waitcnt vmcnt(1)
	ds_write_b32 v156, v140
	s_waitcnt vmcnt(0)
	ds_write_b32 v157, v141
	s_cbranch_scc1 .LBB0_977
	v_or_b32_e32 v52, v50, v101
	v_cndmask_b32_e64 v3, 0, 1, s[96:97]
	v_mov_b32_e32 v71, 1.0
	v_cmp_ne_u32_e64 s[8:9], 1, v3
	s_andn2_b64 vcc, exec, s[96:97]
	v_ashrrev_i32_e32 v53, 31, v52
	v_mov_b32_e32 v70, 1.0
	s_cbranch_vccnz .LBB0_980
	v_lshl_add_u64 v[54:55], v[52:53], 2, s[28:29]
	global_load_dword v70, v[54:55], off

.LBB0_1776:
	s_lshl_b32 s69, s64, 1
	s_lshl_b32 s70, s65, 1
	v_or_b32_e32 v56, s69, v1
	v_or_b32_e32 v57, s70, v0
	v_add_lshl_u32 v4, v56, v3, 10
	v_add_lshl_u32 v53, v57, v48, 10
	v_or_b32_e32 v52, v49, v4
	v_or_b32_e32 v4, v50, v53
	v_lshl_add_u64 v[54:55], v[4:5], 2, s[88:89]
	v_mov_b32_e32 v53, v5
	v_lshl_add_u64 v[52:53], v[52:53], 2, s[88:89]
	global_load_dword v126, v[54:55], off nt
	global_load_dword v127, v[52:53], off nt
	v_mad_u64_u32 v[52:53], s[72:73], v57, s40, v[2:3]
	v_mad_u64_u32 v[54:55], s[72:73], v56, s40, v[2:3]
	s_add_i32 s71, s69, 4
	s_add_i32 s72, s70, 4
	v_or_b32_e32 v56, s71, v1
	v_or_b32_e32 v57, s72, v0
	v_add_lshl_u32 v53, v57, v48, 10
	s_add_i32 s71, s69, 8
	s_add_i32 s65, s65, 16
	s_add_i32 s64, s64, 16
	s_add_i32 s68, s68, -16
	v_mov_b32_e32 v142, v52
	v_mov_b32_e32 v143, v54
	v_add_lshl_u32 v4, v56, v3, 10
	v_or_b32_e32 v52, v49, v4
	v_or_b32_e32 v4, v50, v53
	v_lshl_add_u64 v[54:55], v[4:5], 2, s[88:89]
	v_mov_b32_e32 v53, v5
	v_lshl_add_u64 v[52:53], v[52:53], 2, s[88:89]
	global_load_dword v128, v[54:55], off nt
	global_load_dword v129, v[52:53], off nt
	v_mad_u64_u32 v[52:53], s[72:73], v57, s40, v[2:3]
	v_mad_u64_u32 v[54:55], s[72:73], v56, s40, v[2:3]
	s_add_i32 s72, s70, 8
	v_or_b32_e32 v56, s71, v1
	v_or_b32_e32 v57, s72, v0
	v_add_lshl_u32 v53, v57, v48, 10
	s_add_i32 s71, s69, 12
	v_mov_b32_e32 v144, v52
	v_mov_b32_e32 v145, v54
	v_add_lshl_u32 v4, v56, v3, 10
	v_or_b32_e32 v52, v49, v4
	v_or_b32_e32 v4, v50, v53
	v_lshl_add_u64 v[54:55], v[4:5], 2, s[88:89]
	v_mov_b32_e32 v53, v5
	v_lshl_add_u64 v[52:53], v[52:53], 2, s[88:89]
	global_load_dword v130, v[54:55], off nt
	global_load_dword v131, v[52:53], off nt
	v_mad_u64_u32 v[52:53], s[72:73], v57, s40, v[2:3]
	v_mad_u64_u32 v[54:55], s[72:73], v56, s40, v[2:3]
	s_add_i32 s72, s70, 12
	v_or_b32_e32 v56, s71, v1
	v_or_b32_e32 v57, s72, v0
	v_add_lshl_u32 v53, v57, v48, 10
	s_add_i32 s71, s69, 16
	v_mov_b32_e32 v146, v52
	v_mov_b32_e32 v147, v54
	v_add_lshl_u32 v4, v56, v3, 10
	v_or_b32_e32 v52, v49, v4
	v_or_b32_e32 v4, v50, v53
	v_lshl_add_u64 v[54:55], v[4:5], 2, s[88:89]
	v_mov_b32_e32 v53, v5
	v_lshl_add_u64 v[52:53], v[52:53], 2, s[88:89]
	global_load_dword v132, v[54:55], off nt
	global_load_dword v133, v[52:53], off nt
	v_mad_u64_u32 v[52:53], s[72:73], v57, s40, v[2:3]
	v_mad_u64_u32 v[54:55], s[72:73], v56, s40, v[2:3]
	s_add_i32 s72, s70, 16
	v_or_b32_e32 v56, s71, v1
	v_or_b32_e32 v57, s72, v0
	v_add_lshl_u32 v53, v57, v48, 10
	s_add_i32 s71, s69, 20
	v_mov_b32_e32 v148, v52
	v_mov_b32_e32 v149, v54
	v_add_lshl_u32 v4, v56, v3, 10
	v_or_b32_e32 v52, v49, v4
	v_or_b32_e32 v4, v50, v53
	v_lshl_add_u64 v[54:55], v[4:5], 2, s[88:89]
	v_mov_b32_e32 v53, v5
	v_lshl_add_u64 v[52:53], v[52:53], 2, s[88:89]
	global_load_dword v134, v[54:55], off nt
	global_load_dword v135, v[52:53], off nt
	v_mad_u64_u32 v[52:53], s[72:73], v57, s40, v[2:3]
	v_mad_u64_u32 v[54:55], s[72:73], v56, s40, v[2:3]
	s_add_i32 s72, s70, 20
	v_or_b32_e32 v56, s71, v1
	v_or_b32_e32 v57, s72, v0
	v_add_lshl_u32 v53, v57, v48, 10
	s_add_i32 s71, s69, 24
	s_add_i32 s69, s69, 28
	v_mov_b32_e32 v150, v52
	v_mov_b32_e32 v151, v54
	v_add_lshl_u32 v4, v56, v3, 10
	v_or_b32_e32 v52, v49, v4
	v_or_b32_e32 v4, v50, v53
	v_lshl_add_u64 v[54:55], v[4:5], 2, s[88:89]
	v_mov_b32_e32 v53, v5
	v_lshl_add_u64 v[52:53], v[52:53], 2, s[88:89]
	global_load_dword v136, v[54:55], off nt
	global_load_dword v137, v[52:53], off nt
	v_mad_u64_u32 v[52:53], s[72:73], v57, s40, v[2:3]
	v_mad_u64_u32 v[54:55], s[72:73], v56, s40, v[2:3]
	s_add_i32 s72, s70, 24
	v_or_b32_e32 v56, s71, v1
	v_or_b32_e32 v57, s72, v0
	v_add_lshl_u32 v53, v57, v48, 10
	s_add_i32 s70, s70, 28
	s_cmp_lg_u32 s68, 0
	v_mov_b32_e32 v152, v52
	v_mov_b32_e32 v153, v54
	v_add_lshl_u32 v4, v56, v3, 10
	v_or_b32_e32 v52, v49, v4
	v_or_b32_e32 v4, v50, v53
	v_lshl_add_u64 v[54:55], v[4:5], 2, s[88:89]
	v_mov_b32_e32 v53, v5
	v_lshl_add_u64 v[52:53], v[52:53], 2, s[88:89]
	global_load_dword v138, v[54:55], off nt
	global_load_dword v139, v[52:53], off nt
	v_mad_u64_u32 v[52:53], s[72:73], v57, s40, v[2:3]
	v_mad_u64_u32 v[54:55], s[72:73], v56, s40, v[2:3]
	v_or_b32_e32 v56, s69, v1
	v_or_b32_e32 v57, s70, v0
	v_mov_b32_e32 v55, v5
	v_mov_b32_e32 v154, v52
	v_mov_b32_e32 v155, v54
	v_add_lshl_u32 v4, v56, v3, 10
	v_add_lshl_u32 v52, v57, v48, 10
	v_or_b32_e32 v54, v49, v4
	v_or_b32_e32 v4, v50, v52
	v_lshl_add_u64 v[52:53], v[4:5], 2, s[88:89]
	v_lshl_add_u64 v[54:55], v[54:55], 2, s[88:89]
	global_load_dword v140, v[52:53], off nt
	global_load_dword v141, v[54:55], off nt
	v_mad_u64_u32 v[52:53], s[70:71], v57, s40, v[2:3]
	v_mad_u64_u32 v[54:55], s[70:71], v56, s40, v[2:3]
	v_mov_b32_e32 v156, v52
	v_mov_b32_e32 v157, v54
	s_waitcnt vmcnt(15)
	ds_write_b32 v142, v126
	s_waitcnt vmcnt(14)
	ds_write_b32 v143, v127
	s_waitcnt vmcnt(13)
	ds_write_b32 v144, v128
	s_waitcnt vmcnt(12)
	ds_write_b32 v145, v129
	s_waitcnt vmcnt(11)
	ds_write_b32 v146, v130
	s_waitcnt vmcnt(10)
	ds_write_b32 v147, v131
	s_waitcnt vmcnt(9)
	ds_write_b32 v148, v132
	s_waitcnt vmcnt(8)
	ds_write_b32 v149, v133
	s_waitcnt vmcnt(7)
	ds_write_b32 v150, v134
	s_waitcnt vmcnt(6)
	ds_write_b32 v151, v135
	s_waitcnt vmcnt(5)
	ds_write_b32 v152, v136
	s_waitcnt vmcnt(4)
	ds_write_b32 v153, v137
	s_waitcnt vmcnt(3)
	ds_write_b32 v154, v138
	s_waitcnt vmcnt(2)
	ds_write_b32 v155, v139
	s_waitcnt vmcnt(1)
	ds_write_b32 v156, v140
	s_waitcnt vmcnt(0)
	ds_write_b32 v157, v141
	s_cbranch_scc1 .LBB0_1776
	v_or_b32_e32 v3, v51, v96
	v_lshlrev_b32_e32 v4, 2, v3
	v_or_b32_e32 v49, 0x5000, v4
	global_load_dword v90, v49, s[14:15]
	global_load_dword v80, v49, s[94:95]
	v_or_b32_e32 v49, 0x5020, v4
	global_load_dword v62, v49, s[14:15]
	global_load_dword v60, v49, s[94:95]
	v_or_b32_e32 v49, 0x5040, v4
	global_load_dword v58, v49, s[14:15]
	global_load_dword v56, v49, s[94:95]
	v_or_b32_e32 v4, 0x5060, v4
	global_load_dword v52, v4, s[14:15]
	global_load_dword v50, v4, s[94:95]
	s_waitcnt lgkmcnt(0)
	ds_read2_b32 v[74:75], v97 offset0:33 offset1:41
	ds_read2_b32 v[66:67], v97 offset0:66 offset1:74
	ds_read2_b32 v[64:65], v97 offset0:99 offset1:107
	ds_read2_b32 v[76:77], v97 offset0:132 offset1:140
	ds_read2_b32 v[72:73], v97 offset0:165 offset1:173
	ds_read2_b32 v[70:71], v97 offset0:198 offset1:206
	ds_read2_b32 v[68:69], v97 offset0:231 offset1:239
	ds_read2_b32 v[78:79], v97 offset1:8
	s_waitcnt lgkmcnt(4)
	v_mov_b32_e32 v86, v76
	v_mov_b32_e32 v83, v66
	s_waitcnt lgkmcnt(2)
	v_mov_b32_e32 v87, v70
	v_mov_b32_e32 v84, v74
	s_waitcnt lgkmcnt(0)
	v_mov_b32_e32 v82, v78
	v_mov_b32_e32 v85, v64
	v_mov_b32_e32 v88, v72
	v_mov_b32_e32 v89, v68
	v_lshlrev_b32_e32 v4, 1, v48
	v_lshl_add_u64 v[54:55], v[6:7], 0, v[4:5]
	v_lshl_add_u64 v[48:49], v[22:23], 0, v[4:5]
	v_mul_u32_u24_e32 v3, 0xb00, v3
	v_mov_b32_e32 v70, v77
	v_mov_b32_e32 v68, v73
	v_readlane_b32 s72, v255, 50
	v_readlane_b32 s70, v255, 48
	v_readlane_b32 s73, v255, 51
	v_readlane_b32 s71, v255, 49
	s_waitcnt vmcnt(7)
	v_pk_mul_f32 v[112:113], v[90:91], v[86:87] op_sel_hi:[0,1]
	v_pk_mul_f32 v[92:93], v[90:91], v[82:83] op_sel_hi:[0,1]
	v_pk_mul_f32 v[110:111], v[90:91], v[84:85] op_sel_hi:[0,1]
	v_pk_mul_f32 v[90:91], v[90:91], v[88:89] op_sel_hi:[0,1]
	v_bfe_u32 v64, v112, 16, 1
	v_bfe_u32 v66, v113, 16, 1
	v_bfe_u32 v4, v91, 16, 1
	v_bfe_u32 v53, v90, 16, 1
	v_bfe_u32 v63, v93, 16, 1
	v_add3_u32 v66, v113, v66, s46
	v_add3_u32 v64, v112, v64, s46
	v_bfe_u32 v57, v111, 16, 1
	v_add3_u32 v53, v90, v53, s46
	v_add3_u32 v4, v91, v4, s46
	v_bfe_u32 v61, v92, 16, 1
	v_add3_u32 v63, v93, v63, s46
	v_lshrrev_b32_e32 v64, 16, v64
	v_lshrrev_b32_e32 v66, 16, v66
	s_waitcnt vmcnt(6)
	v_pk_mul_f32 v[86:87], v[80:81], v[86:87] op_sel_hi:[0,1]
	v_bfe_u32 v59, v110, 16, 1
	v_add3_u32 v57, v111, v57, s46
	v_add3_u32 v61, v92, v61, s46
	v_lshrrev_b32_e32 v63, 16, v63
	v_and_or_b32 v93, v4, s47, v66
	v_and_or_b32 v92, v53, s47, v64
	v_pk_mul_f32 v[82:83], v[80:81], v[82:83] op_sel_hi:[0,1]
	v_pk_mul_f32 v[84:85], v[80:81], v[84:85] op_sel_hi:[0,1]
	v_pk_mul_f32 v[80:81], v[80:81], v[88:89] op_sel_hi:[0,1]
	v_bfe_u32 v64, v86, 16, 1
	v_bfe_u32 v66, v87, 16, 1
	v_add3_u32 v59, v110, v59, s46
	v_lshrrev_b32_e32 v61, 16, v61
	v_and_or_b32 v91, v57, s47, v63
	v_lshlrev_b32_e32 v4, 1, v3
	v_bfe_u32 v3, v81, 16, 1
	v_bfe_u32 v53, v80, 16, 1
	v_bfe_u32 v63, v83, 16, 1
	v_add3_u32 v66, v87, v66, s46
	v_add3_u32 v64, v86, v64, s46
	v_and_or_b32 v90, v59, s47, v61
	v_bfe_u32 v57, v85, 16, 1
	v_add3_u32 v53, v80, v53, s46
	v_add3_u32 v3, v81, v3, s46
	v_bfe_u32 v61, v82, 16, 1
	v_add3_u32 v63, v83, v63, s46
	v_lshrrev_b32_e32 v64, 16, v64
	v_lshrrev_b32_e32 v66, 16, v66
	v_add3_u32 v57, v85, v57, s46
	v_add3_u32 v61, v82, v61, s46
	v_lshrrev_b32_e32 v63, 16, v63
	v_and_or_b32 v83, v3, s47, v66
	v_and_or_b32 v82, v53, s47, v64
	v_mov_b32_e32 v66, v79
	v_mov_b32_e32 v64, v75
	v_and_or_b32 v81, v57, s47, v63
	s_waitcnt vmcnt(5)
	v_pk_mul_f32 v[78:79], v[62:63], v[66:67] op_sel_hi:[0,1]
	v_pk_mul_f32 v[74:75], v[62:63], v[64:65] op_sel_hi:[0,1]
	v_pk_mul_f32 v[76:77], v[62:63], v[70:71] op_sel_hi:[0,1]
	v_pk_mul_f32 v[62:63], v[62:63], v[68:69] op_sel_hi:[0,1]
	v_bfe_u32 v3, v63, 16, 1
	v_bfe_u32 v59, v84, 16, 1
	v_add3_u32 v3, v63, v3, s46
	v_bfe_u32 v63, v77, 16, 1
	v_lshl_add_u64 v[110:111], v[54:55], 0, v[4:5]
	v_add3_u32 v59, v84, v59, s46
	v_lshl_add_u64 v[84:85], v[48:49], 0, v[4:5]
	v_bfe_u32 v4, v62, 16, 1
	v_add3_u32 v63, v77, v63, s46
	v_lshrrev_b32_e32 v61, 16, v61
	v_bfe_u32 v53, v75, 16, 1
	v_add3_u32 v4, v62, v4, s46
	v_bfe_u32 v62, v76, 16, 1
	v_lshrrev_b32_e32 v63, 16, v63
	v_and_or_b32 v80, v59, s47, v61
	v_add3_u32 v53, v75, v53, s46
	v_bfe_u32 v59, v78, 16, 1
	v_bfe_u32 v61, v79, 16, 1
	v_add3_u32 v62, v76, v62, s46
	v_and_or_b32 v75, v3, s47, v63
	v_or_b32_e32 v3, v51, v98
	v_bfe_u32 v57, v74, 16, 1
	v_add3_u32 v61, v79, v61, s46
	v_add3_u32 v59, v78, v59, s46
	v_lshrrev_b32_e32 v62, 16, v62
	v_mul_u32_u24_e32 v3, 0xb00, v3
	v_add3_u32 v57, v74, v57, s46
	v_lshrrev_b32_e32 v59, 16, v59
	v_lshrrev_b32_e32 v61, 16, v61
	v_and_or_b32 v74, v4, s47, v62
	v_lshlrev_b32_e32 v4, 1, v3
	v_and_or_b32 v73, v53, s47, v61
	v_and_or_b32 v72, v57, s47, v59
	v_lshl_add_u64 v[62:63], v[54:55], 0, v[4:5]
	global_store_dwordx4 v[110:111], v[90:93], off
	global_store_dwordx4 v[84:85], v[80:83], off
	global_store_dwordx4 v[62:63], v[72:75], off
	s_waitcnt vmcnt(7)
	v_pk_mul_f32 v[62:63], v[60:61], v[66:67] op_sel_hi:[0,1]
	v_pk_mul_f32 v[64:65], v[60:61], v[64:65] op_sel_hi:[0,1]
	v_pk_mul_f32 v[66:67], v[60:61], v[70:71] op_sel_hi:[0,1]
	v_pk_mul_f32 v[60:61], v[60:61], v[68:69] op_sel_hi:[0,1]
	v_bfe_u32 v3, v61, 16, 1
	v_bfe_u32 v53, v60, 16, 1
	v_bfe_u32 v57, v65, 16, 1
	v_bfe_u32 v59, v64, 16, 1
	v_add3_u32 v59, v64, v59, s46
	v_add3_u32 v57, v65, v57, s46
	v_add3_u32 v53, v60, v53, s46
	v_add3_u32 v3, v61, v3, s46
	v_bfe_u32 v60, v62, 16, 1
	v_bfe_u32 v61, v63, 16, 1
	v_bfe_u32 v64, v66, 16, 1
	v_bfe_u32 v65, v67, 16, 1
	v_add3_u32 v65, v67, v65, s46
	v_add3_u32 v64, v66, v64, s46
	v_add3_u32 v61, v63, v61, s46
	v_add3_u32 v60, v62, v60, s46
	v_lshrrev_b32_e32 v60, 16, v60
	v_lshrrev_b32_e32 v61, 16, v61
	v_lshrrev_b32_e32 v62, 16, v64
	v_lshrrev_b32_e32 v63, 16, v65
	v_and_or_b32 v63, v3, s47, v63
	v_and_or_b32 v62, v53, s47, v62
	v_and_or_b32 v61, v57, s47, v61
	v_and_or_b32 v60, v59, s47, v60
	v_lshl_add_u64 v[64:65], v[48:49], 0, v[4:5]
	global_store_dwordx4 v[64:65], v[60:63], off
	ds_read2_b32 v[62:63], v97 offset0:16 offset1:24
	ds_read2_b32 v[64:65], v97 offset0:49 offset1:57
	ds_read2_b32 v[66:67], v97 offset0:82 offset1:90
	ds_read2_b32 v[68:69], v97 offset0:115 offset1:123
	ds_read2_b32 v[70:71], v97 offset0:148 offset1:156
	ds_read2_b32 v[72:73], v97 offset0:181 offset1:189
	ds_read2_b32 v[74:75], v97 offset0:214 offset1:222
	ds_read2_b32 v[76:77], v97 offset0:247 offset1:255
	s_waitcnt lgkmcnt(7)
	v_mov_b32_e32 v78, v62
	s_waitcnt lgkmcnt(5)
	v_mov_b32_e32 v79, v66
	v_mov_b32_e32 v80, v64
	s_waitcnt lgkmcnt(4)
	v_mov_b32_e32 v81, v68
	s_waitcnt lgkmcnt(3)
	v_mov_b32_e32 v84, v70
	s_waitcnt lgkmcnt(1)
	v_mov_b32_e32 v85, v74
	v_mov_b32_e32 v88, v72
	s_waitcnt lgkmcnt(0)
	v_mov_b32_e32 v89, v76
	s_waitcnt vmcnt(7)
	v_pk_mul_f32 v[60:61], v[58:59], v[78:79] op_sel_hi:[0,1]
	v_pk_mul_f32 v[82:83], v[58:59], v[80:81] op_sel_hi:[0,1]
	v_pk_mul_f32 v[86:87], v[58:59], v[84:85] op_sel_hi:[0,1]
	v_pk_mul_f32 v[58:59], v[58:59], v[88:89] op_sel_hi:[0,1]
	v_bfe_u32 v3, v59, 16, 1
	v_bfe_u32 v64, v87, 16, 1
	v_add3_u32 v3, v59, v3, s46
	v_bfe_u32 v59, v61, 16, 1
	v_add3_u32 v64, v87, v64, s46
	v_bfe_u32 v4, v58, 16, 1
	v_bfe_u32 v62, v86, 16, 1
	v_add3_u32 v59, v61, v59, s46
	v_lshrrev_b32_e32 v61, 16, v64
	v_add3_u32 v4, v58, v4, s46
	v_bfe_u32 v58, v60, 16, 1
	v_add3_u32 v62, v86, v62, s46
	v_and_or_b32 v61, v3, s47, v61
	v_or_b32_e32 v3, v51, v99
	v_bfe_u32 v53, v83, 16, 1
	v_bfe_u32 v57, v82, 16, 1
	v_add3_u32 v58, v60, v58, s46
	v_lshrrev_b32_e32 v60, 16, v62
	v_mul_u32_u24_e32 v3, 0xb00, v3
	v_add3_u32 v57, v82, v57, s46
	v_add3_u32 v53, v83, v53, s46
	v_lshrrev_b32_e32 v58, 16, v58
	v_lshrrev_b32_e32 v59, 16, v59
	v_and_or_b32 v60, v4, s47, v60
	v_lshlrev_b32_e32 v4, 1, v3
	v_and_or_b32 v59, v53, s47, v59
	v_and_or_b32 v58, v57, s47, v58
	v_lshl_add_u64 v[82:83], v[54:55], 0, v[4:5]
	global_store_dwordx4 v[82:83], v[58:61], off
	v_mov_b32_e32 v68, v65
	v_mov_b32_e32 v66, v63
	s_waitcnt vmcnt(7)
	v_pk_mul_f32 v[58:59], v[56:57], v[78:79] op_sel_hi:[0,1]
	v_pk_mul_f32 v[60:61], v[56:57], v[80:81] op_sel_hi:[0,1]
	v_pk_mul_f32 v[78:79], v[56:57], v[84:85] op_sel_hi:[0,1]
	v_pk_mul_f32 v[56:57], v[56:57], v[88:89] op_sel_hi:[0,1]
	v_bfe_u32 v3, v57, 16, 1
	v_bfe_u32 v53, v56, 16, 1
	v_bfe_u32 v62, v61, 16, 1
	v_bfe_u32 v64, v60, 16, 1
	v_add3_u32 v60, v60, v64, s46
	v_add3_u32 v61, v61, v62, s46
	v_add3_u32 v53, v56, v53, s46
	v_add3_u32 v3, v57, v3, s46
	v_bfe_u32 v56, v58, 16, 1
	v_bfe_u32 v57, v59, 16, 1
	v_bfe_u32 v62, v78, 16, 1
	v_bfe_u32 v64, v79, 16, 1
	v_add3_u32 v64, v79, v64, s46
	v_add3_u32 v62, v78, v62, s46
	v_add3_u32 v57, v59, v57, s46
	v_add3_u32 v56, v58, v56, s46
	v_lshrrev_b32_e32 v56, 16, v56
	v_lshrrev_b32_e32 v57, 16, v57
	v_lshrrev_b32_e32 v58, 16, v62
	v_lshrrev_b32_e32 v59, 16, v64
	v_and_or_b32 v59, v3, s47, v59
	v_and_or_b32 v58, v53, s47, v58
	v_and_or_b32 v57, v61, s47, v57
	v_and_or_b32 v56, v60, s47, v56
	v_lshl_add_u64 v[60:61], v[48:49], 0, v[4:5]
	global_store_dwordx4 v[60:61], v[56:59], off
	v_mov_b32_e32 v74, v71
	v_mov_b32_e32 v76, v73
	s_waitcnt vmcnt(7)
	v_pk_mul_f32 v[58:59], v[52:53], v[68:69] op_sel_hi:[0,1]
	v_pk_mul_f32 v[56:57], v[52:53], v[66:67] op_sel_hi:[0,1]
	v_pk_mul_f32 v[60:61], v[52:53], v[74:75] op_sel_hi:[0,1]
	v_pk_mul_f32 v[52:53], v[52:53], v[76:77] op_sel_hi:[0,1]
	v_bfe_u32 v62, v59, 16, 1
	v_bfe_u32 v3, v53, 16, 1
	v_add3_u32 v62, v59, v62, s46
	v_bfe_u32 v59, v61, 16, 1
	v_bfe_u32 v63, v58, 16, 1
	v_add3_u32 v3, v53, v3, s46
	v_bfe_u32 v53, v57, 16, 1
	v_add3_u32 v59, v61, v59, s46
	v_bfe_u32 v4, v52, 16, 1
	v_add3_u32 v63, v58, v63, s46
	v_bfe_u32 v58, v60, 16, 1
	v_add3_u32 v53, v57, v53, s46
	v_lshrrev_b32_e32 v57, 16, v59
	v_add3_u32 v4, v52, v4, s46
	v_bfe_u32 v52, v56, 16, 1
	v_add3_u32 v58, v60, v58, s46
	v_and_or_b32 v59, v3, s47, v57
	v_or_b32_e32 v3, v51, v100
	v_add3_u32 v52, v56, v52, s46
	v_lshrrev_b32_e32 v56, 16, v58
	v_mul_u32_u24_e32 v3, 0xb00, v3
	v_lshrrev_b32_e32 v52, 16, v52
	v_lshrrev_b32_e32 v53, 16, v53
	v_and_or_b32 v58, v4, s47, v56
	v_lshlrev_b32_e32 v4, 1, v3
	v_and_or_b32 v57, v62, s47, v53
	v_and_or_b32 v56, v63, s47, v52
	v_lshl_add_u64 v[52:53], v[54:55], 0, v[4:5]
	global_store_dwordx4 v[52:53], v[56:59], off
	s_waitcnt vmcnt(7)
	v_pk_mul_f32 v[52:53], v[50:51], v[66:67] op_sel_hi:[0,1]
	v_pk_mul_f32 v[54:55], v[50:51], v[68:69] op_sel_hi:[0,1]
	v_pk_mul_f32 v[56:57], v[50:51], v[74:75] op_sel_hi:[0,1]
	v_pk_mul_f32 v[50:51], v[50:51], v[76:77] op_sel_hi:[0,1]
	v_bfe_u32 v3, v51, 16, 1
	v_bfe_u32 v58, v50, 16, 1
	v_bfe_u32 v59, v55, 16, 1
	v_bfe_u32 v60, v54, 16, 1
	v_add3_u32 v54, v54, v60, s46
	v_add3_u32 v55, v55, v59, s46
	v_add3_u32 v50, v50, v58, s46
	v_add3_u32 v3, v51, v3, s46
	v_bfe_u32 v51, v52, 16, 1
	v_bfe_u32 v58, v53, 16, 1
	v_bfe_u32 v59, v56, 16, 1
	v_bfe_u32 v60, v57, 16, 1
	v_add3_u32 v57, v57, v60, s46
	v_add3_u32 v56, v56, v59, s46
	v_add3_u32 v53, v53, v58, s46
	v_add3_u32 v51, v52, v51, s46
	v_lshrrev_b32_e32 v58, 16, v51
	v_lshrrev_b32_e32 v51, 16, v53
	v_lshrrev_b32_e32 v52, 16, v56
	v_lshrrev_b32_e32 v53, 16, v57
	v_and_or_b32 v53, v3, s47, v53
	v_and_or_b32 v52, v50, s47, v52
	v_and_or_b32 v51, v55, s47, v51
	v_and_or_b32 v50, v54, s47, v58
	v_lshl_add_u64 v[48:49], v[48:49], 0, v[4:5]
	global_store_dwordx4 v[48:49], v[50:53], off
	s_waitcnt lgkmcnt(0)

.LBB0_1780:
	s_lshl_b32 s69, s64, 1
	s_lshl_b32 s70, s65, 1
	v_or_b32_e32 v56, s69, v1
	v_or_b32_e32 v57, s70, v0
	v_add_lshl_u32 v4, v56, v3, 10
	v_add_lshl_u32 v53, v57, v48, 10
	v_or_b32_e32 v52, v49, v4
	v_or_b32_e32 v4, v50, v53
	v_lshl_add_u64 v[54:55], v[4:5], 2, s[60:61]
	v_mov_b32_e32 v53, v5
	v_lshl_add_u64 v[52:53], v[52:53], 2, s[60:61]
	global_load_dword v126, v[54:55], off nt
	global_load_dword v127, v[52:53], off nt
	v_mad_u64_u32 v[52:53], s[72:73], v57, s40, v[2:3]
	v_mad_u64_u32 v[54:55], s[72:73], v56, s40, v[2:3]
	s_add_i32 s71, s69, 4
	s_add_i32 s72, s70, 4
	v_or_b32_e32 v56, s71, v1
	v_or_b32_e32 v57, s72, v0
	v_add_lshl_u32 v53, v57, v48, 10
	s_add_i32 s71, s69, 8
	s_add_i32 s65, s65, 16
	s_add_i32 s64, s64, 16
	s_add_i32 s68, s68, -16
	v_mov_b32_e32 v142, v52
	v_mov_b32_e32 v143, v54
	v_add_lshl_u32 v4, v56, v3, 10
	v_or_b32_e32 v52, v49, v4
	v_or_b32_e32 v4, v50, v53
	v_lshl_add_u64 v[54:55], v[4:5], 2, s[60:61]
	v_mov_b32_e32 v53, v5
	v_lshl_add_u64 v[52:53], v[52:53], 2, s[60:61]
	global_load_dword v128, v[54:55], off nt
	global_load_dword v129, v[52:53], off nt
	v_mad_u64_u32 v[52:53], s[72:73], v57, s40, v[2:3]
	v_mad_u64_u32 v[54:55], s[72:73], v56, s40, v[2:3]
	s_add_i32 s72, s70, 8
	v_or_b32_e32 v56, s71, v1
	v_or_b32_e32 v57, s72, v0
	v_add_lshl_u32 v53, v57, v48, 10
	s_add_i32 s71, s69, 12
	v_mov_b32_e32 v144, v52
	v_mov_b32_e32 v145, v54
	v_add_lshl_u32 v4, v56, v3, 10
	v_or_b32_e32 v52, v49, v4
	v_or_b32_e32 v4, v50, v53
	v_lshl_add_u64 v[54:55], v[4:5], 2, s[60:61]
	v_mov_b32_e32 v53, v5
	v_lshl_add_u64 v[52:53], v[52:53], 2, s[60:61]
	global_load_dword v130, v[54:55], off nt
	global_load_dword v131, v[52:53], off nt
	v_mad_u64_u32 v[52:53], s[72:73], v57, s40, v[2:3]
	v_mad_u64_u32 v[54:55], s[72:73], v56, s40, v[2:3]
	s_add_i32 s72, s70, 12
	v_or_b32_e32 v56, s71, v1
	v_or_b32_e32 v57, s72, v0
	v_add_lshl_u32 v53, v57, v48, 10
	s_add_i32 s71, s69, 16
	v_mov_b32_e32 v146, v52
	v_mov_b32_e32 v147, v54
	v_add_lshl_u32 v4, v56, v3, 10
	v_or_b32_e32 v52, v49, v4
	v_or_b32_e32 v4, v50, v53
	v_lshl_add_u64 v[54:55], v[4:5], 2, s[60:61]
	v_mov_b32_e32 v53, v5
	v_lshl_add_u64 v[52:53], v[52:53], 2, s[60:61]
	global_load_dword v132, v[54:55], off nt
	global_load_dword v133, v[52:53], off nt
	v_mad_u64_u32 v[52:53], s[72:73], v57, s40, v[2:3]
	v_mad_u64_u32 v[54:55], s[72:73], v56, s40, v[2:3]
	s_add_i32 s72, s70, 16
	v_or_b32_e32 v56, s71, v1
	v_or_b32_e32 v57, s72, v0
	v_add_lshl_u32 v53, v57, v48, 10
	s_add_i32 s71, s69, 20
	v_mov_b32_e32 v148, v52
	v_mov_b32_e32 v149, v54
	v_add_lshl_u32 v4, v56, v3, 10
	v_or_b32_e32 v52, v49, v4
	v_or_b32_e32 v4, v50, v53
	v_lshl_add_u64 v[54:55], v[4:5], 2, s[60:61]
	v_mov_b32_e32 v53, v5
	v_lshl_add_u64 v[52:53], v[52:53], 2, s[60:61]
	global_load_dword v134, v[54:55], off nt
	global_load_dword v135, v[52:53], off nt
	v_mad_u64_u32 v[52:53], s[72:73], v57, s40, v[2:3]
	v_mad_u64_u32 v[54:55], s[72:73], v56, s40, v[2:3]
	s_add_i32 s72, s70, 20
	v_or_b32_e32 v56, s71, v1
	v_or_b32_e32 v57, s72, v0
	v_add_lshl_u32 v53, v57, v48, 10
	s_add_i32 s71, s69, 24
	s_add_i32 s69, s69, 28
	v_mov_b32_e32 v150, v52
	v_mov_b32_e32 v151, v54
	v_add_lshl_u32 v4, v56, v3, 10
	v_or_b32_e32 v52, v49, v4
	v_or_b32_e32 v4, v50, v53
	v_lshl_add_u64 v[54:55], v[4:5], 2, s[60:61]
	v_mov_b32_e32 v53, v5
	v_lshl_add_u64 v[52:53], v[52:53], 2, s[60:61]
	global_load_dword v136, v[54:55], off nt
	global_load_dword v137, v[52:53], off nt
	v_mad_u64_u32 v[52:53], s[72:73], v57, s40, v[2:3]
	v_mad_u64_u32 v[54:55], s[72:73], v56, s40, v[2:3]
	s_add_i32 s72, s70, 24
	v_or_b32_e32 v56, s71, v1
	v_or_b32_e32 v57, s72, v0
	v_add_lshl_u32 v53, v57, v48, 10
	s_add_i32 s70, s70, 28
	s_cmp_lg_u32 s68, 0
	v_mov_b32_e32 v152, v52
	v_mov_b32_e32 v153, v54
	v_add_lshl_u32 v4, v56, v3, 10
	v_or_b32_e32 v52, v49, v4
	v_or_b32_e32 v4, v50, v53
	v_lshl_add_u64 v[54:55], v[4:5], 2, s[60:61]
	v_mov_b32_e32 v53, v5
	v_lshl_add_u64 v[52:53], v[52:53], 2, s[60:61]
	global_load_dword v138, v[54:55], off nt
	global_load_dword v139, v[52:53], off nt
	v_mad_u64_u32 v[52:53], s[72:73], v57, s40, v[2:3]
	v_mad_u64_u32 v[54:55], s[72:73], v56, s40, v[2:3]
	v_or_b32_e32 v56, s69, v1
	v_or_b32_e32 v57, s70, v0
	v_mov_b32_e32 v55, v5
	v_mov_b32_e32 v154, v52
	v_mov_b32_e32 v155, v54
	v_add_lshl_u32 v4, v56, v3, 10
	v_add_lshl_u32 v52, v57, v48, 10
	v_or_b32_e32 v54, v49, v4
	v_or_b32_e32 v4, v50, v52
	v_lshl_add_u64 v[52:53], v[4:5], 2, s[60:61]
	v_lshl_add_u64 v[54:55], v[54:55], 2, s[60:61]
	global_load_dword v140, v[52:53], off nt
	global_load_dword v141, v[54:55], off nt
	v_mad_u64_u32 v[52:53], s[70:71], v57, s40, v[2:3]
	v_mad_u64_u32 v[54:55], s[70:71], v56, s40, v[2:3]
	v_mov_b32_e32 v156, v52
	v_mov_b32_e32 v157, v54
	s_waitcnt vmcnt(15)
	ds_write_b32 v142, v126
	s_waitcnt vmcnt(14)
	ds_write_b32 v143, v127
	s_waitcnt vmcnt(13)
	ds_write_b32 v144, v128
	s_waitcnt vmcnt(12)
	ds_write_b32 v145, v129
	s_waitcnt vmcnt(11)
	ds_write_b32 v146, v130
	s_waitcnt vmcnt(10)
	ds_write_b32 v147, v131
	s_waitcnt vmcnt(9)
	ds_write_b32 v148, v132
	s_waitcnt vmcnt(8)
	ds_write_b32 v149, v133
	s_waitcnt vmcnt(7)
	ds_write_b32 v150, v134
	s_waitcnt vmcnt(6)
	ds_write_b32 v151, v135
	s_waitcnt vmcnt(5)
	ds_write_b32 v152, v136
	s_waitcnt vmcnt(4)
	ds_write_b32 v153, v137
	s_waitcnt vmcnt(3)
	ds_write_b32 v154, v138
	s_waitcnt vmcnt(2)
	ds_write_b32 v155, v139
	s_waitcnt vmcnt(1)
	ds_write_b32 v156, v140
	s_waitcnt vmcnt(0)
	ds_write_b32 v157, v141
	s_cbranch_scc1 .LBB0_1780
	v_or_b32_e32 v3, v51, v96
	v_lshlrev_b32_e32 v4, 2, v3
	v_or_b32_e32 v49, 0x2000, v4
	global_load_dword v90, v49, s[14:15]
	global_load_dword v80, v49, s[94:95]
	v_or_b32_e32 v49, 0x2020, v4
	global_load_dword v62, v49, s[14:15]
	global_load_dword v60, v49, s[94:95]
	v_or_b32_e32 v49, 0x2040, v4
	global_load_dword v58, v49, s[14:15]
	global_load_dword v56, v49, s[94:95]
	v_or_b32_e32 v4, 0x2060, v4
	global_load_dword v52, v4, s[14:15]
	global_load_dword v50, v4, s[94:95]
	s_waitcnt lgkmcnt(0)
	ds_read2_b32 v[74:75], v97 offset0:33 offset1:41
	ds_read2_b32 v[66:67], v97 offset0:66 offset1:74
	ds_read2_b32 v[64:65], v97 offset0:99 offset1:107
	ds_read2_b32 v[76:77], v97 offset0:132 offset1:140
	ds_read2_b32 v[72:73], v97 offset0:165 offset1:173
	ds_read2_b32 v[70:71], v97 offset0:198 offset1:206
	ds_read2_b32 v[68:69], v97 offset0:231 offset1:239
	ds_read2_b32 v[78:79], v97 offset1:8
	s_waitcnt lgkmcnt(4)
	v_mov_b32_e32 v86, v76
	v_mov_b32_e32 v83, v66
	s_waitcnt lgkmcnt(2)
	v_mov_b32_e32 v87, v70
	v_mov_b32_e32 v84, v74
	s_waitcnt lgkmcnt(0)
	v_mov_b32_e32 v82, v78
	v_mov_b32_e32 v85, v64
	v_mov_b32_e32 v88, v72
	v_mov_b32_e32 v89, v68
	v_lshlrev_b32_e32 v4, 1, v48
	v_lshl_add_u64 v[54:55], v[8:9], 0, v[4:5]
	v_lshl_add_u64 v[48:49], v[24:25], 0, v[4:5]
	v_mov_b32_e32 v70, v77
	v_mov_b32_e32 v68, v73
	v_readlane_b32 s72, v255, 50
	v_readlane_b32 s70, v255, 48
	v_readlane_b32 s73, v255, 51
	v_readlane_b32 s71, v255, 49
	s_waitcnt vmcnt(7)
	v_pk_mul_f32 v[112:113], v[90:91], v[86:87] op_sel_hi:[0,1]
	v_pk_mul_f32 v[92:93], v[90:91], v[82:83] op_sel_hi:[0,1]
	v_pk_mul_f32 v[110:111], v[90:91], v[84:85] op_sel_hi:[0,1]
	v_pk_mul_f32 v[90:91], v[90:91], v[88:89] op_sel_hi:[0,1]
	v_bfe_u32 v64, v112, 16, 1
	v_bfe_u32 v66, v113, 16, 1
	v_bfe_u32 v4, v91, 16, 1
	v_bfe_u32 v53, v90, 16, 1
	v_bfe_u32 v63, v93, 16, 1
	v_add3_u32 v66, v113, v66, s46
	v_add3_u32 v64, v112, v64, s46
	v_bfe_u32 v57, v111, 16, 1
	v_add3_u32 v53, v90, v53, s46
	v_add3_u32 v4, v91, v4, s46
	v_bfe_u32 v61, v92, 16, 1
	v_add3_u32 v63, v93, v63, s46
	v_lshrrev_b32_e32 v64, 16, v64
	v_lshrrev_b32_e32 v66, 16, v66
	s_waitcnt vmcnt(6)
	v_pk_mul_f32 v[86:87], v[80:81], v[86:87] op_sel_hi:[0,1]
	v_bfe_u32 v59, v110, 16, 1
	v_add3_u32 v57, v111, v57, s46
	v_add3_u32 v61, v92, v61, s46
	v_lshrrev_b32_e32 v63, 16, v63
	v_and_or_b32 v93, v4, s47, v66
	v_and_or_b32 v92, v53, s47, v64
	v_pk_mul_f32 v[82:83], v[80:81], v[82:83] op_sel_hi:[0,1]
	v_pk_mul_f32 v[84:85], v[80:81], v[84:85] op_sel_hi:[0,1]
	v_pk_mul_f32 v[80:81], v[80:81], v[88:89] op_sel_hi:[0,1]
	v_bfe_u32 v64, v86, 16, 1
	v_bfe_u32 v66, v87, 16, 1
	v_add3_u32 v59, v110, v59, s46
	v_lshrrev_b32_e32 v61, 16, v61
	v_and_or_b32 v91, v57, s47, v63
	v_lshlrev_b32_e32 v4, 11, v3
	v_bfe_u32 v3, v81, 16, 1
	v_bfe_u32 v53, v80, 16, 1
	v_bfe_u32 v63, v83, 16, 1
	v_add3_u32 v66, v87, v66, s46
	v_add3_u32 v64, v86, v64, s46
	v_and_or_b32 v90, v59, s47, v61
	v_bfe_u32 v57, v85, 16, 1
	v_add3_u32 v53, v80, v53, s46
	v_add3_u32 v3, v81, v3, s46
	v_bfe_u32 v61, v82, 16, 1
	v_add3_u32 v63, v83, v63, s46
	v_lshrrev_b32_e32 v64, 16, v64
	v_lshrrev_b32_e32 v66, 16, v66
	v_add3_u32 v57, v85, v57, s46
	v_add3_u32 v61, v82, v61, s46
	v_lshrrev_b32_e32 v63, 16, v63
	v_and_or_b32 v83, v3, s47, v66
	v_and_or_b32 v82, v53, s47, v64
	v_mov_b32_e32 v66, v79
	v_mov_b32_e32 v64, v75
	v_and_or_b32 v81, v57, s47, v63
	s_waitcnt vmcnt(5)
	v_pk_mul_f32 v[78:79], v[62:63], v[66:67] op_sel_hi:[0,1]
	v_pk_mul_f32 v[74:75], v[62:63], v[64:65] op_sel_hi:[0,1]
	v_pk_mul_f32 v[76:77], v[62:63], v[70:71] op_sel_hi:[0,1]
	v_pk_mul_f32 v[62:63], v[62:63], v[68:69] op_sel_hi:[0,1]
	v_bfe_u32 v59, v84, 16, 1
	v_bfe_u32 v3, v63, 16, 1
	v_lshl_add_u64 v[110:111], v[54:55], 0, v[4:5]
	v_add3_u32 v59, v84, v59, s46
	v_lshl_add_u64 v[84:85], v[48:49], 0, v[4:5]
	v_bfe_u32 v4, v62, 16, 1
	v_add3_u32 v3, v63, v3, s46
	v_bfe_u32 v63, v77, 16, 1
	v_lshrrev_b32_e32 v61, 16, v61
	v_add3_u32 v4, v62, v4, s46
	v_bfe_u32 v62, v76, 16, 1
	v_add3_u32 v63, v77, v63, s46
	v_and_or_b32 v80, v59, s47, v61
	v_bfe_u32 v53, v75, 16, 1
	v_bfe_u32 v59, v78, 16, 1
	v_bfe_u32 v61, v79, 16, 1
	v_add3_u32 v62, v76, v62, s46
	v_lshrrev_b32_e32 v63, 16, v63
	v_bfe_u32 v57, v74, 16, 1
	v_add3_u32 v53, v75, v53, s46
	v_add3_u32 v61, v79, v61, s46
	v_add3_u32 v59, v78, v59, s46
	v_lshrrev_b32_e32 v62, 16, v62
	v_and_or_b32 v75, v3, s47, v63
	v_or_b32_e32 v3, v51, v98
	v_add3_u32 v57, v74, v57, s46
	v_lshrrev_b32_e32 v59, 16, v59
	v_lshrrev_b32_e32 v61, 16, v61
	v_and_or_b32 v74, v4, s47, v62
	v_lshlrev_b32_e32 v4, 11, v3
	v_and_or_b32 v73, v53, s47, v61
	v_and_or_b32 v72, v57, s47, v59
	v_lshl_add_u64 v[62:63], v[54:55], 0, v[4:5]
	global_store_dwordx4 v[62:63], v[72:75], off
	s_waitcnt vmcnt(5)
	v_pk_mul_f32 v[62:63], v[60:61], v[66:67] op_sel_hi:[0,1]
	v_pk_mul_f32 v[64:65], v[60:61], v[64:65] op_sel_hi:[0,1]
	v_pk_mul_f32 v[66:67], v[60:61], v[70:71] op_sel_hi:[0,1]
	v_pk_mul_f32 v[60:61], v[60:61], v[68:69] op_sel_hi:[0,1]
	v_bfe_u32 v3, v61, 16, 1
	v_bfe_u32 v53, v60, 16, 1
	v_bfe_u32 v57, v65, 16, 1
	v_bfe_u32 v59, v64, 16, 1
	v_add3_u32 v59, v64, v59, s46
	v_add3_u32 v57, v65, v57, s46
	v_add3_u32 v53, v60, v53, s46
	v_add3_u32 v3, v61, v3, s46
	v_bfe_u32 v60, v62, 16, 1
	v_bfe_u32 v61, v63, 16, 1
	v_bfe_u32 v64, v66, 16, 1
	v_bfe_u32 v65, v67, 16, 1
	v_add3_u32 v65, v67, v65, s46
	v_add3_u32 v64, v66, v64, s46
	v_add3_u32 v61, v63, v61, s46
	v_add3_u32 v60, v62, v60, s46
	v_lshrrev_b32_e32 v60, 16, v60
	v_lshrrev_b32_e32 v61, 16, v61
	v_lshrrev_b32_e32 v62, 16, v64
	v_lshrrev_b32_e32 v63, 16, v65
	v_and_or_b32 v63, v3, s47, v63
	v_and_or_b32 v62, v53, s47, v62
	v_and_or_b32 v61, v57, s47, v61
	v_and_or_b32 v60, v59, s47, v60
	v_lshl_add_u64 v[64:65], v[48:49], 0, v[4:5]
	global_store_dwordx4 v[110:111], v[90:93], off
	global_store_dwordx4 v[84:85], v[80:83], off
	global_store_dwordx4 v[64:65], v[60:63], off
	ds_read2_b32 v[62:63], v97 offset0:49 offset1:57
	ds_read2_b32 v[64:65], v97 offset0:82 offset1:90
	ds_read2_b32 v[66:67], v97 offset0:115 offset1:123
	ds_read2_b32 v[68:69], v97 offset0:148 offset1:156
	ds_read2_b32 v[70:71], v97 offset0:181 offset1:189
	ds_read2_b32 v[72:73], v97 offset0:214 offset1:222
	ds_read2_b32 v[74:75], v97 offset0:247 offset1:255
	ds_read2_b32 v[76:77], v97 offset0:16 offset1:24
	s_waitcnt lgkmcnt(6)
	v_mov_b32_e32 v79, v64
	v_mov_b32_e32 v80, v62
	s_waitcnt lgkmcnt(5)
	v_mov_b32_e32 v81, v66
	s_waitcnt lgkmcnt(4)
	v_mov_b32_e32 v84, v68
	s_waitcnt lgkmcnt(0)
	v_mov_b32_e32 v78, v76
	v_mov_b32_e32 v85, v72
	v_mov_b32_e32 v88, v70
	v_mov_b32_e32 v89, v74
	s_waitcnt vmcnt(7)
	v_pk_mul_f32 v[60:61], v[58:59], v[78:79] op_sel_hi:[0,1]
	v_pk_mul_f32 v[82:83], v[58:59], v[80:81] op_sel_hi:[0,1]
	v_pk_mul_f32 v[86:87], v[58:59], v[84:85] op_sel_hi:[0,1]
	v_pk_mul_f32 v[58:59], v[58:59], v[88:89] op_sel_hi:[0,1]
	v_bfe_u32 v3, v59, 16, 1
	v_bfe_u32 v64, v87, 16, 1
	v_bfe_u32 v4, v58, 16, 1
	v_add3_u32 v3, v59, v3, s46
	v_bfe_u32 v59, v61, 16, 1
	v_bfe_u32 v62, v86, 16, 1
	v_add3_u32 v64, v87, v64, s46
	v_add3_u32 v4, v58, v4, s46
	v_bfe_u32 v58, v60, 16, 1
	v_add3_u32 v62, v86, v62, s46
	v_add3_u32 v59, v61, v59, s46
	v_lshrrev_b32_e32 v61, 16, v64
	v_bfe_u32 v53, v83, 16, 1
	v_bfe_u32 v57, v82, 16, 1
	v_add3_u32 v58, v60, v58, s46
	v_lshrrev_b32_e32 v60, 16, v62
	v_and_or_b32 v61, v3, s47, v61
	v_or_b32_e32 v3, v51, v99
	v_add3_u32 v57, v82, v57, s46
	v_add3_u32 v53, v83, v53, s46
	v_lshrrev_b32_e32 v58, 16, v58
	v_lshrrev_b32_e32 v59, 16, v59
	v_and_or_b32 v60, v4, s47, v60
	v_lshlrev_b32_e32 v4, 11, v3
	v_and_or_b32 v59, v53, s47, v59
	v_and_or_b32 v58, v57, s47, v58
	v_lshl_add_u64 v[82:83], v[54:55], 0, v[4:5]
	global_store_dwordx4 v[82:83], v[58:61], off
	v_mov_b32_e32 v66, v63
	v_mov_b32_e32 v72, v69
	s_waitcnt vmcnt(7)
	v_pk_mul_f32 v[58:59], v[56:57], v[78:79] op_sel_hi:[0,1]
	v_pk_mul_f32 v[60:61], v[56:57], v[80:81] op_sel_hi:[0,1]
	v_pk_mul_f32 v[78:79], v[56:57], v[84:85] op_sel_hi:[0,1]
	v_pk_mul_f32 v[56:57], v[56:57], v[88:89] op_sel_hi:[0,1]
	v_bfe_u32 v3, v57, 16, 1
	v_bfe_u32 v53, v56, 16, 1
	v_bfe_u32 v62, v61, 16, 1
	v_bfe_u32 v64, v60, 16, 1
	v_add3_u32 v60, v60, v64, s46
	v_add3_u32 v61, v61, v62, s46
	v_add3_u32 v53, v56, v53, s46
	v_add3_u32 v3, v57, v3, s46
	v_bfe_u32 v56, v58, 16, 1
	v_bfe_u32 v57, v59, 16, 1
	v_bfe_u32 v62, v78, 16, 1
	v_bfe_u32 v64, v79, 16, 1
	v_add3_u32 v64, v79, v64, s46
	v_add3_u32 v62, v78, v62, s46
	v_add3_u32 v57, v59, v57, s46
	v_add3_u32 v56, v58, v56, s46
	v_lshrrev_b32_e32 v56, 16, v56
	v_lshrrev_b32_e32 v57, 16, v57
	v_lshrrev_b32_e32 v58, 16, v62
	v_lshrrev_b32_e32 v59, 16, v64
	v_and_or_b32 v59, v3, s47, v59
	v_and_or_b32 v58, v53, s47, v58
	v_and_or_b32 v57, v61, s47, v57
	v_and_or_b32 v56, v60, s47, v56
	v_lshl_add_u64 v[60:61], v[48:49], 0, v[4:5]
	global_store_dwordx4 v[60:61], v[56:59], off
	v_mov_b32_e32 v64, v77
	v_mov_b32_e32 v74, v71
	s_waitcnt vmcnt(7)
	v_pk_mul_f32 v[58:59], v[52:53], v[66:67] op_sel_hi:[0,1]
	v_pk_mul_f32 v[56:57], v[52:53], v[64:65] op_sel_hi:[0,1]
	v_pk_mul_f32 v[60:61], v[52:53], v[72:73] op_sel_hi:[0,1]
	v_pk_mul_f32 v[52:53], v[52:53], v[74:75] op_sel_hi:[0,1]
	v_bfe_u32 v62, v59, 16, 1
	v_bfe_u32 v3, v53, 16, 1
	v_bfe_u32 v63, v58, 16, 1
	v_add3_u32 v62, v59, v62, s46
	v_bfe_u32 v59, v61, 16, 1
	v_bfe_u32 v4, v52, 16, 1
	v_add3_u32 v63, v58, v63, s46
	v_add3_u32 v3, v53, v3, s46
	v_bfe_u32 v53, v57, 16, 1
	v_bfe_u32 v58, v60, 16, 1
	v_add3_u32 v59, v61, v59, s46
	v_add3_u32 v4, v52, v4, s46
	v_bfe_u32 v52, v56, 16, 1
	v_add3_u32 v58, v60, v58, s46
	v_add3_u32 v53, v57, v53, s46
	v_lshrrev_b32_e32 v57, 16, v59
	v_add3_u32 v52, v56, v52, s46
	v_lshrrev_b32_e32 v56, 16, v58
	v_and_or_b32 v59, v3, s47, v57
	v_or_b32_e32 v3, v51, v100
	v_lshrrev_b32_e32 v52, 16, v52
	v_lshrrev_b32_e32 v53, 16, v53
	v_and_or_b32 v58, v4, s47, v56
	v_lshlrev_b32_e32 v4, 11, v3
	v_and_or_b32 v57, v62, s47, v53
	v_and_or_b32 v56, v63, s47, v52
	v_lshl_add_u64 v[52:53], v[54:55], 0, v[4:5]
	global_store_dwordx4 v[52:53], v[56:59], off
	s_waitcnt vmcnt(7)
	v_pk_mul_f32 v[52:53], v[50:51], v[64:65] op_sel_hi:[0,1]
	v_pk_mul_f32 v[54:55], v[50:51], v[66:67] op_sel_hi:[0,1]
	v_pk_mul_f32 v[56:57], v[50:51], v[72:73] op_sel_hi:[0,1]
	v_pk_mul_f32 v[50:51], v[50:51], v[74:75] op_sel_hi:[0,1]
	v_bfe_u32 v3, v51, 16, 1
	v_bfe_u32 v58, v50, 16, 1
	v_bfe_u32 v59, v55, 16, 1
	v_bfe_u32 v60, v54, 16, 1
	v_add3_u32 v54, v54, v60, s46
	v_add3_u32 v55, v55, v59, s46
	v_add3_u32 v50, v50, v58, s46
	v_add3_u32 v3, v51, v3, s46
	v_bfe_u32 v51, v52, 16, 1
	v_bfe_u32 v58, v53, 16, 1
	v_bfe_u32 v59, v56, 16, 1
	v_bfe_u32 v60, v57, 16, 1
	v_add3_u32 v57, v57, v60, s46
	v_add3_u32 v56, v56, v59, s46
	v_add3_u32 v53, v53, v58, s46
	v_add3_u32 v51, v52, v51, s46
	v_lshrrev_b32_e32 v58, 16, v51
	v_lshrrev_b32_e32 v51, 16, v53
	v_lshrrev_b32_e32 v52, 16, v56
	v_lshrrev_b32_e32 v53, 16, v57
	v_and_or_b32 v53, v3, s47, v53
	v_and_or_b32 v52, v50, s47, v52
	v_and_or_b32 v51, v55, s47, v51
	v_and_or_b32 v50, v54, s47, v58
	v_lshl_add_u64 v[48:49], v[48:49], 0, v[4:5]
	global_store_dwordx4 v[48:49], v[50:53], off
	s_waitcnt lgkmcnt(0)

.LBB0_1785:
	s_lshl_b32 s69, s64, 1
	s_lshl_b32 s70, s65, 1
	v_or_b32_e32 v56, s69, v1
	v_or_b32_e32 v57, s70, v0
	v_add_lshl_u32 v4, v56, v3, 10
	v_add_lshl_u32 v53, v57, v48, 10
	v_or_b32_e32 v52, v49, v4
	v_or_b32_e32 v4, v50, v53
	v_lshl_add_u64 v[54:55], v[4:5], 2, s[6:7]
	v_mov_b32_e32 v53, v5
	v_lshl_add_u64 v[52:53], v[52:53], 2, s[6:7]
	global_load_dword v126, v[54:55], off nt
	global_load_dword v127, v[52:53], off nt
	v_mad_u64_u32 v[52:53], s[72:73], v57, s40, v[2:3]
	v_mad_u64_u32 v[54:55], s[72:73], v56, s40, v[2:3]
	s_add_i32 s71, s69, 4
	s_add_i32 s72, s70, 4
	v_or_b32_e32 v56, s71, v1
	v_or_b32_e32 v57, s72, v0
	v_add_lshl_u32 v53, v57, v48, 10
	s_add_i32 s71, s69, 8
	s_add_i32 s65, s65, 16
	s_add_i32 s64, s64, 16
	s_add_i32 s68, s68, -16
	v_mov_b32_e32 v142, v52
	v_mov_b32_e32 v143, v54
	v_add_lshl_u32 v4, v56, v3, 10
	v_or_b32_e32 v52, v49, v4
	v_or_b32_e32 v4, v50, v53
	v_lshl_add_u64 v[54:55], v[4:5], 2, s[6:7]
	v_mov_b32_e32 v53, v5
	v_lshl_add_u64 v[52:53], v[52:53], 2, s[6:7]
	global_load_dword v128, v[54:55], off nt
	global_load_dword v129, v[52:53], off nt
	v_mad_u64_u32 v[52:53], s[72:73], v57, s40, v[2:3]
	v_mad_u64_u32 v[54:55], s[72:73], v56, s40, v[2:3]
	s_add_i32 s72, s70, 8
	v_or_b32_e32 v56, s71, v1
	v_or_b32_e32 v57, s72, v0
	v_add_lshl_u32 v53, v57, v48, 10
	s_add_i32 s71, s69, 12
	v_mov_b32_e32 v144, v52
	v_mov_b32_e32 v145, v54
	v_add_lshl_u32 v4, v56, v3, 10
	v_or_b32_e32 v52, v49, v4
	v_or_b32_e32 v4, v50, v53
	v_lshl_add_u64 v[54:55], v[4:5], 2, s[6:7]
	v_mov_b32_e32 v53, v5
	v_lshl_add_u64 v[52:53], v[52:53], 2, s[6:7]
	global_load_dword v130, v[54:55], off nt
	global_load_dword v131, v[52:53], off nt
	v_mad_u64_u32 v[52:53], s[72:73], v57, s40, v[2:3]
	v_mad_u64_u32 v[54:55], s[72:73], v56, s40, v[2:3]
	s_add_i32 s72, s70, 12
	v_or_b32_e32 v56, s71, v1
	v_or_b32_e32 v57, s72, v0
	v_add_lshl_u32 v53, v57, v48, 10
	s_add_i32 s71, s69, 16
	v_mov_b32_e32 v146, v52
	v_mov_b32_e32 v147, v54
	v_add_lshl_u32 v4, v56, v3, 10
	v_or_b32_e32 v52, v49, v4
	v_or_b32_e32 v4, v50, v53
	v_lshl_add_u64 v[54:55], v[4:5], 2, s[6:7]
	v_mov_b32_e32 v53, v5
	v_lshl_add_u64 v[52:53], v[52:53], 2, s[6:7]
	global_load_dword v132, v[54:55], off nt
	global_load_dword v133, v[52:53], off nt
	v_mad_u64_u32 v[52:53], s[72:73], v57, s40, v[2:3]
	v_mad_u64_u32 v[54:55], s[72:73], v56, s40, v[2:3]
	s_add_i32 s72, s70, 16
	v_or_b32_e32 v56, s71, v1
	v_or_b32_e32 v57, s72, v0
	v_add_lshl_u32 v53, v57, v48, 10
	s_add_i32 s71, s69, 20
	v_mov_b32_e32 v148, v52
	v_mov_b32_e32 v149, v54
	v_add_lshl_u32 v4, v56, v3, 10
	v_or_b32_e32 v52, v49, v4
	v_or_b32_e32 v4, v50, v53
	v_lshl_add_u64 v[54:55], v[4:5], 2, s[6:7]
	v_mov_b32_e32 v53, v5
	v_lshl_add_u64 v[52:53], v[52:53], 2, s[6:7]
	global_load_dword v134, v[54:55], off nt
	global_load_dword v135, v[52:53], off nt
	v_mad_u64_u32 v[52:53], s[72:73], v57, s40, v[2:3]
	v_mad_u64_u32 v[54:55], s[72:73], v56, s40, v[2:3]
	s_add_i32 s72, s70, 20
	v_or_b32_e32 v56, s71, v1
	v_or_b32_e32 v57, s72, v0
	v_add_lshl_u32 v53, v57, v48, 10
	s_add_i32 s71, s69, 24
	s_add_i32 s69, s69, 28
	v_mov_b32_e32 v150, v52
	v_mov_b32_e32 v151, v54
	v_add_lshl_u32 v4, v56, v3, 10
	v_or_b32_e32 v52, v49, v4
	v_or_b32_e32 v4, v50, v53
	v_lshl_add_u64 v[54:55], v[4:5], 2, s[6:7]
	v_mov_b32_e32 v53, v5
	v_lshl_add_u64 v[52:53], v[52:53], 2, s[6:7]
	global_load_dword v136, v[54:55], off nt
	global_load_dword v137, v[52:53], off nt
	v_mad_u64_u32 v[52:53], s[72:73], v57, s40, v[2:3]
	v_mad_u64_u32 v[54:55], s[72:73], v56, s40, v[2:3]
	s_add_i32 s72, s70, 24
	v_or_b32_e32 v56, s71, v1
	v_or_b32_e32 v57, s72, v0
	v_add_lshl_u32 v53, v57, v48, 10
	s_add_i32 s70, s70, 28
	s_cmp_lg_u32 s68, 0
	v_mov_b32_e32 v152, v52
	v_mov_b32_e32 v153, v54
	v_add_lshl_u32 v4, v56, v3, 10
	v_or_b32_e32 v52, v49, v4
	v_or_b32_e32 v4, v50, v53
	v_lshl_add_u64 v[54:55], v[4:5], 2, s[6:7]
	v_mov_b32_e32 v53, v5
	v_lshl_add_u64 v[52:53], v[52:53], 2, s[6:7]
	global_load_dword v138, v[54:55], off nt
	global_load_dword v139, v[52:53], off nt
	v_mad_u64_u32 v[52:53], s[72:73], v57, s40, v[2:3]
	v_mad_u64_u32 v[54:55], s[72:73], v56, s40, v[2:3]
	v_or_b32_e32 v56, s69, v1
	v_or_b32_e32 v57, s70, v0
	v_mov_b32_e32 v55, v5
	v_mov_b32_e32 v154, v52
	v_mov_b32_e32 v155, v54
	v_add_lshl_u32 v4, v56, v3, 10
	v_add_lshl_u32 v52, v57, v48, 10
	v_or_b32_e32 v54, v49, v4
	v_or_b32_e32 v4, v50, v52
	v_lshl_add_u64 v[52:53], v[4:5], 2, s[6:7]
	v_lshl_add_u64 v[54:55], v[54:55], 2, s[6:7]
	global_load_dword v140, v[52:53], off nt
	global_load_dword v141, v[54:55], off nt
	v_mad_u64_u32 v[52:53], s[70:71], v57, s40, v[2:3]
	v_mad_u64_u32 v[54:55], s[70:71], v56, s40, v[2:3]
	v_mov_b32_e32 v156, v52
	v_mov_b32_e32 v157, v54
	s_waitcnt vmcnt(15)
	ds_write_b32 v142, v126
	s_waitcnt vmcnt(14)
	ds_write_b32 v143, v127
	s_waitcnt vmcnt(13)
	ds_write_b32 v144, v128
	s_waitcnt vmcnt(12)
	ds_write_b32 v145, v129
	s_waitcnt vmcnt(11)
	ds_write_b32 v146, v130
	s_waitcnt vmcnt(10)
	ds_write_b32 v147, v131
	s_waitcnt vmcnt(9)
	ds_write_b32 v148, v132
	s_waitcnt vmcnt(8)
	ds_write_b32 v149, v133
	s_waitcnt vmcnt(7)
	ds_write_b32 v150, v134
	s_waitcnt vmcnt(6)
	ds_write_b32 v151, v135
	s_waitcnt vmcnt(5)
	ds_write_b32 v152, v136
	s_waitcnt vmcnt(4)
	ds_write_b32 v153, v137
	s_waitcnt vmcnt(3)
	ds_write_b32 v154, v138
	s_waitcnt vmcnt(2)
	ds_write_b32 v155, v139
	s_waitcnt vmcnt(1)
	ds_write_b32 v156, v140
	s_waitcnt vmcnt(0)
	ds_write_b32 v157, v141
	s_cbranch_scc1 .LBB0_1785
	s_waitcnt lgkmcnt(0)
	ds_read2_b32 v[56:57], v97 offset0:33 offset1:41
	ds_read2_b32 v[58:59], v97 offset0:66 offset1:74
	ds_read2_b32 v[60:61], v97 offset0:99 offset1:107
	ds_read2_b32 v[62:63], v97 offset1:8
	ds_read2_b32 v[64:65], v97 offset0:132 offset1:140
	ds_read2_b32 v[66:67], v97 offset0:165 offset1:173
	ds_read2_b32 v[68:69], v97 offset0:198 offset1:206
	ds_read2_b32 v[70:71], v97 offset0:231 offset1:239
	v_lshlrev_b32_e32 v4, 1, v48
	s_waitcnt lgkmcnt(4)
	v_bfe_u32 v3, v62, 16, 1
	v_lshl_add_u64 v[48:49], v[10:11], 0, v[4:5]
	v_add3_u32 v3, v62, v3, s46
	v_bfe_u32 v4, v56, 16, 1
	v_lshrrev_b32_e32 v3, 16, v3
	v_add3_u32 v4, v56, v4, s46
	v_and_or_b32 v52, v4, s47, v3
	v_bfe_u32 v3, v58, 16, 1
	v_add3_u32 v3, v58, v3, s46
	v_bfe_u32 v4, v60, 16, 1
	v_lshrrev_b32_e32 v3, 16, v3
	v_add3_u32 v4, v60, v4, s46
	v_and_or_b32 v53, v4, s47, v3
	s_waitcnt lgkmcnt(3)
	v_bfe_u32 v3, v64, 16, 1
	v_add3_u32 v3, v64, v3, s46
	s_waitcnt lgkmcnt(2)
	v_bfe_u32 v4, v66, 16, 1
	v_lshrrev_b32_e32 v3, 16, v3
	v_add3_u32 v4, v66, v4, s46
	v_and_or_b32 v54, v4, s47, v3
	s_waitcnt lgkmcnt(1)
	v_bfe_u32 v3, v68, 16, 1
	v_add3_u32 v3, v68, v3, s46
	s_waitcnt lgkmcnt(0)
	v_bfe_u32 v4, v70, 16, 1
	v_lshrrev_b32_e32 v3, 16, v3
	v_add3_u32 v4, v70, v4, s46
	v_and_or_b32 v55, v4, s47, v3
	v_or_b32_e32 v3, v51, v96
	v_lshlrev_b32_e32 v4, 9, v3
	v_bfe_u32 v3, v63, 16, 1
	v_lshl_add_u64 v[72:73], v[48:49], 0, v[4:5]
	v_add3_u32 v3, v63, v3, s46
	v_bfe_u32 v4, v57, 16, 1
	v_lshrrev_b32_e32 v3, 16, v3
	v_add3_u32 v4, v57, v4, s46
	global_store_dwordx4 v[72:73], v[52:55], off
	v_readlane_b32 s72, v255, 50
	v_readlane_b32 s70, v255, 48
	v_and_or_b32 v52, v4, s47, v3
	v_bfe_u32 v3, v59, 16, 1
	v_add3_u32 v3, v59, v3, s46
	v_bfe_u32 v4, v61, 16, 1
	v_lshrrev_b32_e32 v3, 16, v3
	v_add3_u32 v4, v61, v4, s46
	v_and_or_b32 v53, v4, s47, v3
	v_bfe_u32 v3, v65, 16, 1
	v_add3_u32 v3, v65, v3, s46
	v_bfe_u32 v4, v67, 16, 1
	v_lshrrev_b32_e32 v3, 16, v3
	v_add3_u32 v4, v67, v4, s46
	v_and_or_b32 v54, v4, s47, v3
	v_bfe_u32 v3, v69, 16, 1
	v_add3_u32 v3, v69, v3, s46
	v_bfe_u32 v4, v71, 16, 1
	v_lshrrev_b32_e32 v3, 16, v3
	v_add3_u32 v4, v71, v4, s46
	v_and_or_b32 v55, v4, s47, v3
	v_or_b32_e32 v3, v51, v98
	v_lshlrev_b32_e32 v4, 9, v3
	v_lshl_add_u64 v[56:57], v[48:49], 0, v[4:5]
	global_store_dwordx4 v[56:57], v[52:55], off
	ds_read2_b32 v[56:57], v97 offset0:49 offset1:57
	ds_read2_b32 v[58:59], v97 offset0:82 offset1:90
	ds_read2_b32 v[60:61], v97 offset0:115 offset1:123
	ds_read2_b32 v[62:63], v97 offset0:16 offset1:24
	ds_read2_b32 v[64:65], v97 offset0:148 offset1:156
	ds_read2_b32 v[66:67], v97 offset0:181 offset1:189
	ds_read2_b32 v[68:69], v97 offset0:214 offset1:222
	ds_read2_b32 v[70:71], v97 offset0:247 offset1:255
	s_waitcnt lgkmcnt(4)
	v_bfe_u32 v3, v62, 16, 1
	v_add3_u32 v3, v62, v3, s46
	v_bfe_u32 v4, v56, 16, 1
	v_lshrrev_b32_e32 v3, 16, v3
	v_add3_u32 v4, v56, v4, s46
	v_and_or_b32 v52, v4, s47, v3
	v_bfe_u32 v3, v58, 16, 1
	v_add3_u32 v3, v58, v3, s46
	v_bfe_u32 v4, v60, 16, 1
	v_lshrrev_b32_e32 v3, 16, v3
	v_add3_u32 v4, v60, v4, s46
	v_and_or_b32 v53, v4, s47, v3
	s_waitcnt lgkmcnt(3)
	v_bfe_u32 v3, v64, 16, 1
	v_add3_u32 v3, v64, v3, s46
	s_waitcnt lgkmcnt(2)
	v_bfe_u32 v4, v66, 16, 1
	v_lshrrev_b32_e32 v3, 16, v3
	v_add3_u32 v4, v66, v4, s46
	v_and_or_b32 v54, v4, s47, v3
	s_waitcnt lgkmcnt(1)
	v_bfe_u32 v3, v68, 16, 1
	v_add3_u32 v3, v68, v3, s46
	s_waitcnt lgkmcnt(0)
	v_bfe_u32 v4, v70, 16, 1
	v_lshrrev_b32_e32 v3, 16, v3
	v_add3_u32 v4, v70, v4, s46
	v_and_or_b32 v55, v4, s47, v3
	v_or_b32_e32 v3, v51, v99
	v_lshlrev_b32_e32 v4, 9, v3
	v_bfe_u32 v3, v63, 16, 1
	v_lshl_add_u64 v[72:73], v[48:49], 0, v[4:5]
	v_add3_u32 v3, v63, v3, s46
	v_bfe_u32 v4, v57, 16, 1
	v_lshrrev_b32_e32 v3, 16, v3
	v_add3_u32 v4, v57, v4, s46
	global_store_dwordx4 v[72:73], v[52:55], off
	v_readlane_b32 s73, v255, 51
	v_readlane_b32 s71, v255, 49
	v_and_or_b32 v52, v4, s47, v3
	v_bfe_u32 v3, v59, 16, 1
	v_add3_u32 v3, v59, v3, s46
	v_bfe_u32 v4, v61, 16, 1
	v_lshrrev_b32_e32 v3, 16, v3
	v_add3_u32 v4, v61, v4, s46
	v_and_or_b32 v53, v4, s47, v3
	v_bfe_u32 v3, v65, 16, 1
	v_add3_u32 v3, v65, v3, s46
	v_bfe_u32 v4, v67, 16, 1
	v_lshrrev_b32_e32 v3, 16, v3
	v_add3_u32 v4, v67, v4, s46
	v_and_or_b32 v54, v4, s47, v3
	v_bfe_u32 v3, v69, 16, 1
	v_add3_u32 v3, v69, v3, s46
	v_bfe_u32 v4, v71, 16, 1
	v_lshrrev_b32_e32 v3, 16, v3
	v_add3_u32 v4, v71, v4, s46
	v_and_or_b32 v55, v4, s47, v3
	v_or_b32_e32 v3, v51, v100
	v_lshlrev_b32_e32 v4, 9, v3
	v_lshl_add_u64 v[48:49], v[48:49], 0, v[4:5]
	global_store_dwordx4 v[48:49], v[52:55], off
	s_waitcnt lgkmcnt(0)

.LBB0_1790:
	s_lshl_b32 s69, s64, 1
	s_lshl_b32 s70, s65, 1
	v_or_b32_e32 v56, s69, v1
	v_or_b32_e32 v57, s70, v0
	v_add_lshl_u32 v4, v56, v3, 10
	v_add_lshl_u32 v53, v57, v48, 10
	v_or_b32_e32 v52, v49, v4
	v_or_b32_e32 v4, v50, v53
	v_lshl_add_u64 v[54:55], v[4:5], 2, s[4:5]
	v_mov_b32_e32 v53, v5
	v_lshl_add_u64 v[52:53], v[52:53], 2, s[4:5]
	global_load_dword v126, v[54:55], off nt
	global_load_dword v127, v[52:53], off nt
	v_mad_u64_u32 v[52:53], s[72:73], v57, s40, v[2:3]
	v_mad_u64_u32 v[54:55], s[72:73], v56, s40, v[2:3]
	s_add_i32 s71, s69, 4
	s_add_i32 s72, s70, 4
	v_or_b32_e32 v56, s71, v1
	v_or_b32_e32 v57, s72, v0
	v_add_lshl_u32 v53, v57, v48, 10
	s_add_i32 s71, s69, 8
	s_add_i32 s65, s65, 16
	s_add_i32 s64, s64, 16
	s_add_i32 s68, s68, -16
	v_mov_b32_e32 v142, v52
	v_mov_b32_e32 v143, v54
	v_add_lshl_u32 v4, v56, v3, 10
	v_or_b32_e32 v52, v49, v4
	v_or_b32_e32 v4, v50, v53
	v_lshl_add_u64 v[54:55], v[4:5], 2, s[4:5]
	v_mov_b32_e32 v53, v5
	v_lshl_add_u64 v[52:53], v[52:53], 2, s[4:5]
	global_load_dword v128, v[54:55], off nt
	global_load_dword v129, v[52:53], off nt
	v_mad_u64_u32 v[52:53], s[72:73], v57, s40, v[2:3]
	v_mad_u64_u32 v[54:55], s[72:73], v56, s40, v[2:3]
	s_add_i32 s72, s70, 8
	v_or_b32_e32 v56, s71, v1
	v_or_b32_e32 v57, s72, v0
	v_add_lshl_u32 v53, v57, v48, 10
	s_add_i32 s71, s69, 12
	v_mov_b32_e32 v144, v52
	v_mov_b32_e32 v145, v54
	v_add_lshl_u32 v4, v56, v3, 10
	v_or_b32_e32 v52, v49, v4
	v_or_b32_e32 v4, v50, v53
	v_lshl_add_u64 v[54:55], v[4:5], 2, s[4:5]
	v_mov_b32_e32 v53, v5
	v_lshl_add_u64 v[52:53], v[52:53], 2, s[4:5]
	global_load_dword v130, v[54:55], off nt
	global_load_dword v131, v[52:53], off nt
	v_mad_u64_u32 v[52:53], s[72:73], v57, s40, v[2:3]
	v_mad_u64_u32 v[54:55], s[72:73], v56, s40, v[2:3]
	s_add_i32 s72, s70, 12
	v_or_b32_e32 v56, s71, v1
	v_or_b32_e32 v57, s72, v0
	v_add_lshl_u32 v53, v57, v48, 10
	s_add_i32 s71, s69, 16
	v_mov_b32_e32 v146, v52
	v_mov_b32_e32 v147, v54
	v_add_lshl_u32 v4, v56, v3, 10
	v_or_b32_e32 v52, v49, v4
	v_or_b32_e32 v4, v50, v53
	v_lshl_add_u64 v[54:55], v[4:5], 2, s[4:5]
	v_mov_b32_e32 v53, v5
	v_lshl_add_u64 v[52:53], v[52:53], 2, s[4:5]
	global_load_dword v132, v[54:55], off nt
	global_load_dword v133, v[52:53], off nt
	v_mad_u64_u32 v[52:53], s[72:73], v57, s40, v[2:3]
	v_mad_u64_u32 v[54:55], s[72:73], v56, s40, v[2:3]
	s_add_i32 s72, s70, 16
	v_or_b32_e32 v56, s71, v1
	v_or_b32_e32 v57, s72, v0
	v_add_lshl_u32 v53, v57, v48, 10
	s_add_i32 s71, s69, 20
	v_mov_b32_e32 v148, v52
	v_mov_b32_e32 v149, v54
	v_add_lshl_u32 v4, v56, v3, 10
	v_or_b32_e32 v52, v49, v4
	v_or_b32_e32 v4, v50, v53
	v_lshl_add_u64 v[54:55], v[4:5], 2, s[4:5]
	v_mov_b32_e32 v53, v5
	v_lshl_add_u64 v[52:53], v[52:53], 2, s[4:5]
	global_load_dword v134, v[54:55], off nt
	global_load_dword v135, v[52:53], off nt
	v_mad_u64_u32 v[52:53], s[72:73], v57, s40, v[2:3]
	v_mad_u64_u32 v[54:55], s[72:73], v56, s40, v[2:3]
	s_add_i32 s72, s70, 20
	v_or_b32_e32 v56, s71, v1
	v_or_b32_e32 v57, s72, v0
	v_add_lshl_u32 v53, v57, v48, 10
	s_add_i32 s71, s69, 24
	s_add_i32 s69, s69, 28
	v_mov_b32_e32 v150, v52
	v_mov_b32_e32 v151, v54
	v_add_lshl_u32 v4, v56, v3, 10
	v_or_b32_e32 v52, v49, v4
	v_or_b32_e32 v4, v50, v53
	v_lshl_add_u64 v[54:55], v[4:5], 2, s[4:5]
	v_mov_b32_e32 v53, v5
	v_lshl_add_u64 v[52:53], v[52:53], 2, s[4:5]
	global_load_dword v136, v[54:55], off nt
	global_load_dword v137, v[52:53], off nt
	v_mad_u64_u32 v[52:53], s[72:73], v57, s40, v[2:3]
	v_mad_u64_u32 v[54:55], s[72:73], v56, s40, v[2:3]
	s_add_i32 s72, s70, 24
	v_or_b32_e32 v56, s71, v1
	v_or_b32_e32 v57, s72, v0
	v_add_lshl_u32 v53, v57, v48, 10
	s_add_i32 s70, s70, 28
	s_cmp_lg_u32 s68, 0
	v_mov_b32_e32 v152, v52
	v_mov_b32_e32 v153, v54
	v_add_lshl_u32 v4, v56, v3, 10
	v_or_b32_e32 v52, v49, v4
	v_or_b32_e32 v4, v50, v53
	v_lshl_add_u64 v[54:55], v[4:5], 2, s[4:5]
	v_mov_b32_e32 v53, v5
	v_lshl_add_u64 v[52:53], v[52:53], 2, s[4:5]
	global_load_dword v138, v[54:55], off nt
	global_load_dword v139, v[52:53], off nt
	v_mad_u64_u32 v[52:53], s[72:73], v57, s40, v[2:3]
	v_mad_u64_u32 v[54:55], s[72:73], v56, s40, v[2:3]
	v_or_b32_e32 v56, s69, v1
	v_or_b32_e32 v57, s70, v0
	v_mov_b32_e32 v55, v5
	v_mov_b32_e32 v154, v52
	v_mov_b32_e32 v155, v54
	v_add_lshl_u32 v4, v56, v3, 10
	v_add_lshl_u32 v52, v57, v48, 10
	v_or_b32_e32 v54, v49, v4
	v_or_b32_e32 v4, v50, v52
	v_lshl_add_u64 v[52:53], v[4:5], 2, s[4:5]
	v_lshl_add_u64 v[54:55], v[54:55], 2, s[4:5]
	global_load_dword v140, v[52:53], off nt
	global_load_dword v141, v[54:55], off nt
	v_mad_u64_u32 v[52:53], s[70:71], v57, s40, v[2:3]
	v_mad_u64_u32 v[54:55], s[70:71], v56, s40, v[2:3]
	v_mov_b32_e32 v156, v52
	v_mov_b32_e32 v157, v54
	s_waitcnt vmcnt(15)
	ds_write_b32 v142, v126
	s_waitcnt vmcnt(14)
	ds_write_b32 v143, v127
	s_waitcnt vmcnt(13)
	ds_write_b32 v144, v128
	s_waitcnt vmcnt(12)
	ds_write_b32 v145, v129
	s_waitcnt vmcnt(11)
	ds_write_b32 v146, v130
	s_waitcnt vmcnt(10)
	ds_write_b32 v147, v131
	s_waitcnt vmcnt(9)
	ds_write_b32 v148, v132
	s_waitcnt vmcnt(8)
	ds_write_b32 v149, v133
	s_waitcnt vmcnt(7)
	ds_write_b32 v150, v134
	s_waitcnt vmcnt(6)
	ds_write_b32 v151, v135
	s_waitcnt vmcnt(5)
	ds_write_b32 v152, v136
	s_waitcnt vmcnt(4)
	ds_write_b32 v153, v137
	s_waitcnt vmcnt(3)
	ds_write_b32 v154, v138
	s_waitcnt vmcnt(2)
	ds_write_b32 v155, v139
	s_waitcnt vmcnt(1)
	ds_write_b32 v156, v140
	s_waitcnt vmcnt(0)
	ds_write_b32 v157, v141
	s_cbranch_scc1 .LBB0_1790
	s_waitcnt lgkmcnt(0)
	ds_read2_b32 v[56:57], v97 offset0:33 offset1:41
	ds_read2_b32 v[58:59], v97 offset0:66 offset1:74
	ds_read2_b32 v[60:61], v97 offset0:99 offset1:107
	ds_read2_b32 v[62:63], v97 offset1:8
	ds_read2_b32 v[64:65], v97 offset0:132 offset1:140
	ds_read2_b32 v[66:67], v97 offset0:165 offset1:173
	ds_read2_b32 v[68:69], v97 offset0:198 offset1:206
	ds_read2_b32 v[70:71], v97 offset0:231 offset1:239
	v_lshlrev_b32_e32 v4, 1, v48
	s_waitcnt lgkmcnt(4)
	v_bfe_u32 v3, v62, 16, 1
	v_lshl_add_u64 v[48:49], v[12:13], 0, v[4:5]
	v_add3_u32 v3, v62, v3, s46
	v_bfe_u32 v4, v56, 16, 1
	v_lshrrev_b32_e32 v3, 16, v3
	v_add3_u32 v4, v56, v4, s46
	v_and_or_b32 v52, v4, s47, v3
	v_bfe_u32 v3, v58, 16, 1
	v_add3_u32 v3, v58, v3, s46
	v_bfe_u32 v4, v60, 16, 1
	v_lshrrev_b32_e32 v3, 16, v3
	v_add3_u32 v4, v60, v4, s46
	v_and_or_b32 v53, v4, s47, v3
	s_waitcnt lgkmcnt(3)
	v_bfe_u32 v3, v64, 16, 1
	v_add3_u32 v3, v64, v3, s46
	s_waitcnt lgkmcnt(2)
	v_bfe_u32 v4, v66, 16, 1
	v_lshrrev_b32_e32 v3, 16, v3
	v_add3_u32 v4, v66, v4, s46
	v_and_or_b32 v54, v4, s47, v3
	s_waitcnt lgkmcnt(1)
	v_bfe_u32 v3, v68, 16, 1
	v_add3_u32 v3, v68, v3, s46
	s_waitcnt lgkmcnt(0)
	v_bfe_u32 v4, v70, 16, 1
	v_lshrrev_b32_e32 v3, 16, v3
	v_add3_u32 v4, v70, v4, s46
	v_and_or_b32 v55, v4, s47, v3
	v_or_b32_e32 v3, v51, v96
	v_lshlrev_b32_e32 v4, 10, v3
	v_bfe_u32 v3, v63, 16, 1
	v_lshl_add_u64 v[72:73], v[48:49], 0, v[4:5]
	v_add3_u32 v3, v63, v3, s46
	v_bfe_u32 v4, v57, 16, 1
	v_lshrrev_b32_e32 v3, 16, v3
	v_add3_u32 v4, v57, v4, s46
	global_store_dwordx4 v[72:73], v[52:55], off
	v_readlane_b32 s72, v255, 50
	v_readlane_b32 s70, v255, 48
	v_and_or_b32 v52, v4, s47, v3
	v_bfe_u32 v3, v59, 16, 1
	v_add3_u32 v3, v59, v3, s46
	v_bfe_u32 v4, v61, 16, 1
	v_lshrrev_b32_e32 v3, 16, v3
	v_add3_u32 v4, v61, v4, s46
	v_and_or_b32 v53, v4, s47, v3
	v_bfe_u32 v3, v65, 16, 1
	v_add3_u32 v3, v65, v3, s46
	v_bfe_u32 v4, v67, 16, 1
	v_lshrrev_b32_e32 v3, 16, v3
	v_add3_u32 v4, v67, v4, s46
	v_and_or_b32 v54, v4, s47, v3
	v_bfe_u32 v3, v69, 16, 1
	v_add3_u32 v3, v69, v3, s46
	v_bfe_u32 v4, v71, 16, 1
	v_lshrrev_b32_e32 v3, 16, v3
	v_add3_u32 v4, v71, v4, s46
	v_and_or_b32 v55, v4, s47, v3
	v_or_b32_e32 v3, v51, v98
	v_lshlrev_b32_e32 v4, 10, v3
	v_lshl_add_u64 v[56:57], v[48:49], 0, v[4:5]
	global_store_dwordx4 v[56:57], v[52:55], off
	ds_read2_b32 v[56:57], v97 offset0:49 offset1:57
	ds_read2_b32 v[58:59], v97 offset0:82 offset1:90
	ds_read2_b32 v[60:61], v97 offset0:115 offset1:123
	ds_read2_b32 v[62:63], v97 offset0:16 offset1:24
	ds_read2_b32 v[64:65], v97 offset0:148 offset1:156
	ds_read2_b32 v[66:67], v97 offset0:181 offset1:189
	ds_read2_b32 v[68:69], v97 offset0:214 offset1:222
	ds_read2_b32 v[70:71], v97 offset0:247 offset1:255
	s_waitcnt lgkmcnt(4)
	v_bfe_u32 v3, v62, 16, 1
	v_add3_u32 v3, v62, v3, s46
	v_bfe_u32 v4, v56, 16, 1
	v_lshrrev_b32_e32 v3, 16, v3
	v_add3_u32 v4, v56, v4, s46
	v_and_or_b32 v52, v4, s47, v3
	v_bfe_u32 v3, v58, 16, 1
	v_add3_u32 v3, v58, v3, s46
	v_bfe_u32 v4, v60, 16, 1
	v_lshrrev_b32_e32 v3, 16, v3
	v_add3_u32 v4, v60, v4, s46
	v_and_or_b32 v53, v4, s47, v3
	s_waitcnt lgkmcnt(3)
	v_bfe_u32 v3, v64, 16, 1
	v_add3_u32 v3, v64, v3, s46
	s_waitcnt lgkmcnt(2)
	v_bfe_u32 v4, v66, 16, 1
	v_lshrrev_b32_e32 v3, 16, v3
	v_add3_u32 v4, v66, v4, s46
	v_and_or_b32 v54, v4, s47, v3
	s_waitcnt lgkmcnt(1)
	v_bfe_u32 v3, v68, 16, 1
	v_add3_u32 v3, v68, v3, s46
	s_waitcnt lgkmcnt(0)
	v_bfe_u32 v4, v70, 16, 1
	v_lshrrev_b32_e32 v3, 16, v3
	v_add3_u32 v4, v70, v4, s46
	v_and_or_b32 v55, v4, s47, v3
	v_or_b32_e32 v3, v51, v99
	v_lshlrev_b32_e32 v4, 10, v3
	v_bfe_u32 v3, v63, 16, 1
	v_lshl_add_u64 v[72:73], v[48:49], 0, v[4:5]
	v_add3_u32 v3, v63, v3, s46
	v_bfe_u32 v4, v57, 16, 1
	v_lshrrev_b32_e32 v3, 16, v3
	v_add3_u32 v4, v57, v4, s46
	global_store_dwordx4 v[72:73], v[52:55], off
	v_readlane_b32 s73, v255, 51
	v_readlane_b32 s71, v255, 49
	v_and_or_b32 v52, v4, s47, v3
	v_bfe_u32 v3, v59, 16, 1
	v_add3_u32 v3, v59, v3, s46
	v_bfe_u32 v4, v61, 16, 1
	v_lshrrev_b32_e32 v3, 16, v3
	v_add3_u32 v4, v61, v4, s46
	v_and_or_b32 v53, v4, s47, v3
	v_bfe_u32 v3, v65, 16, 1
	v_add3_u32 v3, v65, v3, s46
	v_bfe_u32 v4, v67, 16, 1
	v_lshrrev_b32_e32 v3, 16, v3
	v_add3_u32 v4, v67, v4, s46
	v_and_or_b32 v54, v4, s47, v3
	v_bfe_u32 v3, v69, 16, 1
	v_add3_u32 v3, v69, v3, s46
	v_bfe_u32 v4, v71, 16, 1
	v_lshrrev_b32_e32 v3, 16, v3
	v_add3_u32 v4, v71, v4, s46
	v_and_or_b32 v55, v4, s47, v3
	v_or_b32_e32 v3, v51, v100
	v_lshlrev_b32_e32 v4, 10, v3
	v_lshl_add_u64 v[48:49], v[48:49], 0, v[4:5]
	global_store_dwordx4 v[48:49], v[52:55], off
	s_waitcnt lgkmcnt(0)

.LBB0_1795:
	s_lshl_b32 s68, s11, 1
	s_lshl_b32 s65, s10, 1
	v_or_b32_e32 v50, s68, v4
	v_or_b32_e32 v52, s65, v3
	v_mad_u64_u32 v[50:51], s[70:71], v50, s67, v[48:49]
	v_mad_u64_u32 v[52:53], s[70:71], v52, s67, v[48:49]
	global_load_dword v126, v[50:51], off nt
	global_load_dword v127, v[52:53], off nt
	v_or_b32_e32 v54, s65, v1
	v_or_b32_e32 v55, s68, v0
	v_mad_u64_u32 v[50:51], s[70:71], v55, s40, v[2:3]
	v_mad_u64_u32 v[52:53], s[70:71], v54, s40, v[2:3]
	s_add_i32 s70, s68, 4
	s_add_i32 s69, s65, 4
	v_or_b32_e32 v55, s70, v0
	v_or_b32_e32 v54, s69, v1
	s_add_i32 s11, s11, 16
	s_add_i32 s10, s10, 16
	s_add_i32 s64, s64, -16
	v_mov_b32_e32 v142, v50
	v_mov_b32_e32 v143, v52
	v_or_b32_e32 v50, s70, v4
	v_or_b32_e32 v52, s69, v3
	v_mad_u64_u32 v[50:51], s[70:71], v50, s67, v[48:49]
	v_mad_u64_u32 v[52:53], s[70:71], v52, s67, v[48:49]
	global_load_dword v128, v[50:51], off nt
	global_load_dword v129, v[52:53], off nt
	v_mad_u64_u32 v[50:51], s[70:71], v55, s40, v[2:3]
	v_mad_u64_u32 v[52:53], s[70:71], v54, s40, v[2:3]
	s_add_i32 s70, s68, 8
	s_add_i32 s69, s65, 8
	v_or_b32_e32 v55, s70, v0
	v_or_b32_e32 v54, s69, v1
	v_mov_b32_e32 v144, v50
	v_mov_b32_e32 v145, v52
	v_or_b32_e32 v50, s70, v4
	v_or_b32_e32 v52, s69, v3
	v_mad_u64_u32 v[50:51], s[70:71], v50, s67, v[48:49]
	v_mad_u64_u32 v[52:53], s[70:71], v52, s67, v[48:49]
	global_load_dword v130, v[50:51], off nt
	global_load_dword v131, v[52:53], off nt
	v_mad_u64_u32 v[50:51], s[70:71], v55, s40, v[2:3]
	v_mad_u64_u32 v[52:53], s[70:71], v54, s40, v[2:3]
	s_add_i32 s70, s68, 12
	s_add_i32 s69, s65, 12
	v_or_b32_e32 v55, s70, v0
	v_or_b32_e32 v54, s69, v1
	v_mov_b32_e32 v146, v50
	v_mov_b32_e32 v147, v52
	v_or_b32_e32 v50, s70, v4
	v_or_b32_e32 v52, s69, v3
	v_mad_u64_u32 v[50:51], s[70:71], v50, s67, v[48:49]
	v_mad_u64_u32 v[52:53], s[70:71], v52, s67, v[48:49]
	global_load_dword v132, v[50:51], off nt
	global_load_dword v133, v[52:53], off nt
	v_mad_u64_u32 v[50:51], s[70:71], v55, s40, v[2:3]
	v_mad_u64_u32 v[52:53], s[70:71], v54, s40, v[2:3]
	s_add_i32 s70, s68, 16
	s_add_i32 s69, s65, 16
	v_or_b32_e32 v55, s70, v0
	v_or_b32_e32 v54, s69, v1
	v_mov_b32_e32 v148, v50
	v_mov_b32_e32 v149, v52
	v_or_b32_e32 v50, s70, v4
	v_or_b32_e32 v52, s69, v3
	v_mad_u64_u32 v[50:51], s[70:71], v50, s67, v[48:49]
	v_mad_u64_u32 v[52:53], s[70:71], v52, s67, v[48:49]
	global_load_dword v134, v[50:51], off nt
	global_load_dword v135, v[52:53], off nt
	v_mad_u64_u32 v[50:51], s[70:71], v55, s40, v[2:3]
	v_mad_u64_u32 v[52:53], s[70:71], v54, s40, v[2:3]
	s_add_i32 s70, s68, 20
	s_add_i32 s69, s65, 20
	v_or_b32_e32 v55, s70, v0
	v_or_b32_e32 v54, s69, v1
	v_mov_b32_e32 v150, v50
	v_mov_b32_e32 v151, v52
	v_or_b32_e32 v50, s70, v4
	v_or_b32_e32 v52, s69, v3
	v_mad_u64_u32 v[50:51], s[70:71], v50, s67, v[48:49]
	v_mad_u64_u32 v[52:53], s[70:71], v52, s67, v[48:49]
	global_load_dword v136, v[50:51], off nt
	global_load_dword v137, v[52:53], off nt
	v_mad_u64_u32 v[50:51], s[70:71], v55, s40, v[2:3]
	v_mad_u64_u32 v[52:53], s[70:71], v54, s40, v[2:3]
	s_add_i32 s70, s68, 24
	s_add_i32 s69, s65, 24
	v_or_b32_e32 v55, s70, v0
	v_or_b32_e32 v54, s69, v1
	s_add_i32 s68, s68, 28
	s_add_i32 s65, s65, 28
	s_cmp_lg_u32 s64, 0
	v_mov_b32_e32 v152, v50
	v_mov_b32_e32 v153, v52
	v_or_b32_e32 v50, s70, v4
	v_or_b32_e32 v52, s69, v3
	v_mad_u64_u32 v[50:51], s[70:71], v50, s67, v[48:49]
	v_mad_u64_u32 v[52:53], s[70:71], v52, s67, v[48:49]
	global_load_dword v138, v[50:51], off nt
	global_load_dword v139, v[52:53], off nt
	v_mad_u64_u32 v[50:51], s[70:71], v55, s40, v[2:3]
	v_mad_u64_u32 v[52:53], s[70:71], v54, s40, v[2:3]
	v_or_b32_e32 v55, s68, v0
	v_or_b32_e32 v54, s65, v1
	v_mov_b32_e32 v154, v50
	v_mov_b32_e32 v155, v52
	v_or_b32_e32 v50, s68, v4
	v_or_b32_e32 v52, s65, v3
	v_mad_u64_u32 v[50:51], s[68:69], v50, s67, v[48:49]
	v_mad_u64_u32 v[52:53], s[68:69], v52, s67, v[48:49]
	global_load_dword v140, v[50:51], off nt
	global_load_dword v141, v[52:53], off nt
	v_mad_u64_u32 v[50:51], s[68:69], v55, s40, v[2:3]
	v_mad_u64_u32 v[52:53], s[68:69], v54, s40, v[2:3]
	v_mov_b32_e32 v156, v50
	v_mov_b32_e32 v157, v52
	s_waitcnt vmcnt(15)
	ds_write_b32 v142, v126
	s_waitcnt vmcnt(14)
	ds_write_b32 v143, v127
	s_waitcnt vmcnt(13)
	ds_write_b32 v144, v128
	s_waitcnt vmcnt(12)
	ds_write_b32 v145, v129
	s_waitcnt vmcnt(11)
	ds_write_b32 v146, v130
	s_waitcnt vmcnt(10)
	ds_write_b32 v147, v131
	s_waitcnt vmcnt(9)
	ds_write_b32 v148, v132
	s_waitcnt vmcnt(8)
	ds_write_b32 v149, v133
	s_waitcnt vmcnt(7)
	ds_write_b32 v150, v134
	s_waitcnt vmcnt(6)
	ds_write_b32 v151, v135
	s_waitcnt vmcnt(5)
	ds_write_b32 v152, v136
	s_waitcnt vmcnt(4)
	ds_write_b32 v153, v137
	s_waitcnt vmcnt(3)
	ds_write_b32 v154, v138
	s_waitcnt vmcnt(2)
	ds_write_b32 v155, v139
	s_waitcnt vmcnt(1)
	ds_write_b32 v156, v140
	s_waitcnt vmcnt(0)
	ds_write_b32 v157, v141
	s_cbranch_scc1 .LBB0_1795
	v_or_b32_e32 v4, v101, v60
	v_cndmask_b32_e64 v3, 0, 1, s[96:97]
	v_mov_b32_e32 v71, 1.0
	v_cmp_ne_u32_e64 s[10:11], 1, v3
	s_andn2_b64 vcc, exec, s[96:97]
	v_lshlrev_b32_e32 v3, 2, v4
	v_mov_b32_e32 v70, 1.0
	s_cbranch_vccnz .LBB0_1798
	global_load_dword v70, v3, s[72:73]

.LBB0_1816:
	s_lshl_b32 s64, s11, 1
	s_lshl_b32 s37, s10, 1
	v_or_b32_e32 v50, s64, v4
	v_or_b32_e32 v52, s37, v3
	v_mad_u64_u32 v[50:51], s[68:69], v50, s67, v[48:49]
	v_mad_u64_u32 v[52:53], s[68:69], v52, s67, v[48:49]
	global_load_dword v126, v[50:51], off nt
	global_load_dword v127, v[52:53], off nt
	v_or_b32_e32 v54, s37, v1
	v_or_b32_e32 v55, s64, v0
	v_mad_u64_u32 v[50:51], s[68:69], v55, s40, v[2:3]
	v_mad_u64_u32 v[52:53], s[68:69], v54, s40, v[2:3]
	s_add_i32 s68, s64, 4
	s_add_i32 s65, s37, 4
	v_or_b32_e32 v55, s68, v0
	v_or_b32_e32 v54, s65, v1
	s_add_i32 s11, s11, 16
	s_add_i32 s10, s10, 16
	s_add_i32 s36, s36, -16
	v_mov_b32_e32 v142, v50
	v_mov_b32_e32 v143, v52
	v_or_b32_e32 v50, s68, v4
	v_or_b32_e32 v52, s65, v3
	v_mad_u64_u32 v[50:51], s[68:69], v50, s67, v[48:49]
	v_mad_u64_u32 v[52:53], s[68:69], v52, s67, v[48:49]
	global_load_dword v128, v[50:51], off nt
	global_load_dword v129, v[52:53], off nt
	v_mad_u64_u32 v[50:51], s[68:69], v55, s40, v[2:3]
	v_mad_u64_u32 v[52:53], s[68:69], v54, s40, v[2:3]
	s_add_i32 s68, s64, 8
	s_add_i32 s65, s37, 8
	v_or_b32_e32 v55, s68, v0
	v_or_b32_e32 v54, s65, v1
	v_mov_b32_e32 v144, v50
	v_mov_b32_e32 v145, v52
	v_or_b32_e32 v50, s68, v4
	v_or_b32_e32 v52, s65, v3
	v_mad_u64_u32 v[50:51], s[68:69], v50, s67, v[48:49]
	v_mad_u64_u32 v[52:53], s[68:69], v52, s67, v[48:49]
	global_load_dword v130, v[50:51], off nt
	global_load_dword v131, v[52:53], off nt
	v_mad_u64_u32 v[50:51], s[68:69], v55, s40, v[2:3]
	v_mad_u64_u32 v[52:53], s[68:69], v54, s40, v[2:3]
	s_add_i32 s68, s64, 12
	s_add_i32 s65, s37, 12
	v_or_b32_e32 v55, s68, v0
	v_or_b32_e32 v54, s65, v1
	v_mov_b32_e32 v146, v50
	v_mov_b32_e32 v147, v52
	v_or_b32_e32 v50, s68, v4
	v_or_b32_e32 v52, s65, v3
	v_mad_u64_u32 v[50:51], s[68:69], v50, s67, v[48:49]
	v_mad_u64_u32 v[52:53], s[68:69], v52, s67, v[48:49]
	global_load_dword v132, v[50:51], off nt
	global_load_dword v133, v[52:53], off nt
	v_mad_u64_u32 v[50:51], s[68:69], v55, s40, v[2:3]
	v_mad_u64_u32 v[52:53], s[68:69], v54, s40, v[2:3]
	s_add_i32 s68, s64, 16
	s_add_i32 s65, s37, 16
	v_or_b32_e32 v55, s68, v0
	v_or_b32_e32 v54, s65, v1
	v_mov_b32_e32 v148, v50
	v_mov_b32_e32 v149, v52
	v_or_b32_e32 v50, s68, v4
	v_or_b32_e32 v52, s65, v3
	v_mad_u64_u32 v[50:51], s[68:69], v50, s67, v[48:49]
	v_mad_u64_u32 v[52:53], s[68:69], v52, s67, v[48:49]
	global_load_dword v134, v[50:51], off nt
	global_load_dword v135, v[52:53], off nt
	v_mad_u64_u32 v[50:51], s[68:69], v55, s40, v[2:3]
	v_mad_u64_u32 v[52:53], s[68:69], v54, s40, v[2:3]
	s_add_i32 s68, s64, 20
	s_add_i32 s65, s37, 20
	v_or_b32_e32 v55, s68, v0
	v_or_b32_e32 v54, s65, v1
	v_mov_b32_e32 v150, v50
	v_mov_b32_e32 v151, v52
	v_or_b32_e32 v50, s68, v4
	v_or_b32_e32 v52, s65, v3
	v_mad_u64_u32 v[50:51], s[68:69], v50, s67, v[48:49]
	v_mad_u64_u32 v[52:53], s[68:69], v52, s67, v[48:49]
	global_load_dword v136, v[50:51], off nt
	global_load_dword v137, v[52:53], off nt
	v_mad_u64_u32 v[50:51], s[68:69], v55, s40, v[2:3]
	v_mad_u64_u32 v[52:53], s[68:69], v54, s40, v[2:3]
	s_add_i32 s68, s64, 24
	s_add_i32 s65, s37, 24
	v_or_b32_e32 v55, s68, v0
	v_or_b32_e32 v54, s65, v1
	s_add_i32 s64, s64, 28
	s_add_i32 s37, s37, 28
	s_cmp_lg_u32 s36, 0
	v_mov_b32_e32 v152, v50
	v_mov_b32_e32 v153, v52
	v_or_b32_e32 v50, s68, v4
	v_or_b32_e32 v52, s65, v3
	v_mad_u64_u32 v[50:51], s[68:69], v50, s67, v[48:49]
	v_mad_u64_u32 v[52:53], s[68:69], v52, s67, v[48:49]
	global_load_dword v138, v[50:51], off nt
	global_load_dword v139, v[52:53], off nt
	v_mad_u64_u32 v[50:51], s[68:69], v55, s40, v[2:3]
	v_mad_u64_u32 v[52:53], s[68:69], v54, s40, v[2:3]
	v_or_b32_e32 v55, s64, v0
	v_or_b32_e32 v54, s37, v1
	v_mov_b32_e32 v154, v50
	v_mov_b32_e32 v155, v52
	v_or_b32_e32 v50, s64, v4
	v_or_b32_e32 v52, s37, v3
	v_mad_u64_u32 v[50:51], s[64:65], v50, s67, v[48:49]
	v_mad_u64_u32 v[52:53], s[64:65], v52, s67, v[48:49]
	global_load_dword v140, v[50:51], off nt
	global_load_dword v141, v[52:53], off nt
	v_mad_u64_u32 v[50:51], s[64:65], v55, s40, v[2:3]
	v_mad_u64_u32 v[52:53], s[64:65], v54, s40, v[2:3]
	v_mov_b32_e32 v156, v50
	v_mov_b32_e32 v157, v52
	s_waitcnt vmcnt(15)
	ds_write_b32 v142, v126
	s_waitcnt vmcnt(14)
	ds_write_b32 v143, v127
	s_waitcnt vmcnt(13)
	ds_write_b32 v144, v128
	s_waitcnt vmcnt(12)
	ds_write_b32 v145, v129
	s_waitcnt vmcnt(11)
	ds_write_b32 v146, v130
	s_waitcnt vmcnt(10)
	ds_write_b32 v147, v131
	s_waitcnt vmcnt(9)
	ds_write_b32 v148, v132
	s_waitcnt vmcnt(8)
	ds_write_b32 v149, v133
	s_waitcnt vmcnt(7)
	ds_write_b32 v150, v134
	s_waitcnt vmcnt(6)
	ds_write_b32 v151, v135
	s_waitcnt vmcnt(5)
	ds_write_b32 v152, v136
	s_waitcnt vmcnt(4)
	ds_write_b32 v153, v137
	s_waitcnt vmcnt(3)
	ds_write_b32 v154, v138
	s_waitcnt vmcnt(2)
	ds_write_b32 v155, v139
	s_waitcnt vmcnt(1)
	ds_write_b32 v156, v140
	s_waitcnt vmcnt(0)
	ds_write_b32 v157, v141
	s_cbranch_scc1 .LBB0_1816
	v_or_b32_e32 v4, v101, v60
	v_cndmask_b32_e64 v3, 0, 1, s[96:97]
	v_mov_b32_e32 v69, 1.0
	v_cmp_ne_u32_e64 s[10:11], 1, v3
	s_andn2_b64 vcc, exec, s[96:97]
	v_lshlrev_b32_e32 v3, 2, v4
	v_mov_b32_e32 v68, 1.0
	s_cbranch_vccnz .LBB0_1819
	global_load_dword v68, v3, s[72:73]

.LBB0_1837:
	s_lshl_b32 s36, s11, 1
	s_lshl_b32 s35, s10, 1
	v_or_b32_e32 v54, s36, v4
	v_or_b32_e32 v56, s35, v3
	v_mad_i64_i32 v[54:55], s[64:65], v54, s41, v[52:53]
	v_mad_i64_i32 v[56:57], s[64:65], v56, s41, v[52:53]
	global_load_dword v126, v[54:55], off nt
	global_load_dword v127, v[56:57], off nt
	v_or_b32_e32 v49, s35, v1
	v_or_b32_e32 v51, s36, v0
	v_mad_u64_u32 v[54:55], s[64:65], v51, s40, v[2:3]
	v_mad_u64_u32 v[56:57], s[64:65], v49, s40, v[2:3]
	s_add_i32 s64, s36, 4
	s_add_i32 s37, s35, 4
	v_or_b32_e32 v51, s64, v0
	v_or_b32_e32 v49, s37, v1
	s_add_i32 s11, s11, 16
	s_add_i32 s10, s10, 16
	s_add_i32 s34, s34, -16
	v_mov_b32_e32 v142, v54
	v_mov_b32_e32 v143, v56
	v_or_b32_e32 v54, s64, v4
	v_or_b32_e32 v56, s37, v3
	v_mad_i64_i32 v[54:55], s[64:65], v54, s41, v[52:53]
	v_mad_i64_i32 v[56:57], s[64:65], v56, s41, v[52:53]
	global_load_dword v128, v[54:55], off nt
	global_load_dword v129, v[56:57], off nt
	v_mad_u64_u32 v[54:55], s[64:65], v51, s40, v[2:3]
	v_mad_u64_u32 v[56:57], s[64:65], v49, s40, v[2:3]
	s_add_i32 s64, s36, 8
	s_add_i32 s37, s35, 8
	v_or_b32_e32 v51, s64, v0
	v_or_b32_e32 v49, s37, v1
	v_mov_b32_e32 v144, v54
	v_mov_b32_e32 v145, v56
	v_or_b32_e32 v54, s64, v4
	v_or_b32_e32 v56, s37, v3
	v_mad_i64_i32 v[54:55], s[64:65], v54, s41, v[52:53]
	v_mad_i64_i32 v[56:57], s[64:65], v56, s41, v[52:53]
	global_load_dword v130, v[54:55], off nt
	global_load_dword v131, v[56:57], off nt
	v_mad_u64_u32 v[54:55], s[64:65], v51, s40, v[2:3]
	v_mad_u64_u32 v[56:57], s[64:65], v49, s40, v[2:3]
	s_add_i32 s64, s36, 12
	s_add_i32 s37, s35, 12
	v_or_b32_e32 v51, s64, v0
	v_or_b32_e32 v49, s37, v1
	v_mov_b32_e32 v146, v54
	v_mov_b32_e32 v147, v56
	v_or_b32_e32 v54, s64, v4
	v_or_b32_e32 v56, s37, v3
	v_mad_i64_i32 v[54:55], s[64:65], v54, s41, v[52:53]
	v_mad_i64_i32 v[56:57], s[64:65], v56, s41, v[52:53]
	global_load_dword v132, v[54:55], off nt
	global_load_dword v133, v[56:57], off nt
	v_mad_u64_u32 v[54:55], s[64:65], v51, s40, v[2:3]
	v_mad_u64_u32 v[56:57], s[64:65], v49, s40, v[2:3]
	s_add_i32 s64, s36, 16
	s_add_i32 s37, s35, 16
	v_or_b32_e32 v51, s64, v0
	v_or_b32_e32 v49, s37, v1
	v_mov_b32_e32 v148, v54
	v_mov_b32_e32 v149, v56
	v_or_b32_e32 v54, s64, v4
	v_or_b32_e32 v56, s37, v3
	v_mad_i64_i32 v[54:55], s[64:65], v54, s41, v[52:53]
	v_mad_i64_i32 v[56:57], s[64:65], v56, s41, v[52:53]
	global_load_dword v134, v[54:55], off nt
	global_load_dword v135, v[56:57], off nt
	v_mad_u64_u32 v[54:55], s[64:65], v51, s40, v[2:3]
	v_mad_u64_u32 v[56:57], s[64:65], v49, s40, v[2:3]
	s_add_i32 s64, s36, 20
	s_add_i32 s37, s35, 20
	v_or_b32_e32 v51, s64, v0
	v_or_b32_e32 v49, s37, v1
	v_mov_b32_e32 v150, v54
	v_mov_b32_e32 v151, v56
	v_or_b32_e32 v54, s64, v4
	v_or_b32_e32 v56, s37, v3
	v_mad_i64_i32 v[54:55], s[64:65], v54, s41, v[52:53]
	v_mad_i64_i32 v[56:57], s[64:65], v56, s41, v[52:53]
	global_load_dword v136, v[54:55], off nt
	global_load_dword v137, v[56:57], off nt
	v_mad_u64_u32 v[54:55], s[64:65], v51, s40, v[2:3]
	v_mad_u64_u32 v[56:57], s[64:65], v49, s40, v[2:3]
	s_add_i32 s64, s36, 24
	s_add_i32 s37, s35, 24
	v_or_b32_e32 v51, s64, v0
	v_or_b32_e32 v49, s37, v1
	s_add_i32 s36, s36, 28
	s_add_i32 s35, s35, 28
	s_cmp_lg_u32 s34, 0
	v_mov_b32_e32 v152, v54
	v_mov_b32_e32 v153, v56
	v_or_b32_e32 v54, s64, v4
	v_or_b32_e32 v56, s37, v3
	v_mad_i64_i32 v[54:55], s[64:65], v54, s41, v[52:53]
	v_mad_i64_i32 v[56:57], s[64:65], v56, s41, v[52:53]
	global_load_dword v138, v[54:55], off nt
	global_load_dword v139, v[56:57], off nt
	v_mad_u64_u32 v[54:55], s[64:65], v51, s40, v[2:3]
	v_mad_u64_u32 v[56:57], s[64:65], v49, s40, v[2:3]
	v_or_b32_e32 v51, s36, v0
	v_or_b32_e32 v49, s35, v1
	v_mov_b32_e32 v154, v54
	v_mov_b32_e32 v155, v56
	v_or_b32_e32 v54, s36, v4
	v_or_b32_e32 v56, s35, v3
	v_mad_i64_i32 v[54:55], s[36:37], v54, s41, v[52:53]
	v_mad_i64_i32 v[56:57], s[36:37], v56, s41, v[52:53]
	global_load_dword v140, v[54:55], off nt
	global_load_dword v141, v[56:57], off nt
	v_mad_u64_u32 v[54:55], s[36:37], v51, s40, v[2:3]
	v_mad_u64_u32 v[56:57], s[36:37], v49, s40, v[2:3]
	v_mov_b32_e32 v156, v54
	v_mov_b32_e32 v157, v56
	s_waitcnt vmcnt(15)
	ds_write_b32 v142, v126
	s_waitcnt vmcnt(14)
	ds_write_b32 v143, v127
	s_waitcnt vmcnt(13)
	ds_write_b32 v144, v128
	s_waitcnt vmcnt(12)
	ds_write_b32 v145, v129
	s_waitcnt vmcnt(11)
	ds_write_b32 v146, v130
	s_waitcnt vmcnt(10)
	ds_write_b32 v147, v131
	s_waitcnt vmcnt(9)
	ds_write_b32 v148, v132
	s_waitcnt vmcnt(8)
	ds_write_b32 v149, v133
	s_waitcnt vmcnt(7)
	ds_write_b32 v150, v134
	s_waitcnt vmcnt(6)
	ds_write_b32 v151, v135
	s_waitcnt vmcnt(5)
	ds_write_b32 v152, v136
	s_waitcnt vmcnt(4)
	ds_write_b32 v153, v137
	s_waitcnt vmcnt(3)
	ds_write_b32 v154, v138
	s_waitcnt vmcnt(2)
	ds_write_b32 v155, v139
	s_waitcnt vmcnt(1)
	ds_write_b32 v156, v140
	s_waitcnt vmcnt(0)
	ds_write_b32 v157, v141
	s_cbranch_scc1 .LBB0_1837
	v_or_b32_e32 v52, v50, v101
	v_cndmask_b32_e64 v3, 0, 1, s[8:9]
	v_mov_b32_e32 v71, 1.0
	v_cmp_ne_u32_e64 s[10:11], 1, v3
	s_andn2_b64 vcc, exec, s[8:9]
	v_ashrrev_i32_e32 v53, 31, v52
	v_mov_b32_e32 v70, 1.0
	s_cbranch_vccnz .LBB0_1840
	v_lshl_add_u64 v[54:55], v[52:53], 2, s[70:71]
	global_load_dword v70, v[54:55], off

.LBB0_2640:
	s_lshl_b32 s61, s54, 1
	s_lshl_b32 s64, s55, 1
	v_or_b32_e32 v56, s61, v1
	v_or_b32_e32 v57, s64, v0
	v_add_lshl_u32 v4, v56, v3, 10
	v_add_lshl_u32 v53, v57, v48, 10
	v_or_b32_e32 v52, v49, v4
	v_or_b32_e32 v4, v50, v53
	v_lshl_add_u64 v[54:55], v[4:5], 2, s[26:27]
	v_mov_b32_e32 v53, v5
	v_lshl_add_u64 v[52:53], v[52:53], 2, s[26:27]
	global_load_dword v126, v[54:55], off nt
	global_load_dword v127, v[52:53], off nt
	v_mad_u64_u32 v[52:53], s[66:67], v57, s40, v[2:3]
	v_mad_u64_u32 v[54:55], s[66:67], v56, s40, v[2:3]
	s_add_i32 s65, s61, 4
	s_add_i32 s66, s64, 4
	v_or_b32_e32 v56, s65, v1
	v_or_b32_e32 v57, s66, v0
	v_add_lshl_u32 v53, v57, v48, 10
	s_add_i32 s65, s61, 8
	s_add_i32 s55, s55, 16
	s_add_i32 s54, s54, 16
	s_add_i32 s60, s60, -16
	v_mov_b32_e32 v142, v52
	v_mov_b32_e32 v143, v54
	v_add_lshl_u32 v4, v56, v3, 10
	v_or_b32_e32 v52, v49, v4
	v_or_b32_e32 v4, v50, v53
	v_lshl_add_u64 v[54:55], v[4:5], 2, s[26:27]
	v_mov_b32_e32 v53, v5
	v_lshl_add_u64 v[52:53], v[52:53], 2, s[26:27]
	global_load_dword v128, v[54:55], off nt
	global_load_dword v129, v[52:53], off nt
	v_mad_u64_u32 v[52:53], s[66:67], v57, s40, v[2:3]
	v_mad_u64_u32 v[54:55], s[66:67], v56, s40, v[2:3]
	s_add_i32 s66, s64, 8
	v_or_b32_e32 v56, s65, v1
	v_or_b32_e32 v57, s66, v0
	v_add_lshl_u32 v53, v57, v48, 10
	s_add_i32 s65, s61, 12
	v_mov_b32_e32 v144, v52
	v_mov_b32_e32 v145, v54
	v_add_lshl_u32 v4, v56, v3, 10
	v_or_b32_e32 v52, v49, v4
	v_or_b32_e32 v4, v50, v53
	v_lshl_add_u64 v[54:55], v[4:5], 2, s[26:27]
	v_mov_b32_e32 v53, v5
	v_lshl_add_u64 v[52:53], v[52:53], 2, s[26:27]
	global_load_dword v130, v[54:55], off nt
	global_load_dword v131, v[52:53], off nt
	v_mad_u64_u32 v[52:53], s[66:67], v57, s40, v[2:3]
	v_mad_u64_u32 v[54:55], s[66:67], v56, s40, v[2:3]
	s_add_i32 s66, s64, 12
	v_or_b32_e32 v56, s65, v1
	v_or_b32_e32 v57, s66, v0
	v_add_lshl_u32 v53, v57, v48, 10
	s_add_i32 s65, s61, 16
	v_mov_b32_e32 v146, v52
	v_mov_b32_e32 v147, v54
	v_add_lshl_u32 v4, v56, v3, 10
	v_or_b32_e32 v52, v49, v4
	v_or_b32_e32 v4, v50, v53
	v_lshl_add_u64 v[54:55], v[4:5], 2, s[26:27]
	v_mov_b32_e32 v53, v5
	v_lshl_add_u64 v[52:53], v[52:53], 2, s[26:27]
	global_load_dword v132, v[54:55], off nt
	global_load_dword v133, v[52:53], off nt
	v_mad_u64_u32 v[52:53], s[66:67], v57, s40, v[2:3]
	v_mad_u64_u32 v[54:55], s[66:67], v56, s40, v[2:3]
	s_add_i32 s66, s64, 16
	v_or_b32_e32 v56, s65, v1
	v_or_b32_e32 v57, s66, v0
	v_add_lshl_u32 v53, v57, v48, 10
	s_add_i32 s65, s61, 20
	v_mov_b32_e32 v148, v52
	v_mov_b32_e32 v149, v54
	v_add_lshl_u32 v4, v56, v3, 10
	v_or_b32_e32 v52, v49, v4
	v_or_b32_e32 v4, v50, v53
	v_lshl_add_u64 v[54:55], v[4:5], 2, s[26:27]
	v_mov_b32_e32 v53, v5
	v_lshl_add_u64 v[52:53], v[52:53], 2, s[26:27]
	global_load_dword v134, v[54:55], off nt
	global_load_dword v135, v[52:53], off nt
	v_mad_u64_u32 v[52:53], s[66:67], v57, s40, v[2:3]
	v_mad_u64_u32 v[54:55], s[66:67], v56, s40, v[2:3]
	s_add_i32 s66, s64, 20
	v_or_b32_e32 v56, s65, v1
	v_or_b32_e32 v57, s66, v0
	v_add_lshl_u32 v53, v57, v48, 10
	s_add_i32 s65, s61, 24
	s_add_i32 s61, s61, 28
	v_mov_b32_e32 v150, v52
	v_mov_b32_e32 v151, v54
	v_add_lshl_u32 v4, v56, v3, 10
	v_or_b32_e32 v52, v49, v4
	v_or_b32_e32 v4, v50, v53
	v_lshl_add_u64 v[54:55], v[4:5], 2, s[26:27]
	v_mov_b32_e32 v53, v5
	v_lshl_add_u64 v[52:53], v[52:53], 2, s[26:27]
	global_load_dword v136, v[54:55], off nt
	global_load_dword v137, v[52:53], off nt
	v_mad_u64_u32 v[52:53], s[66:67], v57, s40, v[2:3]
	v_mad_u64_u32 v[54:55], s[66:67], v56, s40, v[2:3]
	s_add_i32 s66, s64, 24
	v_or_b32_e32 v56, s65, v1
	v_or_b32_e32 v57, s66, v0
	v_add_lshl_u32 v53, v57, v48, 10
	s_add_i32 s64, s64, 28
	s_cmp_lg_u32 s60, 0
	v_mov_b32_e32 v152, v52
	v_mov_b32_e32 v153, v54
	v_add_lshl_u32 v4, v56, v3, 10
	v_or_b32_e32 v52, v49, v4
	v_or_b32_e32 v4, v50, v53
	v_lshl_add_u64 v[54:55], v[4:5], 2, s[26:27]
	v_mov_b32_e32 v53, v5
	v_lshl_add_u64 v[52:53], v[52:53], 2, s[26:27]
	global_load_dword v138, v[54:55], off nt
	global_load_dword v139, v[52:53], off nt
	v_mad_u64_u32 v[52:53], s[66:67], v57, s40, v[2:3]
	v_mad_u64_u32 v[54:55], s[66:67], v56, s40, v[2:3]
	v_or_b32_e32 v56, s61, v1
	v_or_b32_e32 v57, s64, v0
	v_mov_b32_e32 v55, v5
	v_mov_b32_e32 v154, v52
	v_mov_b32_e32 v155, v54
	v_add_lshl_u32 v4, v56, v3, 10
	v_add_lshl_u32 v52, v57, v48, 10
	v_or_b32_e32 v54, v49, v4
	v_or_b32_e32 v4, v50, v52
	v_lshl_add_u64 v[52:53], v[4:5], 2, s[26:27]
	v_lshl_add_u64 v[54:55], v[54:55], 2, s[26:27]
	global_load_dword v140, v[52:53], off nt
	global_load_dword v141, v[54:55], off nt
	v_mad_u64_u32 v[52:53], s[64:65], v57, s40, v[2:3]
	v_mad_u64_u32 v[54:55], s[64:65], v56, s40, v[2:3]
	v_mov_b32_e32 v156, v52
	v_mov_b32_e32 v157, v54
	s_waitcnt vmcnt(15)
	ds_write_b32 v142, v126
	s_waitcnt vmcnt(14)
	ds_write_b32 v143, v127
	s_waitcnt vmcnt(13)
	ds_write_b32 v144, v128
	s_waitcnt vmcnt(12)
	ds_write_b32 v145, v129
	s_waitcnt vmcnt(11)
	ds_write_b32 v146, v130
	s_waitcnt vmcnt(10)
	ds_write_b32 v147, v131
	s_waitcnt vmcnt(9)
	ds_write_b32 v148, v132
	s_waitcnt vmcnt(8)
	ds_write_b32 v149, v133
	s_waitcnt vmcnt(7)
	ds_write_b32 v150, v134
	s_waitcnt vmcnt(6)
	ds_write_b32 v151, v135
	s_waitcnt vmcnt(5)
	ds_write_b32 v152, v136
	s_waitcnt vmcnt(4)
	ds_write_b32 v153, v137
	s_waitcnt vmcnt(3)
	ds_write_b32 v154, v138
	s_waitcnt vmcnt(2)
	ds_write_b32 v155, v139
	s_waitcnt vmcnt(1)
	ds_write_b32 v156, v140
	s_waitcnt vmcnt(0)
	ds_write_b32 v157, v141
	s_cbranch_scc1 .LBB0_2640
	v_or_b32_e32 v3, v51, v96
	v_lshlrev_b32_e32 v4, 2, v3
	v_or_b32_e32 v49, 0x5000, v4
	global_load_dword v90, v49, s[92:93]
	global_load_dword v80, v49, s[94:95]
	v_or_b32_e32 v49, 0x5020, v4
	global_load_dword v62, v49, s[92:93]
	global_load_dword v60, v49, s[94:95]
	v_or_b32_e32 v49, 0x5040, v4
	global_load_dword v58, v49, s[92:93]
	global_load_dword v56, v49, s[94:95]
	v_or_b32_e32 v4, 0x5060, v4
	global_load_dword v52, v4, s[92:93]
	global_load_dword v50, v4, s[94:95]
	s_waitcnt lgkmcnt(0)
	ds_read2_b32 v[74:75], v97 offset0:33 offset1:41
	ds_read2_b32 v[66:67], v97 offset0:66 offset1:74
	ds_read2_b32 v[64:65], v97 offset0:99 offset1:107
	ds_read2_b32 v[76:77], v97 offset0:132 offset1:140
	ds_read2_b32 v[72:73], v97 offset0:165 offset1:173
	ds_read2_b32 v[70:71], v97 offset0:198 offset1:206
	ds_read2_b32 v[68:69], v97 offset0:231 offset1:239
	ds_read2_b32 v[78:79], v97 offset1:8
	s_waitcnt lgkmcnt(4)
	v_mov_b32_e32 v86, v76
	v_mov_b32_e32 v83, v66
	s_waitcnt lgkmcnt(2)
	v_mov_b32_e32 v87, v70
	v_mov_b32_e32 v84, v74
	s_waitcnt lgkmcnt(0)
	v_mov_b32_e32 v82, v78
	v_mov_b32_e32 v85, v64
	v_mov_b32_e32 v88, v72
	v_mov_b32_e32 v89, v68
	v_lshlrev_b32_e32 v4, 1, v48
	v_lshl_add_u64 v[54:55], v[6:7], 0, v[4:5]
	v_lshl_add_u64 v[48:49], v[22:23], 0, v[4:5]
	v_mul_u32_u24_e32 v3, 0xb00, v3
	v_mov_b32_e32 v70, v77
	v_mov_b32_e32 v68, v73
	s_waitcnt vmcnt(7)
	v_pk_mul_f32 v[112:113], v[90:91], v[86:87] op_sel_hi:[0,1]
	v_pk_mul_f32 v[92:93], v[90:91], v[82:83] op_sel_hi:[0,1]
	v_pk_mul_f32 v[110:111], v[90:91], v[84:85] op_sel_hi:[0,1]
	v_pk_mul_f32 v[90:91], v[90:91], v[88:89] op_sel_hi:[0,1]
	v_bfe_u32 v64, v112, 16, 1
	v_bfe_u32 v66, v113, 16, 1
	v_bfe_u32 v4, v91, 16, 1
	v_bfe_u32 v53, v90, 16, 1
	v_bfe_u32 v63, v93, 16, 1
	v_add3_u32 v66, v113, v66, s46
	v_add3_u32 v64, v112, v64, s46
	v_bfe_u32 v57, v111, 16, 1
	v_add3_u32 v53, v90, v53, s46
	v_add3_u32 v4, v91, v4, s46
	v_bfe_u32 v61, v92, 16, 1
	v_add3_u32 v63, v93, v63, s46
	v_lshrrev_b32_e32 v64, 16, v64
	v_lshrrev_b32_e32 v66, 16, v66
	s_waitcnt vmcnt(6)
	v_pk_mul_f32 v[86:87], v[80:81], v[86:87] op_sel_hi:[0,1]
	v_bfe_u32 v59, v110, 16, 1
	v_add3_u32 v57, v111, v57, s46
	v_add3_u32 v61, v92, v61, s46
	v_lshrrev_b32_e32 v63, 16, v63
	v_and_or_b32 v93, v4, s47, v66
	v_and_or_b32 v92, v53, s47, v64
	v_pk_mul_f32 v[82:83], v[80:81], v[82:83] op_sel_hi:[0,1]
	v_pk_mul_f32 v[84:85], v[80:81], v[84:85] op_sel_hi:[0,1]
	v_pk_mul_f32 v[80:81], v[80:81], v[88:89] op_sel_hi:[0,1]
	v_bfe_u32 v64, v86, 16, 1
	v_bfe_u32 v66, v87, 16, 1
	v_add3_u32 v59, v110, v59, s46
	v_lshrrev_b32_e32 v61, 16, v61
	v_and_or_b32 v91, v57, s47, v63
	v_lshlrev_b32_e32 v4, 1, v3
	v_bfe_u32 v3, v81, 16, 1
	v_bfe_u32 v53, v80, 16, 1
	v_bfe_u32 v63, v83, 16, 1
	v_add3_u32 v66, v87, v66, s46
	v_add3_u32 v64, v86, v64, s46
	v_and_or_b32 v90, v59, s47, v61
	v_bfe_u32 v57, v85, 16, 1
	v_add3_u32 v53, v80, v53, s46
	v_add3_u32 v3, v81, v3, s46
	v_bfe_u32 v61, v82, 16, 1
	v_add3_u32 v63, v83, v63, s46
	v_lshrrev_b32_e32 v64, 16, v64
	v_lshrrev_b32_e32 v66, 16, v66
	v_add3_u32 v57, v85, v57, s46
	v_add3_u32 v61, v82, v61, s46
	v_lshrrev_b32_e32 v63, 16, v63
	v_and_or_b32 v83, v3, s47, v66
	v_and_or_b32 v82, v53, s47, v64
	v_mov_b32_e32 v66, v79
	v_mov_b32_e32 v64, v75
	v_and_or_b32 v81, v57, s47, v63
	s_waitcnt vmcnt(5)
	v_pk_mul_f32 v[78:79], v[62:63], v[66:67] op_sel_hi:[0,1]
	v_pk_mul_f32 v[74:75], v[62:63], v[64:65] op_sel_hi:[0,1]
	v_pk_mul_f32 v[76:77], v[62:63], v[70:71] op_sel_hi:[0,1]
	v_pk_mul_f32 v[62:63], v[62:63], v[68:69] op_sel_hi:[0,1]
	v_bfe_u32 v3, v63, 16, 1
	v_bfe_u32 v59, v84, 16, 1
	v_add3_u32 v3, v63, v3, s46
	v_bfe_u32 v63, v77, 16, 1
	v_lshl_add_u64 v[110:111], v[54:55], 0, v[4:5]
	v_add3_u32 v59, v84, v59, s46
	v_lshl_add_u64 v[84:85], v[48:49], 0, v[4:5]
	v_bfe_u32 v4, v62, 16, 1
	v_add3_u32 v63, v77, v63, s46
	v_lshrrev_b32_e32 v61, 16, v61
	v_bfe_u32 v53, v75, 16, 1
	v_add3_u32 v4, v62, v4, s46
	v_bfe_u32 v62, v76, 16, 1
	v_lshrrev_b32_e32 v63, 16, v63
	v_and_or_b32 v80, v59, s47, v61
	v_add3_u32 v53, v75, v53, s46
	v_bfe_u32 v59, v78, 16, 1
	v_bfe_u32 v61, v79, 16, 1
	v_add3_u32 v62, v76, v62, s46
	v_and_or_b32 v75, v3, s47, v63
	v_or_b32_e32 v3, v51, v98
	v_bfe_u32 v57, v74, 16, 1
	v_add3_u32 v61, v79, v61, s46
	v_add3_u32 v59, v78, v59, s46
	v_lshrrev_b32_e32 v62, 16, v62
	v_mul_u32_u24_e32 v3, 0xb00, v3
	v_add3_u32 v57, v74, v57, s46
	v_lshrrev_b32_e32 v59, 16, v59
	v_lshrrev_b32_e32 v61, 16, v61
	v_and_or_b32 v74, v4, s47, v62
	v_lshlrev_b32_e32 v4, 1, v3
	v_and_or_b32 v73, v53, s47, v61
	v_and_or_b32 v72, v57, s47, v59
	v_lshl_add_u64 v[62:63], v[54:55], 0, v[4:5]
	global_store_dwordx4 v[110:111], v[90:93], off
	global_store_dwordx4 v[84:85], v[80:83], off
	global_store_dwordx4 v[62:63], v[72:75], off
	s_waitcnt vmcnt(7)
	v_pk_mul_f32 v[62:63], v[60:61], v[66:67] op_sel_hi:[0,1]
	v_pk_mul_f32 v[64:65], v[60:61], v[64:65] op_sel_hi:[0,1]
	v_pk_mul_f32 v[66:67], v[60:61], v[70:71] op_sel_hi:[0,1]
	v_pk_mul_f32 v[60:61], v[60:61], v[68:69] op_sel_hi:[0,1]
	v_bfe_u32 v3, v61, 16, 1
	v_bfe_u32 v53, v60, 16, 1
	v_bfe_u32 v57, v65, 16, 1
	v_bfe_u32 v59, v64, 16, 1
	v_add3_u32 v59, v64, v59, s46
	v_add3_u32 v57, v65, v57, s46
	v_add3_u32 v53, v60, v53, s46
	v_add3_u32 v3, v61, v3, s46
	v_bfe_u32 v60, v62, 16, 1
	v_bfe_u32 v61, v63, 16, 1
	v_bfe_u32 v64, v66, 16, 1
	v_bfe_u32 v65, v67, 16, 1
	v_add3_u32 v65, v67, v65, s46
	v_add3_u32 v64, v66, v64, s46
	v_add3_u32 v61, v63, v61, s46
	v_add3_u32 v60, v62, v60, s46
	v_lshrrev_b32_e32 v60, 16, v60
	v_lshrrev_b32_e32 v61, 16, v61
	v_lshrrev_b32_e32 v62, 16, v64
	v_lshrrev_b32_e32 v63, 16, v65
	v_and_or_b32 v63, v3, s47, v63
	v_and_or_b32 v62, v53, s47, v62
	v_and_or_b32 v61, v57, s47, v61
	v_and_or_b32 v60, v59, s47, v60
	v_lshl_add_u64 v[64:65], v[48:49], 0, v[4:5]
	global_store_dwordx4 v[64:65], v[60:63], off
	ds_read2_b32 v[62:63], v97 offset0:16 offset1:24
	ds_read2_b32 v[64:65], v97 offset0:49 offset1:57
	ds_read2_b32 v[66:67], v97 offset0:82 offset1:90
	ds_read2_b32 v[68:69], v97 offset0:115 offset1:123
	ds_read2_b32 v[70:71], v97 offset0:148 offset1:156
	ds_read2_b32 v[72:73], v97 offset0:181 offset1:189
	ds_read2_b32 v[74:75], v97 offset0:214 offset1:222
	ds_read2_b32 v[76:77], v97 offset0:247 offset1:255
	s_waitcnt lgkmcnt(7)
	v_mov_b32_e32 v78, v62
	s_waitcnt lgkmcnt(5)
	v_mov_b32_e32 v79, v66
	v_mov_b32_e32 v80, v64
	s_waitcnt lgkmcnt(4)
	v_mov_b32_e32 v81, v68
	s_waitcnt lgkmcnt(3)
	v_mov_b32_e32 v84, v70
	s_waitcnt lgkmcnt(1)
	v_mov_b32_e32 v85, v74
	v_mov_b32_e32 v88, v72
	s_waitcnt lgkmcnt(0)
	v_mov_b32_e32 v89, v76
	s_waitcnt vmcnt(7)
	v_pk_mul_f32 v[60:61], v[58:59], v[78:79] op_sel_hi:[0,1]
	v_pk_mul_f32 v[82:83], v[58:59], v[80:81] op_sel_hi:[0,1]
	v_pk_mul_f32 v[86:87], v[58:59], v[84:85] op_sel_hi:[0,1]
	v_pk_mul_f32 v[58:59], v[58:59], v[88:89] op_sel_hi:[0,1]
	v_bfe_u32 v3, v59, 16, 1
	v_bfe_u32 v64, v87, 16, 1
	v_add3_u32 v3, v59, v3, s46
	v_bfe_u32 v59, v61, 16, 1
	v_add3_u32 v64, v87, v64, s46
	v_bfe_u32 v4, v58, 16, 1
	v_bfe_u32 v62, v86, 16, 1
	v_add3_u32 v59, v61, v59, s46
	v_lshrrev_b32_e32 v61, 16, v64
	v_add3_u32 v4, v58, v4, s46
	v_bfe_u32 v58, v60, 16, 1
	v_add3_u32 v62, v86, v62, s46
	v_and_or_b32 v61, v3, s47, v61
	v_or_b32_e32 v3, v51, v99
	v_bfe_u32 v53, v83, 16, 1
	v_bfe_u32 v57, v82, 16, 1
	v_add3_u32 v58, v60, v58, s46
	v_lshrrev_b32_e32 v60, 16, v62
	v_mul_u32_u24_e32 v3, 0xb00, v3
	v_add3_u32 v57, v82, v57, s46
	v_add3_u32 v53, v83, v53, s46
	v_lshrrev_b32_e32 v58, 16, v58
	v_lshrrev_b32_e32 v59, 16, v59
	v_and_or_b32 v60, v4, s47, v60
	v_lshlrev_b32_e32 v4, 1, v3
	v_and_or_b32 v59, v53, s47, v59
	v_and_or_b32 v58, v57, s47, v58
	v_lshl_add_u64 v[82:83], v[54:55], 0, v[4:5]
	global_store_dwordx4 v[82:83], v[58:61], off
	v_mov_b32_e32 v68, v65
	v_mov_b32_e32 v66, v63
	s_waitcnt vmcnt(7)
	v_pk_mul_f32 v[58:59], v[56:57], v[78:79] op_sel_hi:[0,1]
	v_pk_mul_f32 v[60:61], v[56:57], v[80:81] op_sel_hi:[0,1]
	v_pk_mul_f32 v[78:79], v[56:57], v[84:85] op_sel_hi:[0,1]
	v_pk_mul_f32 v[56:57], v[56:57], v[88:89] op_sel_hi:[0,1]
	v_bfe_u32 v3, v57, 16, 1
	v_bfe_u32 v53, v56, 16, 1
	v_bfe_u32 v62, v61, 16, 1
	v_bfe_u32 v64, v60, 16, 1
	v_add3_u32 v60, v60, v64, s46
	v_add3_u32 v61, v61, v62, s46
	v_add3_u32 v53, v56, v53, s46
	v_add3_u32 v3, v57, v3, s46
	v_bfe_u32 v56, v58, 16, 1
	v_bfe_u32 v57, v59, 16, 1
	v_bfe_u32 v62, v78, 16, 1
	v_bfe_u32 v64, v79, 16, 1
	v_add3_u32 v64, v79, v64, s46
	v_add3_u32 v62, v78, v62, s46
	v_add3_u32 v57, v59, v57, s46
	v_add3_u32 v56, v58, v56, s46
	v_lshrrev_b32_e32 v56, 16, v56
	v_lshrrev_b32_e32 v57, 16, v57
	v_lshrrev_b32_e32 v58, 16, v62
	v_lshrrev_b32_e32 v59, 16, v64
	v_and_or_b32 v59, v3, s47, v59
	v_and_or_b32 v58, v53, s47, v58
	v_and_or_b32 v57, v61, s47, v57
	v_and_or_b32 v56, v60, s47, v56
	v_lshl_add_u64 v[60:61], v[48:49], 0, v[4:5]
	global_store_dwordx4 v[60:61], v[56:59], off
	v_mov_b32_e32 v74, v71
	v_mov_b32_e32 v76, v73
	s_waitcnt vmcnt(7)
	v_pk_mul_f32 v[58:59], v[52:53], v[68:69] op_sel_hi:[0,1]
	v_pk_mul_f32 v[56:57], v[52:53], v[66:67] op_sel_hi:[0,1]
	v_pk_mul_f32 v[60:61], v[52:53], v[74:75] op_sel_hi:[0,1]
	v_pk_mul_f32 v[52:53], v[52:53], v[76:77] op_sel_hi:[0,1]
	v_bfe_u32 v62, v59, 16, 1
	v_bfe_u32 v3, v53, 16, 1
	v_add3_u32 v62, v59, v62, s46
	v_bfe_u32 v59, v61, 16, 1
	v_bfe_u32 v63, v58, 16, 1
	v_add3_u32 v3, v53, v3, s46
	v_bfe_u32 v53, v57, 16, 1
	v_add3_u32 v59, v61, v59, s46
	v_bfe_u32 v4, v52, 16, 1
	v_add3_u32 v63, v58, v63, s46
	v_bfe_u32 v58, v60, 16, 1
	v_add3_u32 v53, v57, v53, s46
	v_lshrrev_b32_e32 v57, 16, v59
	v_add3_u32 v4, v52, v4, s46
	v_bfe_u32 v52, v56, 16, 1
	v_add3_u32 v58, v60, v58, s46
	v_and_or_b32 v59, v3, s47, v57
	v_or_b32_e32 v3, v51, v100
	v_add3_u32 v52, v56, v52, s46
	v_lshrrev_b32_e32 v56, 16, v58
	v_mul_u32_u24_e32 v3, 0xb00, v3
	v_lshrrev_b32_e32 v52, 16, v52
	v_lshrrev_b32_e32 v53, 16, v53
	v_and_or_b32 v58, v4, s47, v56
	v_lshlrev_b32_e32 v4, 1, v3
	v_and_or_b32 v57, v62, s47, v53
	v_and_or_b32 v56, v63, s47, v52
	v_lshl_add_u64 v[52:53], v[54:55], 0, v[4:5]
	global_store_dwordx4 v[52:53], v[56:59], off
	s_waitcnt vmcnt(7)
	v_pk_mul_f32 v[52:53], v[50:51], v[66:67] op_sel_hi:[0,1]
	v_pk_mul_f32 v[54:55], v[50:51], v[68:69] op_sel_hi:[0,1]
	v_pk_mul_f32 v[56:57], v[50:51], v[74:75] op_sel_hi:[0,1]
	v_pk_mul_f32 v[50:51], v[50:51], v[76:77] op_sel_hi:[0,1]
	v_bfe_u32 v3, v51, 16, 1
	v_bfe_u32 v58, v50, 16, 1
	v_bfe_u32 v59, v55, 16, 1
	v_bfe_u32 v60, v54, 16, 1
	v_add3_u32 v54, v54, v60, s46
	v_add3_u32 v55, v55, v59, s46
	v_add3_u32 v50, v50, v58, s46
	v_add3_u32 v3, v51, v3, s46
	v_bfe_u32 v51, v52, 16, 1
	v_bfe_u32 v58, v53, 16, 1
	v_bfe_u32 v59, v56, 16, 1
	v_bfe_u32 v60, v57, 16, 1
	v_add3_u32 v57, v57, v60, s46
	v_add3_u32 v56, v56, v59, s46
	v_add3_u32 v53, v53, v58, s46
	v_add3_u32 v51, v52, v51, s46
	v_lshrrev_b32_e32 v58, 16, v51
	v_lshrrev_b32_e32 v51, 16, v53
	v_lshrrev_b32_e32 v52, 16, v56
	v_lshrrev_b32_e32 v53, 16, v57
	v_and_or_b32 v53, v3, s47, v53
	v_and_or_b32 v52, v50, s47, v52
	v_and_or_b32 v51, v55, s47, v51
	v_and_or_b32 v50, v54, s47, v58
	v_lshl_add_u64 v[48:49], v[48:49], 0, v[4:5]
	global_store_dwordx4 v[48:49], v[50:53], off
	s_waitcnt lgkmcnt(0)

.LBB0_2644:
	s_lshl_b32 s61, s54, 1
	s_lshl_b32 s64, s55, 1
	v_or_b32_e32 v56, s61, v1
	v_or_b32_e32 v57, s64, v0
	v_add_lshl_u32 v4, v56, v3, 10
	v_add_lshl_u32 v53, v57, v48, 10
	v_or_b32_e32 v52, v49, v4
	v_or_b32_e32 v4, v50, v53
	v_lshl_add_u64 v[54:55], v[4:5], 2, s[16:17]
	v_mov_b32_e32 v53, v5
	v_lshl_add_u64 v[52:53], v[52:53], 2, s[16:17]
	global_load_dword v126, v[54:55], off nt
	global_load_dword v127, v[52:53], off nt
	v_mad_u64_u32 v[52:53], s[66:67], v57, s40, v[2:3]
	v_mad_u64_u32 v[54:55], s[66:67], v56, s40, v[2:3]
	s_add_i32 s65, s61, 4
	s_add_i32 s66, s64, 4
	v_or_b32_e32 v56, s65, v1
	v_or_b32_e32 v57, s66, v0
	v_add_lshl_u32 v53, v57, v48, 10
	s_add_i32 s65, s61, 8
	s_add_i32 s55, s55, 16
	s_add_i32 s54, s54, 16
	s_add_i32 s60, s60, -16
	v_mov_b32_e32 v142, v52
	v_mov_b32_e32 v143, v54
	v_add_lshl_u32 v4, v56, v3, 10
	v_or_b32_e32 v52, v49, v4
	v_or_b32_e32 v4, v50, v53
	v_lshl_add_u64 v[54:55], v[4:5], 2, s[16:17]
	v_mov_b32_e32 v53, v5
	v_lshl_add_u64 v[52:53], v[52:53], 2, s[16:17]
	global_load_dword v128, v[54:55], off nt
	global_load_dword v129, v[52:53], off nt
	v_mad_u64_u32 v[52:53], s[66:67], v57, s40, v[2:3]
	v_mad_u64_u32 v[54:55], s[66:67], v56, s40, v[2:3]
	s_add_i32 s66, s64, 8
	v_or_b32_e32 v56, s65, v1
	v_or_b32_e32 v57, s66, v0
	v_add_lshl_u32 v53, v57, v48, 10
	s_add_i32 s65, s61, 12
	v_mov_b32_e32 v144, v52
	v_mov_b32_e32 v145, v54
	v_add_lshl_u32 v4, v56, v3, 10
	v_or_b32_e32 v52, v49, v4
	v_or_b32_e32 v4, v50, v53
	v_lshl_add_u64 v[54:55], v[4:5], 2, s[16:17]
	v_mov_b32_e32 v53, v5
	v_lshl_add_u64 v[52:53], v[52:53], 2, s[16:17]
	global_load_dword v130, v[54:55], off nt
	global_load_dword v131, v[52:53], off nt
	v_mad_u64_u32 v[52:53], s[66:67], v57, s40, v[2:3]
	v_mad_u64_u32 v[54:55], s[66:67], v56, s40, v[2:3]
	s_add_i32 s66, s64, 12
	v_or_b32_e32 v56, s65, v1
	v_or_b32_e32 v57, s66, v0
	v_add_lshl_u32 v53, v57, v48, 10
	s_add_i32 s65, s61, 16
	v_mov_b32_e32 v146, v52
	v_mov_b32_e32 v147, v54
	v_add_lshl_u32 v4, v56, v3, 10
	v_or_b32_e32 v52, v49, v4
	v_or_b32_e32 v4, v50, v53
	v_lshl_add_u64 v[54:55], v[4:5], 2, s[16:17]
	v_mov_b32_e32 v53, v5
	v_lshl_add_u64 v[52:53], v[52:53], 2, s[16:17]
	global_load_dword v132, v[54:55], off nt
	global_load_dword v133, v[52:53], off nt
	v_mad_u64_u32 v[52:53], s[66:67], v57, s40, v[2:3]
	v_mad_u64_u32 v[54:55], s[66:67], v56, s40, v[2:3]
	s_add_i32 s66, s64, 16
	v_or_b32_e32 v56, s65, v1
	v_or_b32_e32 v57, s66, v0
	v_add_lshl_u32 v53, v57, v48, 10
	s_add_i32 s65, s61, 20
	v_mov_b32_e32 v148, v52
	v_mov_b32_e32 v149, v54
	v_add_lshl_u32 v4, v56, v3, 10
	v_or_b32_e32 v52, v49, v4
	v_or_b32_e32 v4, v50, v53
	v_lshl_add_u64 v[54:55], v[4:5], 2, s[16:17]
	v_mov_b32_e32 v53, v5
	v_lshl_add_u64 v[52:53], v[52:53], 2, s[16:17]
	global_load_dword v134, v[54:55], off nt
	global_load_dword v135, v[52:53], off nt
	v_mad_u64_u32 v[52:53], s[66:67], v57, s40, v[2:3]
	v_mad_u64_u32 v[54:55], s[66:67], v56, s40, v[2:3]
	s_add_i32 s66, s64, 20
	v_or_b32_e32 v56, s65, v1
	v_or_b32_e32 v57, s66, v0
	v_add_lshl_u32 v53, v57, v48, 10
	s_add_i32 s65, s61, 24
	s_add_i32 s61, s61, 28
	v_mov_b32_e32 v150, v52
	v_mov_b32_e32 v151, v54
	v_add_lshl_u32 v4, v56, v3, 10
	v_or_b32_e32 v52, v49, v4
	v_or_b32_e32 v4, v50, v53
	v_lshl_add_u64 v[54:55], v[4:5], 2, s[16:17]
	v_mov_b32_e32 v53, v5
	v_lshl_add_u64 v[52:53], v[52:53], 2, s[16:17]
	global_load_dword v136, v[54:55], off nt
	global_load_dword v137, v[52:53], off nt
	v_mad_u64_u32 v[52:53], s[66:67], v57, s40, v[2:3]
	v_mad_u64_u32 v[54:55], s[66:67], v56, s40, v[2:3]
	s_add_i32 s66, s64, 24
	v_or_b32_e32 v56, s65, v1
	v_or_b32_e32 v57, s66, v0
	v_add_lshl_u32 v53, v57, v48, 10
	s_add_i32 s64, s64, 28
	s_cmp_lg_u32 s60, 0
	v_mov_b32_e32 v152, v52
	v_mov_b32_e32 v153, v54
	v_add_lshl_u32 v4, v56, v3, 10
	v_or_b32_e32 v52, v49, v4
	v_or_b32_e32 v4, v50, v53
	v_lshl_add_u64 v[54:55], v[4:5], 2, s[16:17]
	v_mov_b32_e32 v53, v5
	v_lshl_add_u64 v[52:53], v[52:53], 2, s[16:17]
	global_load_dword v138, v[54:55], off nt
	global_load_dword v139, v[52:53], off nt
	v_mad_u64_u32 v[52:53], s[66:67], v57, s40, v[2:3]
	v_mad_u64_u32 v[54:55], s[66:67], v56, s40, v[2:3]
	v_or_b32_e32 v56, s61, v1
	v_or_b32_e32 v57, s64, v0
	v_mov_b32_e32 v55, v5
	v_mov_b32_e32 v154, v52
	v_mov_b32_e32 v155, v54
	v_add_lshl_u32 v4, v56, v3, 10
	v_add_lshl_u32 v52, v57, v48, 10
	v_or_b32_e32 v54, v49, v4
	v_or_b32_e32 v4, v50, v52
	v_lshl_add_u64 v[52:53], v[4:5], 2, s[16:17]
	v_lshl_add_u64 v[54:55], v[54:55], 2, s[16:17]
	global_load_dword v140, v[52:53], off nt
	global_load_dword v141, v[54:55], off nt
	v_mad_u64_u32 v[52:53], s[64:65], v57, s40, v[2:3]
	v_mad_u64_u32 v[54:55], s[64:65], v56, s40, v[2:3]
	v_mov_b32_e32 v156, v52
	v_mov_b32_e32 v157, v54
	s_waitcnt vmcnt(15)
	ds_write_b32 v142, v126
	s_waitcnt vmcnt(14)
	ds_write_b32 v143, v127
	s_waitcnt vmcnt(13)
	ds_write_b32 v144, v128
	s_waitcnt vmcnt(12)
	ds_write_b32 v145, v129
	s_waitcnt vmcnt(11)
	ds_write_b32 v146, v130
	s_waitcnt vmcnt(10)
	ds_write_b32 v147, v131
	s_waitcnt vmcnt(9)
	ds_write_b32 v148, v132
	s_waitcnt vmcnt(8)
	ds_write_b32 v149, v133
	s_waitcnt vmcnt(7)
	ds_write_b32 v150, v134
	s_waitcnt vmcnt(6)
	ds_write_b32 v151, v135
	s_waitcnt vmcnt(5)
	ds_write_b32 v152, v136
	s_waitcnt vmcnt(4)
	ds_write_b32 v153, v137
	s_waitcnt vmcnt(3)
	ds_write_b32 v154, v138
	s_waitcnt vmcnt(2)
	ds_write_b32 v155, v139
	s_waitcnt vmcnt(1)
	ds_write_b32 v156, v140
	s_waitcnt vmcnt(0)
	ds_write_b32 v157, v141
	s_cbranch_scc1 .LBB0_2644
	v_or_b32_e32 v3, v51, v96
	v_lshlrev_b32_e32 v4, 2, v3
	v_or_b32_e32 v49, 0x2000, v4
	global_load_dword v90, v49, s[92:93]
	global_load_dword v80, v49, s[94:95]
	v_or_b32_e32 v49, 0x2020, v4
	global_load_dword v62, v49, s[92:93]
	global_load_dword v60, v49, s[94:95]
	v_or_b32_e32 v49, 0x2040, v4
	global_load_dword v58, v49, s[92:93]
	global_load_dword v56, v49, s[94:95]
	v_or_b32_e32 v4, 0x2060, v4
	global_load_dword v52, v4, s[92:93]
	global_load_dword v50, v4, s[94:95]
	s_waitcnt lgkmcnt(0)
	ds_read2_b32 v[74:75], v97 offset0:33 offset1:41
	ds_read2_b32 v[66:67], v97 offset0:66 offset1:74
	ds_read2_b32 v[64:65], v97 offset0:99 offset1:107
	ds_read2_b32 v[76:77], v97 offset0:132 offset1:140
	ds_read2_b32 v[72:73], v97 offset0:165 offset1:173
	ds_read2_b32 v[70:71], v97 offset0:198 offset1:206
	ds_read2_b32 v[68:69], v97 offset0:231 offset1:239
	ds_read2_b32 v[78:79], v97 offset1:8
	s_waitcnt lgkmcnt(4)
	v_mov_b32_e32 v86, v76
	v_mov_b32_e32 v83, v66
	s_waitcnt lgkmcnt(2)
	v_mov_b32_e32 v87, v70
	v_mov_b32_e32 v84, v74
	s_waitcnt lgkmcnt(0)
	v_mov_b32_e32 v82, v78
	v_mov_b32_e32 v85, v64
	v_mov_b32_e32 v88, v72
	v_mov_b32_e32 v89, v68
	v_lshlrev_b32_e32 v4, 1, v48
	v_lshl_add_u64 v[54:55], v[8:9], 0, v[4:5]
	v_lshl_add_u64 v[48:49], v[24:25], 0, v[4:5]
	v_mov_b32_e32 v70, v77
	v_mov_b32_e32 v68, v73
	s_waitcnt vmcnt(7)
	v_pk_mul_f32 v[112:113], v[90:91], v[86:87] op_sel_hi:[0,1]
	v_pk_mul_f32 v[92:93], v[90:91], v[82:83] op_sel_hi:[0,1]
	v_pk_mul_f32 v[110:111], v[90:91], v[84:85] op_sel_hi:[0,1]
	v_pk_mul_f32 v[90:91], v[90:91], v[88:89] op_sel_hi:[0,1]
	v_bfe_u32 v64, v112, 16, 1
	v_bfe_u32 v66, v113, 16, 1
	v_bfe_u32 v4, v91, 16, 1
	v_bfe_u32 v53, v90, 16, 1
	v_bfe_u32 v63, v93, 16, 1
	v_add3_u32 v66, v113, v66, s46
	v_add3_u32 v64, v112, v64, s46
	v_bfe_u32 v57, v111, 16, 1
	v_add3_u32 v53, v90, v53, s46
	v_add3_u32 v4, v91, v4, s46
	v_bfe_u32 v61, v92, 16, 1
	v_add3_u32 v63, v93, v63, s46
	v_lshrrev_b32_e32 v64, 16, v64
	v_lshrrev_b32_e32 v66, 16, v66
	s_waitcnt vmcnt(6)
	v_pk_mul_f32 v[86:87], v[80:81], v[86:87] op_sel_hi:[0,1]
	v_bfe_u32 v59, v110, 16, 1
	v_add3_u32 v57, v111, v57, s46
	v_add3_u32 v61, v92, v61, s46
	v_lshrrev_b32_e32 v63, 16, v63
	v_and_or_b32 v93, v4, s47, v66
	v_and_or_b32 v92, v53, s47, v64
	v_pk_mul_f32 v[82:83], v[80:81], v[82:83] op_sel_hi:[0,1]
	v_pk_mul_f32 v[84:85], v[80:81], v[84:85] op_sel_hi:[0,1]
	v_pk_mul_f32 v[80:81], v[80:81], v[88:89] op_sel_hi:[0,1]
	v_bfe_u32 v64, v86, 16, 1
	v_bfe_u32 v66, v87, 16, 1
	v_add3_u32 v59, v110, v59, s46
	v_lshrrev_b32_e32 v61, 16, v61
	v_and_or_b32 v91, v57, s47, v63
	v_lshlrev_b32_e32 v4, 11, v3
	v_bfe_u32 v3, v81, 16, 1
	v_bfe_u32 v53, v80, 16, 1
	v_bfe_u32 v63, v83, 16, 1
	v_add3_u32 v66, v87, v66, s46
	v_add3_u32 v64, v86, v64, s46
	v_and_or_b32 v90, v59, s47, v61
	v_bfe_u32 v57, v85, 16, 1
	v_add3_u32 v53, v80, v53, s46
	v_add3_u32 v3, v81, v3, s46
	v_bfe_u32 v61, v82, 16, 1
	v_add3_u32 v63, v83, v63, s46
	v_lshrrev_b32_e32 v64, 16, v64
	v_lshrrev_b32_e32 v66, 16, v66
	v_add3_u32 v57, v85, v57, s46
	v_add3_u32 v61, v82, v61, s46
	v_lshrrev_b32_e32 v63, 16, v63
	v_and_or_b32 v83, v3, s47, v66
	v_and_or_b32 v82, v53, s47, v64
	v_mov_b32_e32 v66, v79
	v_mov_b32_e32 v64, v75
	v_and_or_b32 v81, v57, s47, v63
	s_waitcnt vmcnt(5)
	v_pk_mul_f32 v[78:79], v[62:63], v[66:67] op_sel_hi:[0,1]
	v_pk_mul_f32 v[74:75], v[62:63], v[64:65] op_sel_hi:[0,1]
	v_pk_mul_f32 v[76:77], v[62:63], v[70:71] op_sel_hi:[0,1]
	v_pk_mul_f32 v[62:63], v[62:63], v[68:69] op_sel_hi:[0,1]
	v_bfe_u32 v59, v84, 16, 1
	v_bfe_u32 v3, v63, 16, 1
	v_lshl_add_u64 v[110:111], v[54:55], 0, v[4:5]
	v_add3_u32 v59, v84, v59, s46
	v_lshl_add_u64 v[84:85], v[48:49], 0, v[4:5]
	v_bfe_u32 v4, v62, 16, 1
	v_add3_u32 v3, v63, v3, s46
	v_bfe_u32 v63, v77, 16, 1
	v_lshrrev_b32_e32 v61, 16, v61
	v_add3_u32 v4, v62, v4, s46
	v_bfe_u32 v62, v76, 16, 1
	v_add3_u32 v63, v77, v63, s46
	v_and_or_b32 v80, v59, s47, v61
	v_bfe_u32 v53, v75, 16, 1
	v_bfe_u32 v59, v78, 16, 1
	v_bfe_u32 v61, v79, 16, 1
	v_add3_u32 v62, v76, v62, s46
	v_lshrrev_b32_e32 v63, 16, v63
	v_bfe_u32 v57, v74, 16, 1
	v_add3_u32 v53, v75, v53, s46
	v_add3_u32 v61, v79, v61, s46
	v_add3_u32 v59, v78, v59, s46
	v_lshrrev_b32_e32 v62, 16, v62
	v_and_or_b32 v75, v3, s47, v63
	v_or_b32_e32 v3, v51, v98
	v_add3_u32 v57, v74, v57, s46
	v_lshrrev_b32_e32 v59, 16, v59
	v_lshrrev_b32_e32 v61, 16, v61
	v_and_or_b32 v74, v4, s47, v62
	v_lshlrev_b32_e32 v4, 11, v3
	v_and_or_b32 v73, v53, s47, v61
	v_and_or_b32 v72, v57, s47, v59
	v_lshl_add_u64 v[62:63], v[54:55], 0, v[4:5]
	global_store_dwordx4 v[62:63], v[72:75], off
	s_waitcnt vmcnt(5)
	v_pk_mul_f32 v[62:63], v[60:61], v[66:67] op_sel_hi:[0,1]
	v_pk_mul_f32 v[64:65], v[60:61], v[64:65] op_sel_hi:[0,1]
	v_pk_mul_f32 v[66:67], v[60:61], v[70:71] op_sel_hi:[0,1]
	v_pk_mul_f32 v[60:61], v[60:61], v[68:69] op_sel_hi:[0,1]
	v_bfe_u32 v3, v61, 16, 1
	v_bfe_u32 v53, v60, 16, 1
	v_bfe_u32 v57, v65, 16, 1
	v_bfe_u32 v59, v64, 16, 1
	v_add3_u32 v59, v64, v59, s46
	v_add3_u32 v57, v65, v57, s46
	v_add3_u32 v53, v60, v53, s46
	v_add3_u32 v3, v61, v3, s46
	v_bfe_u32 v60, v62, 16, 1
	v_bfe_u32 v61, v63, 16, 1
	v_bfe_u32 v64, v66, 16, 1
	v_bfe_u32 v65, v67, 16, 1
	v_add3_u32 v65, v67, v65, s46
	v_add3_u32 v64, v66, v64, s46
	v_add3_u32 v61, v63, v61, s46
	v_add3_u32 v60, v62, v60, s46
	v_lshrrev_b32_e32 v60, 16, v60
	v_lshrrev_b32_e32 v61, 16, v61
	v_lshrrev_b32_e32 v62, 16, v64
	v_lshrrev_b32_e32 v63, 16, v65
	v_and_or_b32 v63, v3, s47, v63
	v_and_or_b32 v62, v53, s47, v62
	v_and_or_b32 v61, v57, s47, v61
	v_and_or_b32 v60, v59, s47, v60
	v_lshl_add_u64 v[64:65], v[48:49], 0, v[4:5]
	global_store_dwordx4 v[110:111], v[90:93], off
	global_store_dwordx4 v[84:85], v[80:83], off
	global_store_dwordx4 v[64:65], v[60:63], off
	ds_read2_b32 v[62:63], v97 offset0:49 offset1:57
	ds_read2_b32 v[64:65], v97 offset0:82 offset1:90
	ds_read2_b32 v[66:67], v97 offset0:115 offset1:123
	ds_read2_b32 v[68:69], v97 offset0:148 offset1:156
	ds_read2_b32 v[70:71], v97 offset0:181 offset1:189
	ds_read2_b32 v[72:73], v97 offset0:214 offset1:222
	ds_read2_b32 v[74:75], v97 offset0:247 offset1:255
	ds_read2_b32 v[76:77], v97 offset0:16 offset1:24
	s_waitcnt lgkmcnt(6)
	v_mov_b32_e32 v79, v64
	v_mov_b32_e32 v80, v62
	s_waitcnt lgkmcnt(5)
	v_mov_b32_e32 v81, v66
	s_waitcnt lgkmcnt(4)
	v_mov_b32_e32 v84, v68
	s_waitcnt lgkmcnt(0)
	v_mov_b32_e32 v78, v76
	v_mov_b32_e32 v85, v72
	v_mov_b32_e32 v88, v70
	v_mov_b32_e32 v89, v74
	s_waitcnt vmcnt(7)
	v_pk_mul_f32 v[60:61], v[58:59], v[78:79] op_sel_hi:[0,1]
	v_pk_mul_f32 v[82:83], v[58:59], v[80:81] op_sel_hi:[0,1]
	v_pk_mul_f32 v[86:87], v[58:59], v[84:85] op_sel_hi:[0,1]
	v_pk_mul_f32 v[58:59], v[58:59], v[88:89] op_sel_hi:[0,1]
	v_bfe_u32 v3, v59, 16, 1
	v_bfe_u32 v64, v87, 16, 1
	v_bfe_u32 v4, v58, 16, 1
	v_add3_u32 v3, v59, v3, s46
	v_bfe_u32 v59, v61, 16, 1
	v_bfe_u32 v62, v86, 16, 1
	v_add3_u32 v64, v87, v64, s46
	v_add3_u32 v4, v58, v4, s46
	v_bfe_u32 v58, v60, 16, 1
	v_add3_u32 v62, v86, v62, s46
	v_add3_u32 v59, v61, v59, s46
	v_lshrrev_b32_e32 v61, 16, v64
	v_bfe_u32 v53, v83, 16, 1
	v_bfe_u32 v57, v82, 16, 1
	v_add3_u32 v58, v60, v58, s46
	v_lshrrev_b32_e32 v60, 16, v62
	v_and_or_b32 v61, v3, s47, v61
	v_or_b32_e32 v3, v51, v99
	v_add3_u32 v57, v82, v57, s46
	v_add3_u32 v53, v83, v53, s46
	v_lshrrev_b32_e32 v58, 16, v58
	v_lshrrev_b32_e32 v59, 16, v59
	v_and_or_b32 v60, v4, s47, v60
	v_lshlrev_b32_e32 v4, 11, v3
	v_and_or_b32 v59, v53, s47, v59
	v_and_or_b32 v58, v57, s47, v58
	v_lshl_add_u64 v[82:83], v[54:55], 0, v[4:5]
	global_store_dwordx4 v[82:83], v[58:61], off
	v_mov_b32_e32 v66, v63
	v_mov_b32_e32 v72, v69
	s_waitcnt vmcnt(7)
	v_pk_mul_f32 v[58:59], v[56:57], v[78:79] op_sel_hi:[0,1]
	v_pk_mul_f32 v[60:61], v[56:57], v[80:81] op_sel_hi:[0,1]
	v_pk_mul_f32 v[78:79], v[56:57], v[84:85] op_sel_hi:[0,1]
	v_pk_mul_f32 v[56:57], v[56:57], v[88:89] op_sel_hi:[0,1]
	v_bfe_u32 v3, v57, 16, 1
	v_bfe_u32 v53, v56, 16, 1
	v_bfe_u32 v62, v61, 16, 1
	v_bfe_u32 v64, v60, 16, 1
	v_add3_u32 v60, v60, v64, s46
	v_add3_u32 v61, v61, v62, s46
	v_add3_u32 v53, v56, v53, s46
	v_add3_u32 v3, v57, v3, s46
	v_bfe_u32 v56, v58, 16, 1
	v_bfe_u32 v57, v59, 16, 1
	v_bfe_u32 v62, v78, 16, 1
	v_bfe_u32 v64, v79, 16, 1
	v_add3_u32 v64, v79, v64, s46
	v_add3_u32 v62, v78, v62, s46
	v_add3_u32 v57, v59, v57, s46
	v_add3_u32 v56, v58, v56, s46
	v_lshrrev_b32_e32 v56, 16, v56
	v_lshrrev_b32_e32 v57, 16, v57
	v_lshrrev_b32_e32 v58, 16, v62
	v_lshrrev_b32_e32 v59, 16, v64
	v_and_or_b32 v59, v3, s47, v59
	v_and_or_b32 v58, v53, s47, v58
	v_and_or_b32 v57, v61, s47, v57
	v_and_or_b32 v56, v60, s47, v56
	v_lshl_add_u64 v[60:61], v[48:49], 0, v[4:5]
	global_store_dwordx4 v[60:61], v[56:59], off
	v_mov_b32_e32 v64, v77
	v_mov_b32_e32 v74, v71
	s_waitcnt vmcnt(7)
	v_pk_mul_f32 v[58:59], v[52:53], v[66:67] op_sel_hi:[0,1]
	v_pk_mul_f32 v[56:57], v[52:53], v[64:65] op_sel_hi:[0,1]
	v_pk_mul_f32 v[60:61], v[52:53], v[72:73] op_sel_hi:[0,1]
	v_pk_mul_f32 v[52:53], v[52:53], v[74:75] op_sel_hi:[0,1]
	v_bfe_u32 v62, v59, 16, 1
	v_bfe_u32 v3, v53, 16, 1
	v_bfe_u32 v63, v58, 16, 1
	v_add3_u32 v62, v59, v62, s46
	v_bfe_u32 v59, v61, 16, 1
	v_bfe_u32 v4, v52, 16, 1
	v_add3_u32 v63, v58, v63, s46
	v_add3_u32 v3, v53, v3, s46
	v_bfe_u32 v53, v57, 16, 1
	v_bfe_u32 v58, v60, 16, 1
	v_add3_u32 v59, v61, v59, s46
	v_add3_u32 v4, v52, v4, s46
	v_bfe_u32 v52, v56, 16, 1
	v_add3_u32 v58, v60, v58, s46
	v_add3_u32 v53, v57, v53, s46
	v_lshrrev_b32_e32 v57, 16, v59
	v_add3_u32 v52, v56, v52, s46
	v_lshrrev_b32_e32 v56, 16, v58
	v_and_or_b32 v59, v3, s47, v57
	v_or_b32_e32 v3, v51, v100
	v_lshrrev_b32_e32 v52, 16, v52
	v_lshrrev_b32_e32 v53, 16, v53
	v_and_or_b32 v58, v4, s47, v56
	v_lshlrev_b32_e32 v4, 11, v3
	v_and_or_b32 v57, v62, s47, v53
	v_and_or_b32 v56, v63, s47, v52
	v_lshl_add_u64 v[52:53], v[54:55], 0, v[4:5]
	global_store_dwordx4 v[52:53], v[56:59], off
	s_waitcnt vmcnt(7)
	v_pk_mul_f32 v[52:53], v[50:51], v[64:65] op_sel_hi:[0,1]
	v_pk_mul_f32 v[54:55], v[50:51], v[66:67] op_sel_hi:[0,1]
	v_pk_mul_f32 v[56:57], v[50:51], v[72:73] op_sel_hi:[0,1]
	v_pk_mul_f32 v[50:51], v[50:51], v[74:75] op_sel_hi:[0,1]
	v_bfe_u32 v3, v51, 16, 1
	v_bfe_u32 v58, v50, 16, 1
	v_bfe_u32 v59, v55, 16, 1
	v_bfe_u32 v60, v54, 16, 1
	v_add3_u32 v54, v54, v60, s46
	v_add3_u32 v55, v55, v59, s46
	v_add3_u32 v50, v50, v58, s46
	v_add3_u32 v3, v51, v3, s46
	v_bfe_u32 v51, v52, 16, 1
	v_bfe_u32 v58, v53, 16, 1
	v_bfe_u32 v59, v56, 16, 1
	v_bfe_u32 v60, v57, 16, 1
	v_add3_u32 v57, v57, v60, s46
	v_add3_u32 v56, v56, v59, s46
	v_add3_u32 v53, v53, v58, s46
	v_add3_u32 v51, v52, v51, s46
	v_lshrrev_b32_e32 v58, 16, v51
	v_lshrrev_b32_e32 v51, 16, v53
	v_lshrrev_b32_e32 v52, 16, v56
	v_lshrrev_b32_e32 v53, 16, v57
	v_and_or_b32 v53, v3, s47, v53
	v_and_or_b32 v52, v50, s47, v52
	v_and_or_b32 v51, v55, s47, v51
	v_and_or_b32 v50, v54, s47, v58
	v_lshl_add_u64 v[48:49], v[48:49], 0, v[4:5]
	global_store_dwordx4 v[48:49], v[50:53], off
	s_waitcnt lgkmcnt(0)

.LBB0_2649:
	s_lshl_b32 s55, s48, 1
	s_lshl_b32 s60, s49, 1
	v_or_b32_e32 v56, s55, v1
	v_or_b32_e32 v57, s60, v0
	v_add_lshl_u32 v4, v56, v3, 10
	v_add_lshl_u32 v53, v57, v48, 10
	v_or_b32_e32 v52, v49, v4
	v_or_b32_e32 v4, v50, v53
	v_lshl_add_u64 v[54:55], v[4:5], 2, s[6:7]
	v_mov_b32_e32 v53, v5
	v_lshl_add_u64 v[52:53], v[52:53], 2, s[6:7]
	global_load_dword v126, v[54:55], off nt
	global_load_dword v127, v[52:53], off nt
	v_mad_u64_u32 v[52:53], s[64:65], v57, s40, v[2:3]
	v_mad_u64_u32 v[54:55], s[64:65], v56, s40, v[2:3]
	s_add_i32 s61, s55, 4
	s_add_i32 s64, s60, 4
	v_or_b32_e32 v56, s61, v1
	v_or_b32_e32 v57, s64, v0
	v_add_lshl_u32 v53, v57, v48, 10
	s_add_i32 s61, s55, 8
	s_add_i32 s49, s49, 16
	s_add_i32 s48, s48, 16
	s_add_i32 s54, s54, -16
	v_mov_b32_e32 v142, v52
	v_mov_b32_e32 v143, v54
	v_add_lshl_u32 v4, v56, v3, 10
	v_or_b32_e32 v52, v49, v4
	v_or_b32_e32 v4, v50, v53
	v_lshl_add_u64 v[54:55], v[4:5], 2, s[6:7]
	v_mov_b32_e32 v53, v5
	v_lshl_add_u64 v[52:53], v[52:53], 2, s[6:7]
	global_load_dword v128, v[54:55], off nt
	global_load_dword v129, v[52:53], off nt
	v_mad_u64_u32 v[52:53], s[64:65], v57, s40, v[2:3]
	v_mad_u64_u32 v[54:55], s[64:65], v56, s40, v[2:3]
	s_add_i32 s64, s60, 8
	v_or_b32_e32 v56, s61, v1
	v_or_b32_e32 v57, s64, v0
	v_add_lshl_u32 v53, v57, v48, 10
	s_add_i32 s61, s55, 12
	v_mov_b32_e32 v144, v52
	v_mov_b32_e32 v145, v54
	v_add_lshl_u32 v4, v56, v3, 10
	v_or_b32_e32 v52, v49, v4
	v_or_b32_e32 v4, v50, v53
	v_lshl_add_u64 v[54:55], v[4:5], 2, s[6:7]
	v_mov_b32_e32 v53, v5
	v_lshl_add_u64 v[52:53], v[52:53], 2, s[6:7]
	global_load_dword v130, v[54:55], off nt
	global_load_dword v131, v[52:53], off nt
	v_mad_u64_u32 v[52:53], s[64:65], v57, s40, v[2:3]
	v_mad_u64_u32 v[54:55], s[64:65], v56, s40, v[2:3]
	s_add_i32 s64, s60, 12
	v_or_b32_e32 v56, s61, v1
	v_or_b32_e32 v57, s64, v0
	v_add_lshl_u32 v53, v57, v48, 10
	s_add_i32 s61, s55, 16
	v_mov_b32_e32 v146, v52
	v_mov_b32_e32 v147, v54
	v_add_lshl_u32 v4, v56, v3, 10
	v_or_b32_e32 v52, v49, v4
	v_or_b32_e32 v4, v50, v53
	v_lshl_add_u64 v[54:55], v[4:5], 2, s[6:7]
	v_mov_b32_e32 v53, v5
	v_lshl_add_u64 v[52:53], v[52:53], 2, s[6:7]
	global_load_dword v132, v[54:55], off nt
	global_load_dword v133, v[52:53], off nt
	v_mad_u64_u32 v[52:53], s[64:65], v57, s40, v[2:3]
	v_mad_u64_u32 v[54:55], s[64:65], v56, s40, v[2:3]
	s_add_i32 s64, s60, 16
	v_or_b32_e32 v56, s61, v1
	v_or_b32_e32 v57, s64, v0
	v_add_lshl_u32 v53, v57, v48, 10
	s_add_i32 s61, s55, 20
	v_mov_b32_e32 v148, v52
	v_mov_b32_e32 v149, v54
	v_add_lshl_u32 v4, v56, v3, 10
	v_or_b32_e32 v52, v49, v4
	v_or_b32_e32 v4, v50, v53
	v_lshl_add_u64 v[54:55], v[4:5], 2, s[6:7]
	v_mov_b32_e32 v53, v5
	v_lshl_add_u64 v[52:53], v[52:53], 2, s[6:7]
	global_load_dword v134, v[54:55], off nt
	global_load_dword v135, v[52:53], off nt
	v_mad_u64_u32 v[52:53], s[64:65], v57, s40, v[2:3]
	v_mad_u64_u32 v[54:55], s[64:65], v56, s40, v[2:3]
	s_add_i32 s64, s60, 20
	v_or_b32_e32 v56, s61, v1
	v_or_b32_e32 v57, s64, v0
	v_add_lshl_u32 v53, v57, v48, 10
	s_add_i32 s61, s55, 24
	s_add_i32 s55, s55, 28
	v_mov_b32_e32 v150, v52
	v_mov_b32_e32 v151, v54
	v_add_lshl_u32 v4, v56, v3, 10
	v_or_b32_e32 v52, v49, v4
	v_or_b32_e32 v4, v50, v53
	v_lshl_add_u64 v[54:55], v[4:5], 2, s[6:7]
	v_mov_b32_e32 v53, v5
	v_lshl_add_u64 v[52:53], v[52:53], 2, s[6:7]
	global_load_dword v136, v[54:55], off nt
	global_load_dword v137, v[52:53], off nt
	v_mad_u64_u32 v[52:53], s[64:65], v57, s40, v[2:3]
	v_mad_u64_u32 v[54:55], s[64:65], v56, s40, v[2:3]
	s_add_i32 s64, s60, 24
	v_or_b32_e32 v56, s61, v1
	v_or_b32_e32 v57, s64, v0
	v_add_lshl_u32 v53, v57, v48, 10
	s_add_i32 s60, s60, 28
	s_cmp_lg_u32 s54, 0
	v_mov_b32_e32 v152, v52
	v_mov_b32_e32 v153, v54
	v_add_lshl_u32 v4, v56, v3, 10
	v_or_b32_e32 v52, v49, v4
	v_or_b32_e32 v4, v50, v53
	v_lshl_add_u64 v[54:55], v[4:5], 2, s[6:7]
	v_mov_b32_e32 v53, v5
	v_lshl_add_u64 v[52:53], v[52:53], 2, s[6:7]
	global_load_dword v138, v[54:55], off nt
	global_load_dword v139, v[52:53], off nt
	v_mad_u64_u32 v[52:53], s[64:65], v57, s40, v[2:3]
	v_mad_u64_u32 v[54:55], s[64:65], v56, s40, v[2:3]
	v_or_b32_e32 v56, s55, v1
	v_or_b32_e32 v57, s60, v0
	v_mov_b32_e32 v55, v5
	v_mov_b32_e32 v154, v52
	v_mov_b32_e32 v155, v54
	v_add_lshl_u32 v4, v56, v3, 10
	v_add_lshl_u32 v52, v57, v48, 10
	v_or_b32_e32 v54, v49, v4
	v_or_b32_e32 v4, v50, v52
	v_lshl_add_u64 v[52:53], v[4:5], 2, s[6:7]
	v_lshl_add_u64 v[54:55], v[54:55], 2, s[6:7]
	global_load_dword v140, v[52:53], off nt
	global_load_dword v141, v[54:55], off nt
	v_mad_u64_u32 v[52:53], s[60:61], v57, s40, v[2:3]
	v_mad_u64_u32 v[54:55], s[60:61], v56, s40, v[2:3]
	v_mov_b32_e32 v156, v52
	v_mov_b32_e32 v157, v54
	s_waitcnt vmcnt(15)
	ds_write_b32 v142, v126
	s_waitcnt vmcnt(14)
	ds_write_b32 v143, v127
	s_waitcnt vmcnt(13)
	ds_write_b32 v144, v128
	s_waitcnt vmcnt(12)
	ds_write_b32 v145, v129
	s_waitcnt vmcnt(11)
	ds_write_b32 v146, v130
	s_waitcnt vmcnt(10)
	ds_write_b32 v147, v131
	s_waitcnt vmcnt(9)
	ds_write_b32 v148, v132
	s_waitcnt vmcnt(8)
	ds_write_b32 v149, v133
	s_waitcnt vmcnt(7)
	ds_write_b32 v150, v134
	s_waitcnt vmcnt(6)
	ds_write_b32 v151, v135
	s_waitcnt vmcnt(5)
	ds_write_b32 v152, v136
	s_waitcnt vmcnt(4)
	ds_write_b32 v153, v137
	s_waitcnt vmcnt(3)
	ds_write_b32 v154, v138
	s_waitcnt vmcnt(2)
	ds_write_b32 v155, v139
	s_waitcnt vmcnt(1)
	ds_write_b32 v156, v140
	s_waitcnt vmcnt(0)
	ds_write_b32 v157, v141
	s_cbranch_scc1 .LBB0_2649
	s_waitcnt lgkmcnt(0)
	ds_read2_b32 v[56:57], v97 offset0:33 offset1:41
	ds_read2_b32 v[58:59], v97 offset0:66 offset1:74
	ds_read2_b32 v[60:61], v97 offset0:99 offset1:107
	ds_read2_b32 v[62:63], v97 offset1:8
	ds_read2_b32 v[64:65], v97 offset0:132 offset1:140
	ds_read2_b32 v[66:67], v97 offset0:165 offset1:173
	ds_read2_b32 v[68:69], v97 offset0:198 offset1:206
	ds_read2_b32 v[70:71], v97 offset0:231 offset1:239
	v_lshlrev_b32_e32 v4, 1, v48
	s_waitcnt lgkmcnt(4)
	v_bfe_u32 v3, v62, 16, 1
	v_lshl_add_u64 v[48:49], v[10:11], 0, v[4:5]
	v_add3_u32 v3, v62, v3, s46
	v_bfe_u32 v4, v56, 16, 1
	v_lshrrev_b32_e32 v3, 16, v3
	v_add3_u32 v4, v56, v4, s46
	v_and_or_b32 v52, v4, s47, v3
	v_bfe_u32 v3, v58, 16, 1
	v_add3_u32 v3, v58, v3, s46
	v_bfe_u32 v4, v60, 16, 1
	v_lshrrev_b32_e32 v3, 16, v3
	v_add3_u32 v4, v60, v4, s46
	v_and_or_b32 v53, v4, s47, v3
	s_waitcnt lgkmcnt(3)
	v_bfe_u32 v3, v64, 16, 1
	v_add3_u32 v3, v64, v3, s46
	s_waitcnt lgkmcnt(2)
	v_bfe_u32 v4, v66, 16, 1
	v_lshrrev_b32_e32 v3, 16, v3
	v_add3_u32 v4, v66, v4, s46
	v_and_or_b32 v54, v4, s47, v3
	s_waitcnt lgkmcnt(1)
	v_bfe_u32 v3, v68, 16, 1
	v_add3_u32 v3, v68, v3, s46
	s_waitcnt lgkmcnt(0)
	v_bfe_u32 v4, v70, 16, 1
	v_lshrrev_b32_e32 v3, 16, v3
	v_add3_u32 v4, v70, v4, s46
	v_and_or_b32 v55, v4, s47, v3
	v_or_b32_e32 v3, v51, v96
	v_lshlrev_b32_e32 v4, 9, v3
	v_bfe_u32 v3, v63, 16, 1
	v_lshl_add_u64 v[72:73], v[48:49], 0, v[4:5]
	v_add3_u32 v3, v63, v3, s46
	v_bfe_u32 v4, v57, 16, 1
	v_lshrrev_b32_e32 v3, 16, v3
	v_add3_u32 v4, v57, v4, s46
	global_store_dwordx4 v[72:73], v[52:55], off
	s_nop 1
	v_and_or_b32 v52, v4, s47, v3
	v_bfe_u32 v3, v59, 16, 1
	v_add3_u32 v3, v59, v3, s46
	v_bfe_u32 v4, v61, 16, 1
	v_lshrrev_b32_e32 v3, 16, v3
	v_add3_u32 v4, v61, v4, s46
	v_and_or_b32 v53, v4, s47, v3
	v_bfe_u32 v3, v65, 16, 1
	v_add3_u32 v3, v65, v3, s46
	v_bfe_u32 v4, v67, 16, 1
	v_lshrrev_b32_e32 v3, 16, v3
	v_add3_u32 v4, v67, v4, s46
	v_and_or_b32 v54, v4, s47, v3
	v_bfe_u32 v3, v69, 16, 1
	v_add3_u32 v3, v69, v3, s46
	v_bfe_u32 v4, v71, 16, 1
	v_lshrrev_b32_e32 v3, 16, v3
	v_add3_u32 v4, v71, v4, s46
	v_and_or_b32 v55, v4, s47, v3
	v_or_b32_e32 v3, v51, v98
	v_lshlrev_b32_e32 v4, 9, v3
	v_lshl_add_u64 v[56:57], v[48:49], 0, v[4:5]
	global_store_dwordx4 v[56:57], v[52:55], off
	ds_read2_b32 v[56:57], v97 offset0:49 offset1:57
	ds_read2_b32 v[58:59], v97 offset0:82 offset1:90
	ds_read2_b32 v[60:61], v97 offset0:115 offset1:123
	ds_read2_b32 v[62:63], v97 offset0:16 offset1:24
	ds_read2_b32 v[64:65], v97 offset0:148 offset1:156
	ds_read2_b32 v[66:67], v97 offset0:181 offset1:189
	ds_read2_b32 v[68:69], v97 offset0:214 offset1:222
	ds_read2_b32 v[70:71], v97 offset0:247 offset1:255
	s_waitcnt lgkmcnt(4)
	v_bfe_u32 v3, v62, 16, 1
	v_add3_u32 v3, v62, v3, s46
	v_bfe_u32 v4, v56, 16, 1
	v_lshrrev_b32_e32 v3, 16, v3
	v_add3_u32 v4, v56, v4, s46
	v_and_or_b32 v52, v4, s47, v3
	v_bfe_u32 v3, v58, 16, 1
	v_add3_u32 v3, v58, v3, s46
	v_bfe_u32 v4, v60, 16, 1
	v_lshrrev_b32_e32 v3, 16, v3
	v_add3_u32 v4, v60, v4, s46
	v_and_or_b32 v53, v4, s47, v3
	s_waitcnt lgkmcnt(3)
	v_bfe_u32 v3, v64, 16, 1
	v_add3_u32 v3, v64, v3, s46
	s_waitcnt lgkmcnt(2)
	v_bfe_u32 v4, v66, 16, 1
	v_lshrrev_b32_e32 v3, 16, v3
	v_add3_u32 v4, v66, v4, s46
	v_and_or_b32 v54, v4, s47, v3
	s_waitcnt lgkmcnt(1)
	v_bfe_u32 v3, v68, 16, 1
	v_add3_u32 v3, v68, v3, s46
	s_waitcnt lgkmcnt(0)
	v_bfe_u32 v4, v70, 16, 1
	v_lshrrev_b32_e32 v3, 16, v3
	v_add3_u32 v4, v70, v4, s46
	v_and_or_b32 v55, v4, s47, v3
	v_or_b32_e32 v3, v51, v99
	v_lshlrev_b32_e32 v4, 9, v3
	v_bfe_u32 v3, v63, 16, 1
	v_lshl_add_u64 v[72:73], v[48:49], 0, v[4:5]
	v_add3_u32 v3, v63, v3, s46
	v_bfe_u32 v4, v57, 16, 1
	v_lshrrev_b32_e32 v3, 16, v3
	v_add3_u32 v4, v57, v4, s46
	global_store_dwordx4 v[72:73], v[52:55], off
	s_nop 1
	v_and_or_b32 v52, v4, s47, v3
	v_bfe_u32 v3, v59, 16, 1
	v_add3_u32 v3, v59, v3, s46
	v_bfe_u32 v4, v61, 16, 1
	v_lshrrev_b32_e32 v3, 16, v3
	v_add3_u32 v4, v61, v4, s46
	v_and_or_b32 v53, v4, s47, v3
	v_bfe_u32 v3, v65, 16, 1
	v_add3_u32 v3, v65, v3, s46
	v_bfe_u32 v4, v67, 16, 1
	v_lshrrev_b32_e32 v3, 16, v3
	v_add3_u32 v4, v67, v4, s46
	v_and_or_b32 v54, v4, s47, v3
	v_bfe_u32 v3, v69, 16, 1
	v_add3_u32 v3, v69, v3, s46
	v_bfe_u32 v4, v71, 16, 1
	v_lshrrev_b32_e32 v3, 16, v3
	v_add3_u32 v4, v71, v4, s46
	v_and_or_b32 v55, v4, s47, v3
	v_or_b32_e32 v3, v51, v100
	v_lshlrev_b32_e32 v4, 9, v3
	v_lshl_add_u64 v[48:49], v[48:49], 0, v[4:5]
	global_store_dwordx4 v[48:49], v[52:55], off
	s_waitcnt lgkmcnt(0)

.LBB0_2654:
	s_lshl_b32 s49, s36, 1
	s_lshl_b32 s54, s37, 1
	v_or_b32_e32 v56, s49, v1
	v_or_b32_e32 v57, s54, v0
	v_add_lshl_u32 v4, v56, v3, 10
	v_add_lshl_u32 v53, v57, v48, 10
	v_or_b32_e32 v52, v49, v4
	v_or_b32_e32 v4, v50, v53
	v_lshl_add_u64 v[54:55], v[4:5], 2, s[4:5]
	v_mov_b32_e32 v53, v5
	v_lshl_add_u64 v[52:53], v[52:53], 2, s[4:5]
	global_load_dword v126, v[54:55], off nt
	global_load_dword v127, v[52:53], off nt
	v_mad_u64_u32 v[52:53], s[60:61], v57, s40, v[2:3]
	v_mad_u64_u32 v[54:55], s[60:61], v56, s40, v[2:3]
	s_add_i32 s55, s49, 4
	s_add_i32 s60, s54, 4
	v_or_b32_e32 v56, s55, v1
	v_or_b32_e32 v57, s60, v0
	v_add_lshl_u32 v53, v57, v48, 10
	s_add_i32 s55, s49, 8
	s_add_i32 s37, s37, 16
	s_add_i32 s36, s36, 16
	s_add_i32 s48, s48, -16
	v_mov_b32_e32 v142, v52
	v_mov_b32_e32 v143, v54
	v_add_lshl_u32 v4, v56, v3, 10
	v_or_b32_e32 v52, v49, v4
	v_or_b32_e32 v4, v50, v53
	v_lshl_add_u64 v[54:55], v[4:5], 2, s[4:5]
	v_mov_b32_e32 v53, v5
	v_lshl_add_u64 v[52:53], v[52:53], 2, s[4:5]
	global_load_dword v128, v[54:55], off nt
	global_load_dword v129, v[52:53], off nt
	v_mad_u64_u32 v[52:53], s[60:61], v57, s40, v[2:3]
	v_mad_u64_u32 v[54:55], s[60:61], v56, s40, v[2:3]
	s_add_i32 s60, s54, 8
	v_or_b32_e32 v56, s55, v1
	v_or_b32_e32 v57, s60, v0
	v_add_lshl_u32 v53, v57, v48, 10
	s_add_i32 s55, s49, 12
	v_mov_b32_e32 v144, v52
	v_mov_b32_e32 v145, v54
	v_add_lshl_u32 v4, v56, v3, 10
	v_or_b32_e32 v52, v49, v4
	v_or_b32_e32 v4, v50, v53
	v_lshl_add_u64 v[54:55], v[4:5], 2, s[4:5]
	v_mov_b32_e32 v53, v5
	v_lshl_add_u64 v[52:53], v[52:53], 2, s[4:5]
	global_load_dword v130, v[54:55], off nt
	global_load_dword v131, v[52:53], off nt
	v_mad_u64_u32 v[52:53], s[60:61], v57, s40, v[2:3]
	v_mad_u64_u32 v[54:55], s[60:61], v56, s40, v[2:3]
	s_add_i32 s60, s54, 12
	v_or_b32_e32 v56, s55, v1
	v_or_b32_e32 v57, s60, v0
	v_add_lshl_u32 v53, v57, v48, 10
	s_add_i32 s55, s49, 16
	v_mov_b32_e32 v146, v52
	v_mov_b32_e32 v147, v54
	v_add_lshl_u32 v4, v56, v3, 10
	v_or_b32_e32 v52, v49, v4
	v_or_b32_e32 v4, v50, v53
	v_lshl_add_u64 v[54:55], v[4:5], 2, s[4:5]
	v_mov_b32_e32 v53, v5
	v_lshl_add_u64 v[52:53], v[52:53], 2, s[4:5]
	global_load_dword v132, v[54:55], off nt
	global_load_dword v133, v[52:53], off nt
	v_mad_u64_u32 v[52:53], s[60:61], v57, s40, v[2:3]
	v_mad_u64_u32 v[54:55], s[60:61], v56, s40, v[2:3]
	s_add_i32 s60, s54, 16
	v_or_b32_e32 v56, s55, v1
	v_or_b32_e32 v57, s60, v0
	v_add_lshl_u32 v53, v57, v48, 10
	s_add_i32 s55, s49, 20
	v_mov_b32_e32 v148, v52
	v_mov_b32_e32 v149, v54
	v_add_lshl_u32 v4, v56, v3, 10
	v_or_b32_e32 v52, v49, v4
	v_or_b32_e32 v4, v50, v53
	v_lshl_add_u64 v[54:55], v[4:5], 2, s[4:5]
	v_mov_b32_e32 v53, v5
	v_lshl_add_u64 v[52:53], v[52:53], 2, s[4:5]
	global_load_dword v134, v[54:55], off nt
	global_load_dword v135, v[52:53], off nt
	v_mad_u64_u32 v[52:53], s[60:61], v57, s40, v[2:3]
	v_mad_u64_u32 v[54:55], s[60:61], v56, s40, v[2:3]
	s_add_i32 s60, s54, 20
	v_or_b32_e32 v56, s55, v1
	v_or_b32_e32 v57, s60, v0
	v_add_lshl_u32 v53, v57, v48, 10
	s_add_i32 s55, s49, 24
	s_add_i32 s49, s49, 28
	v_mov_b32_e32 v150, v52
	v_mov_b32_e32 v151, v54
	v_add_lshl_u32 v4, v56, v3, 10
	v_or_b32_e32 v52, v49, v4
	v_or_b32_e32 v4, v50, v53
	v_lshl_add_u64 v[54:55], v[4:5], 2, s[4:5]
	v_mov_b32_e32 v53, v5
	v_lshl_add_u64 v[52:53], v[52:53], 2, s[4:5]
	global_load_dword v136, v[54:55], off nt
	global_load_dword v137, v[52:53], off nt
	v_mad_u64_u32 v[52:53], s[60:61], v57, s40, v[2:3]
	v_mad_u64_u32 v[54:55], s[60:61], v56, s40, v[2:3]
	s_add_i32 s60, s54, 24
	v_or_b32_e32 v56, s55, v1
	v_or_b32_e32 v57, s60, v0
	v_add_lshl_u32 v53, v57, v48, 10
	s_add_i32 s54, s54, 28
	s_cmp_lg_u32 s48, 0
	v_mov_b32_e32 v152, v52
	v_mov_b32_e32 v153, v54
	v_add_lshl_u32 v4, v56, v3, 10
	v_or_b32_e32 v52, v49, v4
	v_or_b32_e32 v4, v50, v53
	v_lshl_add_u64 v[54:55], v[4:5], 2, s[4:5]
	v_mov_b32_e32 v53, v5
	v_lshl_add_u64 v[52:53], v[52:53], 2, s[4:5]
	global_load_dword v138, v[54:55], off nt
	global_load_dword v139, v[52:53], off nt
	v_mad_u64_u32 v[52:53], s[60:61], v57, s40, v[2:3]
	v_mad_u64_u32 v[54:55], s[60:61], v56, s40, v[2:3]
	v_or_b32_e32 v56, s49, v1
	v_or_b32_e32 v57, s54, v0
	v_mov_b32_e32 v55, v5
	v_mov_b32_e32 v154, v52
	v_mov_b32_e32 v155, v54
	v_add_lshl_u32 v4, v56, v3, 10
	v_add_lshl_u32 v52, v57, v48, 10
	v_or_b32_e32 v54, v49, v4
	v_or_b32_e32 v4, v50, v52
	v_lshl_add_u64 v[52:53], v[4:5], 2, s[4:5]
	v_lshl_add_u64 v[54:55], v[54:55], 2, s[4:5]
	global_load_dword v140, v[52:53], off nt
	global_load_dword v141, v[54:55], off nt
	v_mad_u64_u32 v[52:53], s[54:55], v57, s40, v[2:3]
	v_mad_u64_u32 v[54:55], s[54:55], v56, s40, v[2:3]
	v_mov_b32_e32 v156, v52
	v_mov_b32_e32 v157, v54
	s_waitcnt vmcnt(15)
	ds_write_b32 v142, v126
	s_waitcnt vmcnt(14)
	ds_write_b32 v143, v127
	s_waitcnt vmcnt(13)
	ds_write_b32 v144, v128
	s_waitcnt vmcnt(12)
	ds_write_b32 v145, v129
	s_waitcnt vmcnt(11)
	ds_write_b32 v146, v130
	s_waitcnt vmcnt(10)
	ds_write_b32 v147, v131
	s_waitcnt vmcnt(9)
	ds_write_b32 v148, v132
	s_waitcnt vmcnt(8)
	ds_write_b32 v149, v133
	s_waitcnt vmcnt(7)
	ds_write_b32 v150, v134
	s_waitcnt vmcnt(6)
	ds_write_b32 v151, v135
	s_waitcnt vmcnt(5)
	ds_write_b32 v152, v136
	s_waitcnt vmcnt(4)
	ds_write_b32 v153, v137
	s_waitcnt vmcnt(3)
	ds_write_b32 v154, v138
	s_waitcnt vmcnt(2)
	ds_write_b32 v155, v139
	s_waitcnt vmcnt(1)
	ds_write_b32 v156, v140
	s_waitcnt vmcnt(0)
	ds_write_b32 v157, v141
	s_cbranch_scc1 .LBB0_2654
	s_waitcnt lgkmcnt(0)
	ds_read2_b32 v[56:57], v97 offset0:33 offset1:41
	ds_read2_b32 v[58:59], v97 offset0:66 offset1:74
	ds_read2_b32 v[60:61], v97 offset0:99 offset1:107
	ds_read2_b32 v[62:63], v97 offset1:8
	ds_read2_b32 v[64:65], v97 offset0:132 offset1:140
	ds_read2_b32 v[66:67], v97 offset0:165 offset1:173
	ds_read2_b32 v[68:69], v97 offset0:198 offset1:206
	ds_read2_b32 v[70:71], v97 offset0:231 offset1:239
	v_lshlrev_b32_e32 v4, 1, v48
	s_waitcnt lgkmcnt(4)
	v_bfe_u32 v3, v62, 16, 1
	v_lshl_add_u64 v[48:49], v[12:13], 0, v[4:5]
	v_add3_u32 v3, v62, v3, s46
	v_bfe_u32 v4, v56, 16, 1
	v_lshrrev_b32_e32 v3, 16, v3
	v_add3_u32 v4, v56, v4, s46
	v_and_or_b32 v52, v4, s47, v3
	v_bfe_u32 v3, v58, 16, 1
	v_add3_u32 v3, v58, v3, s46
	v_bfe_u32 v4, v60, 16, 1
	v_lshrrev_b32_e32 v3, 16, v3
	v_add3_u32 v4, v60, v4, s46
	v_and_or_b32 v53, v4, s47, v3
	s_waitcnt lgkmcnt(3)
	v_bfe_u32 v3, v64, 16, 1
	v_add3_u32 v3, v64, v3, s46
	s_waitcnt lgkmcnt(2)
	v_bfe_u32 v4, v66, 16, 1
	v_lshrrev_b32_e32 v3, 16, v3
	v_add3_u32 v4, v66, v4, s46
	v_and_or_b32 v54, v4, s47, v3
	s_waitcnt lgkmcnt(1)
	v_bfe_u32 v3, v68, 16, 1
	v_add3_u32 v3, v68, v3, s46
	s_waitcnt lgkmcnt(0)
	v_bfe_u32 v4, v70, 16, 1
	v_lshrrev_b32_e32 v3, 16, v3
	v_add3_u32 v4, v70, v4, s46
	v_and_or_b32 v55, v4, s47, v3
	v_or_b32_e32 v3, v51, v96
	v_lshlrev_b32_e32 v4, 10, v3
	v_bfe_u32 v3, v63, 16, 1
	v_lshl_add_u64 v[72:73], v[48:49], 0, v[4:5]
	v_add3_u32 v3, v63, v3, s46
	v_bfe_u32 v4, v57, 16, 1
	v_lshrrev_b32_e32 v3, 16, v3
	v_add3_u32 v4, v57, v4, s46
	global_store_dwordx4 v[72:73], v[52:55], off
	s_nop 1
	v_and_or_b32 v52, v4, s47, v3
	v_bfe_u32 v3, v59, 16, 1
	v_add3_u32 v3, v59, v3, s46
	v_bfe_u32 v4, v61, 16, 1
	v_lshrrev_b32_e32 v3, 16, v3
	v_add3_u32 v4, v61, v4, s46
	v_and_or_b32 v53, v4, s47, v3
	v_bfe_u32 v3, v65, 16, 1
	v_add3_u32 v3, v65, v3, s46
	v_bfe_u32 v4, v67, 16, 1
	v_lshrrev_b32_e32 v3, 16, v3
	v_add3_u32 v4, v67, v4, s46
	v_and_or_b32 v54, v4, s47, v3
	v_bfe_u32 v3, v69, 16, 1
	v_add3_u32 v3, v69, v3, s46
	v_bfe_u32 v4, v71, 16, 1
	v_lshrrev_b32_e32 v3, 16, v3
	v_add3_u32 v4, v71, v4, s46
	v_and_or_b32 v55, v4, s47, v3
	v_or_b32_e32 v3, v51, v98
	v_lshlrev_b32_e32 v4, 10, v3
	v_lshl_add_u64 v[56:57], v[48:49], 0, v[4:5]
	global_store_dwordx4 v[56:57], v[52:55], off
	ds_read2_b32 v[56:57], v97 offset0:49 offset1:57
	ds_read2_b32 v[58:59], v97 offset0:82 offset1:90
	ds_read2_b32 v[60:61], v97 offset0:115 offset1:123
	ds_read2_b32 v[62:63], v97 offset0:16 offset1:24
	ds_read2_b32 v[64:65], v97 offset0:148 offset1:156
	ds_read2_b32 v[66:67], v97 offset0:181 offset1:189
	ds_read2_b32 v[68:69], v97 offset0:214 offset1:222
	ds_read2_b32 v[70:71], v97 offset0:247 offset1:255
	s_waitcnt lgkmcnt(4)
	v_bfe_u32 v3, v62, 16, 1
	v_add3_u32 v3, v62, v3, s46
	v_bfe_u32 v4, v56, 16, 1
	v_lshrrev_b32_e32 v3, 16, v3
	v_add3_u32 v4, v56, v4, s46
	v_and_or_b32 v52, v4, s47, v3
	v_bfe_u32 v3, v58, 16, 1
	v_add3_u32 v3, v58, v3, s46
	v_bfe_u32 v4, v60, 16, 1
	v_lshrrev_b32_e32 v3, 16, v3
	v_add3_u32 v4, v60, v4, s46
	v_and_or_b32 v53, v4, s47, v3
	s_waitcnt lgkmcnt(3)
	v_bfe_u32 v3, v64, 16, 1
	v_add3_u32 v3, v64, v3, s46
	s_waitcnt lgkmcnt(2)
	v_bfe_u32 v4, v66, 16, 1
	v_lshrrev_b32_e32 v3, 16, v3
	v_add3_u32 v4, v66, v4, s46
	v_and_or_b32 v54, v4, s47, v3
	s_waitcnt lgkmcnt(1)
	v_bfe_u32 v3, v68, 16, 1
	v_add3_u32 v3, v68, v3, s46
	s_waitcnt lgkmcnt(0)
	v_bfe_u32 v4, v70, 16, 1
	v_lshrrev_b32_e32 v3, 16, v3
	v_add3_u32 v4, v70, v4, s46
	v_and_or_b32 v55, v4, s47, v3
	v_or_b32_e32 v3, v51, v99
	v_lshlrev_b32_e32 v4, 10, v3
	v_bfe_u32 v3, v63, 16, 1
	v_lshl_add_u64 v[72:73], v[48:49], 0, v[4:5]
	v_add3_u32 v3, v63, v3, s46
	v_bfe_u32 v4, v57, 16, 1
	v_lshrrev_b32_e32 v3, 16, v3
	v_add3_u32 v4, v57, v4, s46
	global_store_dwordx4 v[72:73], v[52:55], off
	s_nop 1
	v_and_or_b32 v52, v4, s47, v3
	v_bfe_u32 v3, v59, 16, 1
	v_add3_u32 v3, v59, v3, s46
	v_bfe_u32 v4, v61, 16, 1
	v_lshrrev_b32_e32 v3, 16, v3
	v_add3_u32 v4, v61, v4, s46
	v_and_or_b32 v53, v4, s47, v3
	v_bfe_u32 v3, v65, 16, 1
	v_add3_u32 v3, v65, v3, s46
	v_bfe_u32 v4, v67, 16, 1
	v_lshrrev_b32_e32 v3, 16, v3
	v_add3_u32 v4, v67, v4, s46
	v_and_or_b32 v54, v4, s47, v3
	v_bfe_u32 v3, v69, 16, 1
	v_add3_u32 v3, v69, v3, s46
	v_bfe_u32 v4, v71, 16, 1
	v_lshrrev_b32_e32 v3, 16, v3
	v_add3_u32 v4, v71, v4, s46
	v_and_or_b32 v55, v4, s47, v3
	v_or_b32_e32 v3, v51, v100
	v_lshlrev_b32_e32 v4, 10, v3
	v_lshl_add_u64 v[48:49], v[48:49], 0, v[4:5]
	global_store_dwordx4 v[48:49], v[52:55], off
	s_waitcnt lgkmcnt(0)

.LBB0_2659:
	s_lshl_b32 s48, s11, 1
	s_lshl_b32 s37, s10, 1
	v_or_b32_e32 v50, s48, v4
	v_or_b32_e32 v52, s37, v3
	v_mad_u64_u32 v[50:51], s[54:55], v50, s53, v[48:49]
	v_mad_u64_u32 v[52:53], s[54:55], v52, s53, v[48:49]
	global_load_dword v126, v[50:51], off nt
	global_load_dword v127, v[52:53], off nt
	v_or_b32_e32 v54, s37, v1
	v_or_b32_e32 v55, s48, v0
	v_mad_u64_u32 v[50:51], s[54:55], v55, s40, v[2:3]
	v_mad_u64_u32 v[52:53], s[54:55], v54, s40, v[2:3]
	s_add_i32 s54, s48, 4
	s_add_i32 s49, s37, 4
	v_or_b32_e32 v55, s54, v0
	v_or_b32_e32 v54, s49, v1
	s_add_i32 s11, s11, 16
	s_add_i32 s10, s10, 16
	s_add_i32 s36, s36, -16
	v_mov_b32_e32 v142, v50
	v_mov_b32_e32 v143, v52
	v_or_b32_e32 v50, s54, v4
	v_or_b32_e32 v52, s49, v3
	v_mad_u64_u32 v[50:51], s[54:55], v50, s53, v[48:49]
	v_mad_u64_u32 v[52:53], s[54:55], v52, s53, v[48:49]
	global_load_dword v128, v[50:51], off nt
	global_load_dword v129, v[52:53], off nt
	v_mad_u64_u32 v[50:51], s[54:55], v55, s40, v[2:3]
	v_mad_u64_u32 v[52:53], s[54:55], v54, s40, v[2:3]
	s_add_i32 s54, s48, 8
	s_add_i32 s49, s37, 8
	v_or_b32_e32 v55, s54, v0
	v_or_b32_e32 v54, s49, v1
	v_mov_b32_e32 v144, v50
	v_mov_b32_e32 v145, v52
	v_or_b32_e32 v50, s54, v4
	v_or_b32_e32 v52, s49, v3
	v_mad_u64_u32 v[50:51], s[54:55], v50, s53, v[48:49]
	v_mad_u64_u32 v[52:53], s[54:55], v52, s53, v[48:49]
	global_load_dword v130, v[50:51], off nt
	global_load_dword v131, v[52:53], off nt
	v_mad_u64_u32 v[50:51], s[54:55], v55, s40, v[2:3]
	v_mad_u64_u32 v[52:53], s[54:55], v54, s40, v[2:3]
	s_add_i32 s54, s48, 12
	s_add_i32 s49, s37, 12
	v_or_b32_e32 v55, s54, v0
	v_or_b32_e32 v54, s49, v1
	v_mov_b32_e32 v146, v50
	v_mov_b32_e32 v147, v52
	v_or_b32_e32 v50, s54, v4
	v_or_b32_e32 v52, s49, v3
	v_mad_u64_u32 v[50:51], s[54:55], v50, s53, v[48:49]
	v_mad_u64_u32 v[52:53], s[54:55], v52, s53, v[48:49]
	global_load_dword v132, v[50:51], off nt
	global_load_dword v133, v[52:53], off nt
	v_mad_u64_u32 v[50:51], s[54:55], v55, s40, v[2:3]
	v_mad_u64_u32 v[52:53], s[54:55], v54, s40, v[2:3]
	s_add_i32 s54, s48, 16
	s_add_i32 s49, s37, 16
	v_or_b32_e32 v55, s54, v0
	v_or_b32_e32 v54, s49, v1
	v_mov_b32_e32 v148, v50
	v_mov_b32_e32 v149, v52
	v_or_b32_e32 v50, s54, v4
	v_or_b32_e32 v52, s49, v3
	v_mad_u64_u32 v[50:51], s[54:55], v50, s53, v[48:49]
	v_mad_u64_u32 v[52:53], s[54:55], v52, s53, v[48:49]
	global_load_dword v134, v[50:51], off nt
	global_load_dword v135, v[52:53], off nt
	v_mad_u64_u32 v[50:51], s[54:55], v55, s40, v[2:3]
	v_mad_u64_u32 v[52:53], s[54:55], v54, s40, v[2:3]
	s_add_i32 s54, s48, 20
	s_add_i32 s49, s37, 20
	v_or_b32_e32 v55, s54, v0
	v_or_b32_e32 v54, s49, v1
	v_mov_b32_e32 v150, v50
	v_mov_b32_e32 v151, v52
	v_or_b32_e32 v50, s54, v4
	v_or_b32_e32 v52, s49, v3
	v_mad_u64_u32 v[50:51], s[54:55], v50, s53, v[48:49]
	v_mad_u64_u32 v[52:53], s[54:55], v52, s53, v[48:49]
	global_load_dword v136, v[50:51], off nt
	global_load_dword v137, v[52:53], off nt
	v_mad_u64_u32 v[50:51], s[54:55], v55, s40, v[2:3]
	v_mad_u64_u32 v[52:53], s[54:55], v54, s40, v[2:3]
	s_add_i32 s54, s48, 24
	s_add_i32 s49, s37, 24
	v_or_b32_e32 v55, s54, v0
	v_or_b32_e32 v54, s49, v1
	s_add_i32 s48, s48, 28
	s_add_i32 s37, s37, 28
	s_cmp_lg_u32 s36, 0
	v_mov_b32_e32 v152, v50
	v_mov_b32_e32 v153, v52
	v_or_b32_e32 v50, s54, v4
	v_or_b32_e32 v52, s49, v3
	v_mad_u64_u32 v[50:51], s[54:55], v50, s53, v[48:49]
	v_mad_u64_u32 v[52:53], s[54:55], v52, s53, v[48:49]
	global_load_dword v138, v[50:51], off nt
	global_load_dword v139, v[52:53], off nt
	v_mad_u64_u32 v[50:51], s[54:55], v55, s40, v[2:3]
	v_mad_u64_u32 v[52:53], s[54:55], v54, s40, v[2:3]
	v_or_b32_e32 v55, s48, v0
	v_or_b32_e32 v54, s37, v1
	v_mov_b32_e32 v154, v50
	v_mov_b32_e32 v155, v52
	v_or_b32_e32 v50, s48, v4
	v_or_b32_e32 v52, s37, v3
	v_mad_u64_u32 v[50:51], s[48:49], v50, s53, v[48:49]
	v_mad_u64_u32 v[52:53], s[48:49], v52, s53, v[48:49]
	global_load_dword v140, v[50:51], off nt
	global_load_dword v141, v[52:53], off nt
	v_mad_u64_u32 v[50:51], s[48:49], v55, s40, v[2:3]
	v_mad_u64_u32 v[52:53], s[48:49], v54, s40, v[2:3]
	v_mov_b32_e32 v156, v50
	v_mov_b32_e32 v157, v52
	s_waitcnt vmcnt(15)
	ds_write_b32 v142, v126
	s_waitcnt vmcnt(14)
	ds_write_b32 v143, v127
	s_waitcnt vmcnt(13)
	ds_write_b32 v144, v128
	s_waitcnt vmcnt(12)
	ds_write_b32 v145, v129
	s_waitcnt vmcnt(11)
	ds_write_b32 v146, v130
	s_waitcnt vmcnt(10)
	ds_write_b32 v147, v131
	s_waitcnt vmcnt(9)
	ds_write_b32 v148, v132
	s_waitcnt vmcnt(8)
	ds_write_b32 v149, v133
	s_waitcnt vmcnt(7)
	ds_write_b32 v150, v134
	s_waitcnt vmcnt(6)
	ds_write_b32 v151, v135
	s_waitcnt vmcnt(5)
	ds_write_b32 v152, v136
	s_waitcnt vmcnt(4)
	ds_write_b32 v153, v137
	s_waitcnt vmcnt(3)
	ds_write_b32 v154, v138
	s_waitcnt vmcnt(2)
	ds_write_b32 v155, v139
	s_waitcnt vmcnt(1)
	ds_write_b32 v156, v140
	s_waitcnt vmcnt(0)
	ds_write_b32 v157, v141
	s_cbranch_scc1 .LBB0_2659
	v_or_b32_e32 v4, v101, v60
	v_cndmask_b32_e64 v3, 0, 1, s[18:19]
	v_mov_b32_e32 v71, 1.0
	v_cmp_ne_u32_e64 s[10:11], 1, v3
	s_andn2_b64 vcc, exec, s[18:19]
	v_lshlrev_b32_e32 v3, 2, v4
	v_mov_b32_e32 v70, 1.0
	s_cbranch_vccnz .LBB0_2662
	global_load_dword v70, v3, s[14:15]

.LBB0_2680:
	s_lshl_b32 s36, s11, 1
	s_lshl_b32 s35, s10, 1
	v_or_b32_e32 v50, s36, v4
	v_or_b32_e32 v52, s35, v3
	v_mad_u64_u32 v[50:51], s[48:49], v50, s53, v[48:49]
	v_mad_u64_u32 v[52:53], s[48:49], v52, s53, v[48:49]
	global_load_dword v126, v[50:51], off nt
	global_load_dword v127, v[52:53], off nt
	v_or_b32_e32 v54, s35, v1
	v_or_b32_e32 v55, s36, v0
	v_mad_u64_u32 v[50:51], s[48:49], v55, s40, v[2:3]
	v_mad_u64_u32 v[52:53], s[48:49], v54, s40, v[2:3]
	s_add_i32 s48, s36, 4
	s_add_i32 s37, s35, 4
	v_or_b32_e32 v55, s48, v0
	v_or_b32_e32 v54, s37, v1
	s_add_i32 s11, s11, 16
	s_add_i32 s10, s10, 16
	s_add_i32 s34, s34, -16
	v_mov_b32_e32 v142, v50
	v_mov_b32_e32 v143, v52
	v_or_b32_e32 v50, s48, v4
	v_or_b32_e32 v52, s37, v3
	v_mad_u64_u32 v[50:51], s[48:49], v50, s53, v[48:49]
	v_mad_u64_u32 v[52:53], s[48:49], v52, s53, v[48:49]
	global_load_dword v128, v[50:51], off nt
	global_load_dword v129, v[52:53], off nt
	v_mad_u64_u32 v[50:51], s[48:49], v55, s40, v[2:3]
	v_mad_u64_u32 v[52:53], s[48:49], v54, s40, v[2:3]
	s_add_i32 s48, s36, 8
	s_add_i32 s37, s35, 8
	v_or_b32_e32 v55, s48, v0
	v_or_b32_e32 v54, s37, v1
	v_mov_b32_e32 v144, v50
	v_mov_b32_e32 v145, v52
	v_or_b32_e32 v50, s48, v4
	v_or_b32_e32 v52, s37, v3
	v_mad_u64_u32 v[50:51], s[48:49], v50, s53, v[48:49]
	v_mad_u64_u32 v[52:53], s[48:49], v52, s53, v[48:49]
	global_load_dword v130, v[50:51], off nt
	global_load_dword v131, v[52:53], off nt
	v_mad_u64_u32 v[50:51], s[48:49], v55, s40, v[2:3]
	v_mad_u64_u32 v[52:53], s[48:49], v54, s40, v[2:3]
	s_add_i32 s48, s36, 12
	s_add_i32 s37, s35, 12
	v_or_b32_e32 v55, s48, v0
	v_or_b32_e32 v54, s37, v1
	v_mov_b32_e32 v146, v50
	v_mov_b32_e32 v147, v52
	v_or_b32_e32 v50, s48, v4
	v_or_b32_e32 v52, s37, v3
	v_mad_u64_u32 v[50:51], s[48:49], v50, s53, v[48:49]
	v_mad_u64_u32 v[52:53], s[48:49], v52, s53, v[48:49]
	global_load_dword v132, v[50:51], off nt
	global_load_dword v133, v[52:53], off nt
	v_mad_u64_u32 v[50:51], s[48:49], v55, s40, v[2:3]
	v_mad_u64_u32 v[52:53], s[48:49], v54, s40, v[2:3]
	s_add_i32 s48, s36, 16
	s_add_i32 s37, s35, 16
	v_or_b32_e32 v55, s48, v0
	v_or_b32_e32 v54, s37, v1
	v_mov_b32_e32 v148, v50
	v_mov_b32_e32 v149, v52
	v_or_b32_e32 v50, s48, v4
	v_or_b32_e32 v52, s37, v3
	v_mad_u64_u32 v[50:51], s[48:49], v50, s53, v[48:49]
	v_mad_u64_u32 v[52:53], s[48:49], v52, s53, v[48:49]
	global_load_dword v134, v[50:51], off nt
	global_load_dword v135, v[52:53], off nt
	v_mad_u64_u32 v[50:51], s[48:49], v55, s40, v[2:3]
	v_mad_u64_u32 v[52:53], s[48:49], v54, s40, v[2:3]
	s_add_i32 s48, s36, 20
	s_add_i32 s37, s35, 20
	v_or_b32_e32 v55, s48, v0
	v_or_b32_e32 v54, s37, v1
	v_mov_b32_e32 v150, v50
	v_mov_b32_e32 v151, v52
	v_or_b32_e32 v50, s48, v4
	v_or_b32_e32 v52, s37, v3
	v_mad_u64_u32 v[50:51], s[48:49], v50, s53, v[48:49]
	v_mad_u64_u32 v[52:53], s[48:49], v52, s53, v[48:49]
	global_load_dword v136, v[50:51], off nt
	global_load_dword v137, v[52:53], off nt
	v_mad_u64_u32 v[50:51], s[48:49], v55, s40, v[2:3]
	v_mad_u64_u32 v[52:53], s[48:49], v54, s40, v[2:3]
	s_add_i32 s48, s36, 24
	s_add_i32 s37, s35, 24
	v_or_b32_e32 v55, s48, v0
	v_or_b32_e32 v54, s37, v1
	s_add_i32 s36, s36, 28
	s_add_i32 s35, s35, 28
	s_cmp_lg_u32 s34, 0
	v_mov_b32_e32 v152, v50
	v_mov_b32_e32 v153, v52
	v_or_b32_e32 v50, s48, v4
	v_or_b32_e32 v52, s37, v3
	v_mad_u64_u32 v[50:51], s[48:49], v50, s53, v[48:49]
	v_mad_u64_u32 v[52:53], s[48:49], v52, s53, v[48:49]
	global_load_dword v138, v[50:51], off nt
	global_load_dword v139, v[52:53], off nt
	v_mad_u64_u32 v[50:51], s[48:49], v55, s40, v[2:3]
	v_mad_u64_u32 v[52:53], s[48:49], v54, s40, v[2:3]
	v_or_b32_e32 v55, s36, v0
	v_or_b32_e32 v54, s35, v1
	v_mov_b32_e32 v154, v50
	v_mov_b32_e32 v155, v52
	v_or_b32_e32 v50, s36, v4
	v_or_b32_e32 v52, s35, v3
	v_mad_u64_u32 v[50:51], s[36:37], v50, s53, v[48:49]
	v_mad_u64_u32 v[52:53], s[36:37], v52, s53, v[48:49]
	global_load_dword v140, v[50:51], off nt
	global_load_dword v141, v[52:53], off nt
	v_mad_u64_u32 v[50:51], s[36:37], v55, s40, v[2:3]
	v_mad_u64_u32 v[52:53], s[36:37], v54, s40, v[2:3]
	v_mov_b32_e32 v156, v50
	v_mov_b32_e32 v157, v52
	s_waitcnt vmcnt(15)
	ds_write_b32 v142, v126
	s_waitcnt vmcnt(14)
	ds_write_b32 v143, v127
	s_waitcnt vmcnt(13)
	ds_write_b32 v144, v128
	s_waitcnt vmcnt(12)
	ds_write_b32 v145, v129
	s_waitcnt vmcnt(11)
	ds_write_b32 v146, v130
	s_waitcnt vmcnt(10)
	ds_write_b32 v147, v131
	s_waitcnt vmcnt(9)
	ds_write_b32 v148, v132
	s_waitcnt vmcnt(8)
	ds_write_b32 v149, v133
	s_waitcnt vmcnt(7)
	ds_write_b32 v150, v134
	s_waitcnt vmcnt(6)
	ds_write_b32 v151, v135
	s_waitcnt vmcnt(5)
	ds_write_b32 v152, v136
	s_waitcnt vmcnt(4)
	ds_write_b32 v153, v137
	s_waitcnt vmcnt(3)
	ds_write_b32 v154, v138
	s_waitcnt vmcnt(2)
	ds_write_b32 v155, v139
	s_waitcnt vmcnt(1)
	ds_write_b32 v156, v140
	s_waitcnt vmcnt(0)
	ds_write_b32 v157, v141
	s_cbranch_scc1 .LBB0_2680
	v_or_b32_e32 v4, v101, v60
	v_cndmask_b32_e64 v3, 0, 1, s[18:19]
	v_mov_b32_e32 v69, 1.0
	v_cmp_ne_u32_e64 s[10:11], 1, v3
	s_andn2_b64 vcc, exec, s[18:19]
	v_lshlrev_b32_e32 v3, 2, v4
	v_mov_b32_e32 v68, 1.0
	s_cbranch_vccnz .LBB0_2683
	global_load_dword v68, v3, s[14:15]

.LBB0_2701:
	s_lshl_b32 s34, s11, 1
	s_lshl_b32 s25, s10, 1
	v_or_b32_e32 v54, s34, v4
	v_or_b32_e32 v56, s25, v3
	v_mad_i64_i32 v[54:55], s[36:37], v54, s41, v[52:53]
	v_mad_i64_i32 v[56:57], s[36:37], v56, s41, v[52:53]
	global_load_dword v126, v[54:55], off nt
	global_load_dword v127, v[56:57], off nt
	v_or_b32_e32 v49, s25, v1
	v_or_b32_e32 v51, s34, v0
	v_mad_u64_u32 v[54:55], s[36:37], v51, s40, v[2:3]
	v_mad_u64_u32 v[56:57], s[36:37], v49, s40, v[2:3]
	s_add_i32 s36, s34, 4
	s_add_i32 s35, s25, 4
	v_or_b32_e32 v51, s36, v0
	v_or_b32_e32 v49, s35, v1
	s_add_i32 s11, s11, 16
	s_add_i32 s10, s10, 16
	s_add_i32 s24, s24, -16
	v_mov_b32_e32 v142, v54
	v_mov_b32_e32 v143, v56
	v_or_b32_e32 v54, s36, v4
	v_or_b32_e32 v56, s35, v3
	v_mad_i64_i32 v[54:55], s[36:37], v54, s41, v[52:53]
	v_mad_i64_i32 v[56:57], s[36:37], v56, s41, v[52:53]
	global_load_dword v128, v[54:55], off nt
	global_load_dword v129, v[56:57], off nt
	v_mad_u64_u32 v[54:55], s[36:37], v51, s40, v[2:3]
	v_mad_u64_u32 v[56:57], s[36:37], v49, s40, v[2:3]
	s_add_i32 s36, s34, 8
	s_add_i32 s35, s25, 8
	v_or_b32_e32 v51, s36, v0
	v_or_b32_e32 v49, s35, v1
	v_mov_b32_e32 v144, v54
	v_mov_b32_e32 v145, v56
	v_or_b32_e32 v54, s36, v4
	v_or_b32_e32 v56, s35, v3
	v_mad_i64_i32 v[54:55], s[36:37], v54, s41, v[52:53]
	v_mad_i64_i32 v[56:57], s[36:37], v56, s41, v[52:53]
	global_load_dword v130, v[54:55], off nt
	global_load_dword v131, v[56:57], off nt
	v_mad_u64_u32 v[54:55], s[36:37], v51, s40, v[2:3]
	v_mad_u64_u32 v[56:57], s[36:37], v49, s40, v[2:3]
	s_add_i32 s36, s34, 12
	s_add_i32 s35, s25, 12
	v_or_b32_e32 v51, s36, v0
	v_or_b32_e32 v49, s35, v1
	v_mov_b32_e32 v146, v54
	v_mov_b32_e32 v147, v56
	v_or_b32_e32 v54, s36, v4
	v_or_b32_e32 v56, s35, v3
	v_mad_i64_i32 v[54:55], s[36:37], v54, s41, v[52:53]
	v_mad_i64_i32 v[56:57], s[36:37], v56, s41, v[52:53]
	global_load_dword v132, v[54:55], off nt
	global_load_dword v133, v[56:57], off nt
	v_mad_u64_u32 v[54:55], s[36:37], v51, s40, v[2:3]
	v_mad_u64_u32 v[56:57], s[36:37], v49, s40, v[2:3]
	s_add_i32 s36, s34, 16
	s_add_i32 s35, s25, 16
	v_or_b32_e32 v51, s36, v0
	v_or_b32_e32 v49, s35, v1
	v_mov_b32_e32 v148, v54
	v_mov_b32_e32 v149, v56
	v_or_b32_e32 v54, s36, v4
	v_or_b32_e32 v56, s35, v3
	v_mad_i64_i32 v[54:55], s[36:37], v54, s41, v[52:53]
	v_mad_i64_i32 v[56:57], s[36:37], v56, s41, v[52:53]
	global_load_dword v134, v[54:55], off nt
	global_load_dword v135, v[56:57], off nt
	v_mad_u64_u32 v[54:55], s[36:37], v51, s40, v[2:3]
	v_mad_u64_u32 v[56:57], s[36:37], v49, s40, v[2:3]
	s_add_i32 s36, s34, 20
	s_add_i32 s35, s25, 20
	v_or_b32_e32 v51, s36, v0
	v_or_b32_e32 v49, s35, v1
	v_mov_b32_e32 v150, v54
	v_mov_b32_e32 v151, v56
	v_or_b32_e32 v54, s36, v4
	v_or_b32_e32 v56, s35, v3
	v_mad_i64_i32 v[54:55], s[36:37], v54, s41, v[52:53]
	v_mad_i64_i32 v[56:57], s[36:37], v56, s41, v[52:53]
	global_load_dword v136, v[54:55], off nt
	global_load_dword v137, v[56:57], off nt
	v_mad_u64_u32 v[54:55], s[36:37], v51, s40, v[2:3]
	v_mad_u64_u32 v[56:57], s[36:37], v49, s40, v[2:3]
	s_add_i32 s36, s34, 24
	s_add_i32 s35, s25, 24
	v_or_b32_e32 v51, s36, v0
	v_or_b32_e32 v49, s35, v1
	s_add_i32 s34, s34, 28
	s_add_i32 s25, s25, 28
	s_cmp_lg_u32 s24, 0
	v_mov_b32_e32 v152, v54
	v_mov_b32_e32 v153, v56
	v_or_b32_e32 v54, s36, v4
	v_or_b32_e32 v56, s35, v3
	v_mad_i64_i32 v[54:55], s[36:37], v54, s41, v[52:53]
	v_mad_i64_i32 v[56:57], s[36:37], v56, s41, v[52:53]
	global_load_dword v138, v[54:55], off nt
	global_load_dword v139, v[56:57], off nt
	v_mad_u64_u32 v[54:55], s[36:37], v51, s40, v[2:3]
	v_mad_u64_u32 v[56:57], s[36:37], v49, s40, v[2:3]
	v_or_b32_e32 v51, s34, v0
	v_or_b32_e32 v49, s25, v1
	v_mov_b32_e32 v154, v54
	v_mov_b32_e32 v155, v56
	v_or_b32_e32 v54, s34, v4
	v_or_b32_e32 v56, s25, v3
	v_mad_i64_i32 v[54:55], s[34:35], v54, s41, v[52:53]
	v_mad_i64_i32 v[56:57], s[34:35], v56, s41, v[52:53]
	global_load_dword v140, v[54:55], off nt
	global_load_dword v141, v[56:57], off nt
	v_mad_u64_u32 v[54:55], s[34:35], v51, s40, v[2:3]
	v_mad_u64_u32 v[56:57], s[34:35], v49, s40, v[2:3]
	v_mov_b32_e32 v156, v54
	v_mov_b32_e32 v157, v56
	s_waitcnt vmcnt(15)
	ds_write_b32 v142, v126
	s_waitcnt vmcnt(14)
	ds_write_b32 v143, v127
	s_waitcnt vmcnt(13)
	ds_write_b32 v144, v128
	s_waitcnt vmcnt(12)
	ds_write_b32 v145, v129
	s_waitcnt vmcnt(11)
	ds_write_b32 v146, v130
	s_waitcnt vmcnt(10)
	ds_write_b32 v147, v131
	s_waitcnt vmcnt(9)
	ds_write_b32 v148, v132
	s_waitcnt vmcnt(8)
	ds_write_b32 v149, v133
	s_waitcnt vmcnt(7)
	ds_write_b32 v150, v134
	s_waitcnt vmcnt(6)
	ds_write_b32 v151, v135
	s_waitcnt vmcnt(5)
	ds_write_b32 v152, v136
	s_waitcnt vmcnt(4)
	ds_write_b32 v153, v137
	s_waitcnt vmcnt(3)
	ds_write_b32 v154, v138
	s_waitcnt vmcnt(2)
	ds_write_b32 v155, v139
	s_waitcnt vmcnt(1)
	ds_write_b32 v156, v140
	s_waitcnt vmcnt(0)
	ds_write_b32 v157, v141
	s_cbranch_scc1 .LBB0_2701
	v_or_b32_e32 v52, v50, v101
	v_cndmask_b32_e64 v3, 0, 1, s[8:9]
	v_mov_b32_e32 v71, 1.0
	v_cmp_ne_u32_e64 s[10:11], 1, v3
	s_andn2_b64 vcc, exec, s[8:9]
	v_ashrrev_i32_e32 v53, 31, v52
	v_mov_b32_e32 v70, 1.0
	s_cbranch_vccnz .LBB0_2704
	v_lshl_add_u64 v[54:55], v[52:53], 2, s[90:91]
	global_load_dword v70, v[54:55], off
